# K-loop SP1: 4 k1 A-fragment LDS reads trail the barrier (lgkmcnt(4)), MFMA block reordered k0-first with lgkmcnt(0) before the k1 MFMAs
# baseline (speedup 1.0000x reference)
; #define PG8_STAGE(bufoff, gbase, voff) do { _Pragma("unroll") for (int _i = 0; _i < 2; ++_i) \
;         __builtin_amdgcn_global_load_lds((const unsigned*)((const char*)(gbase) + (voff)[_i]), (PG8_LAS unsigned*)(lds + (bufoff) + ldsw + _i * 8192), 16, 0, 0); } while (0)
; #define PG8_LDA(dst, b, h) do { _Pragma("unroll") for (int m = 0; m < 4; ++m) _Pragma("unroll") for (int k = 0; k < 2; ++k) dst[m][k] = *(const PG8_LAS bf16x8*)(lds + PG8_SA(b, h) + aoff + m * 2048 + k * 1024); } while (0)
; #define PG8_LDB(dst, b, h) do { _Pragma("unroll") for (int n = 0; n < 2; ++n) _Pragma("unroll") for (int k = 0; k < 2; ++k) dst[n][k] = *(const PG8_LAS bf16x8*)(lds + PG8_SB(b, h) + boff + n * 2048 + k * 1024); } while (0)
; #define PG8_MMA(ai, bj, At, Bt) do { __builtin_amdgcn_s_setprio(1); _Pragma("unroll") for (int m = 0; m < 4; ++m) _Pragma("unroll") for (int n = 0; n < 2; ++n) _Pragma("unroll") for (int k = 0; k < 2; ++k) \
;         acc[ai][bj][m][n] = __builtin_amdgcn_mfma_f32_16x16x32_bf16(Bt[n][k], At[m][k], acc[ai][bj][m][n], 0, 0, 0); __builtin_amdgcn_s_setprio(0); } while (0)
; #define PG8_WAIT_V(n) asm volatile("s_waitcnt vmcnt(" #n ")" ::: "memory")
; #define PG8_WAIT_L(n) asm volatile("s_waitcnt lgkmcnt(" #n ")" ::: "memory")
; #define PG8_BAR __builtin_amdgcn_s_barrier()
; #define PG8_SCHED __builtin_amdgcn_sched_barrier(0)
; template <class Epi, class Sched, bool ALIGN_EPI = false, bool SP2 = false>
; __device__ __forceinline__ void gemm_phase(PG8_LAS unsigned char* lds, const Gemm g, const Sched& S, const Epi& E) {
;     ...
;             PG8_LDB(B0, 0, 0); PG8_LDB(B1, 0, 1); PG8_SCHED; PG8_LDA(At, 0, 0); PG8_STAGE(PG8_SA(1, 1), a1 + hstep, voffA);
;             PG8_WAIT_V(8); PG8_WAIT_L(0); PG8_BAR; PG8_MMA(0, 0, At, B0); PG8_MMA(0, 1, At, B1); PG8_BAR; PG8_SCHED;
;             PG8_LDA(At, 0, 1); PG8_STAGE(PG8_SB(0, 0), b2, voffB); PG8_STAGE(PG8_SB(0, 1), b2 + hstep, voffB); PG8_STAGE(PG8_SA(0, 0), a2, voffA);
;             PG8_WAIT_V(8); PG8_WAIT_L(0); PG8_BAR; PG8_MMA(1, 0, At, B0); PG8_MMA(1, 1, At, B1); PG8_BAR; PG8_SCHED;
.LBB0_309:
	s_add_u32 s40, s54, 0xfff80080
	s_addc_u32 s41, s55, -1
	s_add_i32 s36, 0, 0x10000
	s_cmp_eq_u32 s7, 28
	s_cselect_b32 s97, s9, s41
	s_cselect_b32 s96, s35, s40
	v_add_u32_e32 v156, s36, v164
	s_cselect_b32 s85, s87, vcc_hi
	s_cselect_b32 s84, s91, vcc_lo
	s_add_i32 s37, 0, 0x14000
	ds_read_b128 v[130:133], v156
	ds_read_b128 v[168:171], v156 offset:1024
	ds_read_b128 v[172:175], v156 offset:2048
	ds_read_b128 v[176:179], v156 offset:3072
	v_add_u32_e32 v156, s37, v164
	ds_read_b128 v[180:183], v156
	ds_read_b128 v[188:191], v156 offset:1024
	ds_read_b128 v[192:195], v156 offset:2048
	ds_read_b128 v[196:199], v156 offset:3072
	v_lshl_add_u64 v[156:157], s[54:55], 0, v[146:147]
	s_add_i32 m0, s82, 0xc000
	ds_read_b128 v[200:203], v166
	ds_read_b128 v[208:211], v166 offset:2048
	ds_read_b128 v[216:219], v166 offset:4096
	ds_read_b128 v[224:227], v166 offset:6144
	ds_read_b128 v[204:207], v166 offset:1024
	ds_read_b128 v[212:215], v166 offset:3072
	ds_read_b128 v[220:223], v166 offset:5120
	ds_read_b128 v[228:231], v166 offset:7168
	s_add_u32 s98, s54, 0xfff80000
	s_addc_u32 s99, s55, -1
	s_mov_b32 m0, s60
	s_nop 0
	global_load_lds_dwordx4 v146, s[98:99]
	s_mov_b32 m0, s61
	s_nop 0
	global_load_lds_dwordx4 v148, s[98:99]
	s_add_i32 m0, s82, 0xc000
	s_nop 0
	global_load_lds_dwordx4 v[156:157], off
	v_lshl_add_u64 v[156:157], s[54:55], 0, v[148:149]
	s_add_i32 m0, s82, 0xe000
	s_nop 0
	global_load_lds_dwordx4 v[156:157], off
	s_waitcnt vmcnt(8)
	s_waitcnt lgkmcnt(4)
	s_setprio 1
	s_barrier
	v_mfma_f32_16x16x32_bf16 v[126:129], v[130:133], v[200:203], v[126:129]
	v_mfma_f32_16x16x32_bf16 v[122:125], v[172:175], v[200:203], v[122:125]
	v_mfma_f32_16x16x32_bf16 v[110:113], v[130:133], v[208:211], v[110:113]
	v_mfma_f32_16x16x32_bf16 v[106:109], v[172:175], v[208:211], v[106:109]
	v_mfma_f32_16x16x32_bf16 v[94:97], v[130:133], v[216:219], v[94:97]
	v_mfma_f32_16x16x32_bf16 v[90:93], v[172:175], v[216:219], v[90:93]
	v_mfma_f32_16x16x32_bf16 v[78:81], v[130:133], v[224:227], v[78:81]
	v_mfma_f32_16x16x32_bf16 v[74:77], v[172:175], v[224:227], v[74:77]
	v_mfma_f32_16x16x32_bf16 v[118:121], v[180:183], v[200:203], v[118:121]
	v_mfma_f32_16x16x32_bf16 v[114:117], v[192:195], v[200:203], v[114:117]
	v_mfma_f32_16x16x32_bf16 v[102:105], v[180:183], v[208:211], v[102:105]
	v_mfma_f32_16x16x32_bf16 v[98:101], v[192:195], v[208:211], v[98:101]
	v_mfma_f32_16x16x32_bf16 v[86:89], v[180:183], v[216:219], v[86:89]
	v_mfma_f32_16x16x32_bf16 v[82:85], v[192:195], v[216:219], v[82:85]
	v_mfma_f32_16x16x32_bf16 v[70:73], v[180:183], v[224:227], v[70:73]
	v_mfma_f32_16x16x32_bf16 v[66:69], v[192:195], v[224:227], v[66:69]
	s_waitcnt lgkmcnt(0)
	v_mfma_f32_16x16x32_bf16 v[126:129], v[168:171], v[204:207], v[126:129]
	v_mfma_f32_16x16x32_bf16 v[122:125], v[176:179], v[204:207], v[122:125]
	v_mfma_f32_16x16x32_bf16 v[110:113], v[168:171], v[212:215], v[110:113]
	v_mfma_f32_16x16x32_bf16 v[106:109], v[176:179], v[212:215], v[106:109]
	v_mfma_f32_16x16x32_bf16 v[94:97], v[168:171], v[220:223], v[94:97]
	v_mfma_f32_16x16x32_bf16 v[90:93], v[176:179], v[220:223], v[90:93]
	v_mfma_f32_16x16x32_bf16 v[78:81], v[168:171], v[228:231], v[78:81]
	v_mfma_f32_16x16x32_bf16 v[74:77], v[176:179], v[228:231], v[74:77]
	v_mfma_f32_16x16x32_bf16 v[118:121], v[188:191], v[204:207], v[118:121]
	v_mfma_f32_16x16x32_bf16 v[114:117], v[196:199], v[204:207], v[114:117]
	v_mfma_f32_16x16x32_bf16 v[102:105], v[188:191], v[212:215], v[102:105]
	v_mfma_f32_16x16x32_bf16 v[98:101], v[196:199], v[212:215], v[98:101]
	v_mfma_f32_16x16x32_bf16 v[86:89], v[188:191], v[220:223], v[86:89]
	v_mfma_f32_16x16x32_bf16 v[82:85], v[196:199], v[220:223], v[82:85]
	v_mfma_f32_16x16x32_bf16 v[70:73], v[188:191], v[228:231], v[70:73]
	v_mfma_f32_16x16x32_bf16 v[66:69], v[196:199], v[228:231], v[66:69]
	s_setprio 0
	s_barrier
	s_add_i32 s36, s36, s20
	v_lshl_add_u64 v[156:157], s[84:85], 0, v[138:139]
	s_mov_b32 m0, s36
	ds_read_b128 v[200:203], v166 offset:16384
	ds_read_b128 v[204:207], v166 offset:17408
	ds_read_b128 v[208:211], v166 offset:18432
	ds_read_b128 v[212:215], v166 offset:19456
	ds_read_b128 v[216:219], v166 offset:20480
	ds_read_b128 v[220:223], v166 offset:21504
	ds_read_b128 v[224:227], v166 offset:22528
	ds_read_b128 v[228:231], v166 offset:23552
	global_load_lds_dwordx4 v[156:157], off
	s_add_i32 m0, s36, 0x2000
	s_add_u32 s40, s84, 0x80000
	v_lshl_add_u64 v[184:185], s[84:85], 0, v[142:143]
	s_addc_u32 s41, s85, 0
	s_add_i32 s36, s37, s20
	global_load_lds_dwordx4 v[184:185], off
	v_lshl_add_u64 v[232:233], s[40:41], 0, v[138:139]
	s_mov_b32 m0, s36
	v_lshl_add_u64 v[234:235], s[96:97], 0, v[140:141]
	global_load_lds_dwordx4 v[232:233], off
	v_lshl_add_u64 v[232:233], s[40:41], 0, v[142:143]
	s_add_i32 m0, s36, 0x2000
	s_nop 0
	global_load_lds_dwordx4 v[232:233], off
	v_lshl_add_u64 v[232:233], s[96:97], 0, v[136:137]
	s_mov_b32 m0, s82
	s_nop 0
	s_mov_b32 m0, s83
	s_nop 0
	s_waitcnt vmcnt(6)
	s_waitcnt lgkmcnt(0)
	s_setprio 1
	s_barrier
; #define PG8_STAGE(bufoff, gbase, voff) do { _Pragma("unroll") for (int _i = 0; _i < 2; ++_i) \
;         __builtin_amdgcn_global_load_lds((const unsigned*)((const char*)(gbase) + (voff)[_i]), (PG8_LAS unsigned*)(lds + (bufoff) + ldsw + _i * 8192), 16, 0, 0); } while (0)
; #define PG8_LDA(dst, b, h) do { _Pragma("unroll") for (int m = 0; m < 4; ++m) _Pragma("unroll") for (int k = 0; k < 2; ++k) dst[m][k] = *(const PG8_LAS bf16x8*)(lds + PG8_SA(b, h) + aoff + m * 2048 + k * 1024); } while (0)
; #define PG8_LDB(dst, b, h) do { _Pragma("unroll") for (int n = 0; n < 2; ++n) _Pragma("unroll") for (int k = 0; k < 2; ++k) dst[n][k] = *(const PG8_LAS bf16x8*)(lds + PG8_SB(b, h) + boff + n * 2048 + k * 1024); } while (0)
; #define PG8_MMA(ai, bj, At, Bt) do { __builtin_amdgcn_s_setprio(1); _Pragma("unroll") for (int m = 0; m < 4; ++m) _Pragma("unroll") for (int n = 0; n < 2; ++n) _Pragma("unroll") for (int k = 0; k < 2; ++k) \
;         acc[ai][bj][m][n] = __builtin_amdgcn_mfma_f32_16x16x32_bf16(Bt[n][k], At[m][k], acc[ai][bj][m][n], 0, 0, 0); __builtin_amdgcn_s_setprio(0); } while (0)
; #define PG8_WAIT_V(n) asm volatile("s_waitcnt vmcnt(" #n ")" ::: "memory")
; #define PG8_WAIT_L(n) asm volatile("s_waitcnt lgkmcnt(" #n ")" ::: "memory")
; #define PG8_BAR __builtin_amdgcn_s_barrier()
; #define PG8_SCHED __builtin_amdgcn_sched_barrier(0)
; template <class Epi, class Sched, bool ALIGN_EPI = false, bool SP2 = false>
; __device__ __forceinline__ void gemm_phase(PG8_LAS unsigned char* lds, const Gemm g, const Sched& S, const Epi& E) {
;     ...
;             PG8_WAIT_V(8); PG8_WAIT_L(0); PG8_BAR; PG8_MMA(1, 0, At, B0); PG8_MMA(1, 1, At, B1); PG8_BAR; PG8_SCHED;
;             PG8_LDB(B0, 1, 0); PG8_LDB(B1, 1, 1); PG8_SCHED; PG8_LDA(At, 1, 0); PG8_STAGE(PG8_SA(0, 1), a2 + hstep, voffA);
;             PG8_WAIT_V(8); PG8_WAIT_L(0); PG8_BAR; PG8_MMA(0, 0, At, B0); PG8_MMA(0, 1, At, B1); PG8_BAR; PG8_SCHED;
	v_mfma_f32_16x16x32_bf16 v[62:65], v[130:133], v[200:203], v[62:65]
	v_mfma_f32_16x16x32_bf16 v[58:61], v[172:175], v[200:203], v[58:61]
	v_mfma_f32_16x16x32_bf16 v[46:49], v[130:133], v[208:211], v[46:49]
	v_mfma_f32_16x16x32_bf16 v[42:45], v[172:175], v[208:211], v[42:45]
	v_mfma_f32_16x16x32_bf16 v[30:33], v[130:133], v[216:219], v[30:33]
	v_mfma_f32_16x16x32_bf16 v[26:29], v[172:175], v[216:219], v[26:29]
	v_mfma_f32_16x16x32_bf16 v[14:17], v[130:133], v[224:227], v[14:17]
	v_mfma_f32_16x16x32_bf16 v[10:13], v[172:175], v[224:227], v[10:13]
	v_mfma_f32_16x16x32_bf16 v[62:65], v[168:171], v[204:207], v[62:65]
	v_mfma_f32_16x16x32_bf16 v[58:61], v[176:179], v[204:207], v[58:61]
	v_mfma_f32_16x16x32_bf16 v[46:49], v[168:171], v[212:215], v[46:49]
	v_mfma_f32_16x16x32_bf16 v[42:45], v[176:179], v[212:215], v[42:45]
	v_mfma_f32_16x16x32_bf16 v[30:33], v[168:171], v[220:223], v[30:33]
	v_mfma_f32_16x16x32_bf16 v[26:29], v[176:179], v[220:223], v[26:29]
	v_mfma_f32_16x16x32_bf16 v[14:17], v[168:171], v[228:231], v[14:17]
	v_mfma_f32_16x16x32_bf16 v[10:13], v[176:179], v[228:231], v[10:13]
	v_mfma_f32_16x16x32_bf16 v[54:57], v[180:183], v[200:203], v[54:57]
	v_mfma_f32_16x16x32_bf16 v[50:53], v[192:195], v[200:203], v[50:53]
	v_mfma_f32_16x16x32_bf16 v[38:41], v[180:183], v[208:211], v[38:41]
	v_mfma_f32_16x16x32_bf16 v[34:37], v[192:195], v[208:211], v[34:37]
	v_mfma_f32_16x16x32_bf16 v[22:25], v[180:183], v[216:219], v[22:25]
	v_mfma_f32_16x16x32_bf16 v[18:21], v[192:195], v[216:219], v[18:21]
	v_mfma_f32_16x16x32_bf16 v[6:9], v[180:183], v[224:227], v[6:9]
	v_mfma_f32_16x16x32_bf16 v[2:5], v[192:195], v[224:227], v[2:5]
	v_mfma_f32_16x16x32_bf16 v[54:57], v[188:191], v[204:207], v[54:57]
	v_mfma_f32_16x16x32_bf16 v[50:53], v[196:199], v[204:207], v[50:53]
	v_mfma_f32_16x16x32_bf16 v[38:41], v[188:191], v[212:215], v[38:41]
	v_mfma_f32_16x16x32_bf16 v[34:37], v[196:199], v[212:215], v[34:37]
	v_mfma_f32_16x16x32_bf16 v[22:25], v[188:191], v[220:223], v[22:25]
	v_mfma_f32_16x16x32_bf16 v[18:21], v[196:199], v[220:223], v[18:21]
	v_mfma_f32_16x16x32_bf16 v[6:9], v[188:191], v[228:231], v[6:9]
	v_mfma_f32_16x16x32_bf16 v[2:5], v[196:199], v[228:231], v[2:5]
	s_setprio 0
	s_barrier
	s_add_i32 s36, 0, 0x18000
	v_add_u32_e32 v167, s36, v164
	s_add_i32 s37, 0, 0x1c000
	ds_read_b128 v[130:133], v167
	ds_read_b128 v[168:171], v167 offset:1024
	ds_read_b128 v[172:175], v167 offset:2048
	ds_read_b128 v[176:179], v167 offset:3072
	v_add_u32_e32 v167, s37, v164
	ds_read_b128 v[180:183], v167
	ds_read_b128 v[188:191], v167 offset:1024
	ds_read_b128 v[192:195], v167 offset:2048
	ds_read_b128 v[196:199], v167 offset:3072
	s_add_u32 s40, s96, 0x80000
	s_addc_u32 s41, s97, 0
	s_mov_b32 m0, s3
	v_lshl_add_u64 v[236:237], s[40:41], 0, v[136:137]
	ds_read_b128 v[200:203], v166 offset:32768
	ds_read_b128 v[208:211], v166 offset:34816
	ds_read_b128 v[216:219], v166 offset:36864
	ds_read_b128 v[224:227], v166 offset:38912
	ds_read_b128 v[204:207], v166 offset:33792
	ds_read_b128 v[212:215], v166 offset:35840
	ds_read_b128 v[220:223], v166 offset:37888
	ds_read_b128 v[228:231], v166 offset:39936
	s_add_u32 s98, s40, 0xfff80000
	s_addc_u32 s99, s41, -1
	s_mov_b32 m0, s82
	s_nop 0
	global_load_lds_dwordx4 v136, s[98:99]
	s_mov_b32 m0, s83
	s_nop 0
	global_load_lds_dwordx4 v140, s[98:99]
	s_mov_b32 m0, s3
	s_nop 0
	global_load_lds_dwordx4 v[236:237], off
	v_lshl_add_u64 v[236:237], s[40:41], 0, v[140:141]
	s_mov_b32 m0, s74
	s_nop 0
	global_load_lds_dwordx4 v[236:237], off
	s_waitcnt vmcnt(8)
	s_waitcnt lgkmcnt(4)
	s_setprio 1
	s_barrier
	v_mfma_f32_16x16x32_bf16 v[126:129], v[130:133], v[200:203], v[126:129]
	v_mfma_f32_16x16x32_bf16 v[122:125], v[172:175], v[200:203], v[122:125]
	v_mfma_f32_16x16x32_bf16 v[110:113], v[130:133], v[208:211], v[110:113]
	v_mfma_f32_16x16x32_bf16 v[106:109], v[172:175], v[208:211], v[106:109]
	v_mfma_f32_16x16x32_bf16 v[94:97], v[130:133], v[216:219], v[94:97]
	v_mfma_f32_16x16x32_bf16 v[90:93], v[172:175], v[216:219], v[90:93]
	v_mfma_f32_16x16x32_bf16 v[78:81], v[130:133], v[224:227], v[78:81]
	v_mfma_f32_16x16x32_bf16 v[74:77], v[172:175], v[224:227], v[74:77]
	v_mfma_f32_16x16x32_bf16 v[118:121], v[180:183], v[200:203], v[118:121]
	v_mfma_f32_16x16x32_bf16 v[114:117], v[192:195], v[200:203], v[114:117]
	v_mfma_f32_16x16x32_bf16 v[102:105], v[180:183], v[208:211], v[102:105]
	v_mfma_f32_16x16x32_bf16 v[98:101], v[192:195], v[208:211], v[98:101]
	v_mfma_f32_16x16x32_bf16 v[86:89], v[180:183], v[216:219], v[86:89]
	v_mfma_f32_16x16x32_bf16 v[82:85], v[192:195], v[216:219], v[82:85]
	v_mfma_f32_16x16x32_bf16 v[70:73], v[180:183], v[224:227], v[70:73]
	v_mfma_f32_16x16x32_bf16 v[66:69], v[192:195], v[224:227], v[66:69]
	s_waitcnt lgkmcnt(0)
	v_mfma_f32_16x16x32_bf16 v[126:129], v[168:171], v[204:207], v[126:129]
	v_mfma_f32_16x16x32_bf16 v[122:125], v[176:179], v[204:207], v[122:125]
	v_mfma_f32_16x16x32_bf16 v[110:113], v[168:171], v[212:215], v[110:113]
	v_mfma_f32_16x16x32_bf16 v[106:109], v[176:179], v[212:215], v[106:109]
	v_mfma_f32_16x16x32_bf16 v[94:97], v[168:171], v[220:223], v[94:97]
	v_mfma_f32_16x16x32_bf16 v[90:93], v[176:179], v[220:223], v[90:93]
	v_mfma_f32_16x16x32_bf16 v[78:81], v[168:171], v[228:231], v[78:81]
	v_mfma_f32_16x16x32_bf16 v[74:77], v[176:179], v[228:231], v[74:77]
	v_mfma_f32_16x16x32_bf16 v[118:121], v[188:191], v[204:207], v[118:121]
	v_mfma_f32_16x16x32_bf16 v[114:117], v[196:199], v[204:207], v[114:117]
	v_mfma_f32_16x16x32_bf16 v[102:105], v[188:191], v[212:215], v[102:105]
	v_mfma_f32_16x16x32_bf16 v[98:101], v[196:199], v[212:215], v[98:101]
	v_mfma_f32_16x16x32_bf16 v[86:89], v[188:191], v[220:223], v[86:89]
	v_mfma_f32_16x16x32_bf16 v[82:85], v[196:199], v[220:223], v[82:85]
	v_mfma_f32_16x16x32_bf16 v[70:73], v[188:191], v[228:231], v[70:73]
	v_mfma_f32_16x16x32_bf16 v[66:69], v[196:199], v[228:231], v[66:69]
	s_setprio 0
	s_barrier
; #define PG8_STAGE(bufoff, gbase, voff) do { _Pragma("unroll") for (int _i = 0; _i < 2; ++_i) \
;         __builtin_amdgcn_global_load_lds((const unsigned*)((const char*)(gbase) + (voff)[_i]), (PG8_LAS unsigned*)(lds + (bufoff) + ldsw + _i * 8192), 16, 0, 0); } while (0)
; #define PG8_LDA(dst, b, h) do { _Pragma("unroll") for (int m = 0; m < 4; ++m) _Pragma("unroll") for (int k = 0; k < 2; ++k) dst[m][k] = *(const PG8_LAS bf16x8*)(lds + PG8_SA(b, h) + aoff + m * 2048 + k * 1024); } while (0)
; #define PG8_MMA(ai, bj, At, Bt) do { __builtin_amdgcn_s_setprio(1); _Pragma("unroll") for (int m = 0; m < 4; ++m) _Pragma("unroll") for (int n = 0; n < 2; ++n) _Pragma("unroll") for (int k = 0; k < 2; ++k) \
;         acc[ai][bj][m][n] = __builtin_amdgcn_mfma_f32_16x16x32_bf16(Bt[n][k], At[m][k], acc[ai][bj][m][n], 0, 0, 0); __builtin_amdgcn_s_setprio(0); } while (0)
; #define PG8_WAIT_V(n) asm volatile("s_waitcnt vmcnt(" #n ")" ::: "memory")
; #define PG8_WAIT_L(n) asm volatile("s_waitcnt lgkmcnt(" #n ")" ::: "memory")
; #define PG8_BAR __builtin_amdgcn_s_barrier()
; #define PG8_SCHED __builtin_amdgcn_sched_barrier(0)
; template <class Epi, class Sched, bool ALIGN_EPI = false, bool SP2 = false>
; __device__ __forceinline__ void gemm_phase(PG8_LAS unsigned char* lds, const Gemm g, const Sched& S, const Epi& E) {
;     ...
;         for (int t = 0; t < nt; t += 2) {
;     ...
;             PG8_WAIT_V(8); PG8_WAIT_L(0); PG8_BAR; PG8_MMA(0, 0, At, B0); PG8_MMA(0, 1, At, B1); PG8_BAR; PG8_SCHED;
;             PG8_LDA(At, 1, 1); PG8_STAGE(PG8_SB(1, 0), b3, voffB); PG8_STAGE(PG8_SB(1, 1), b3 + hstep, voffB); PG8_STAGE(PG8_SA(1, 0), a3, voffA);
;             PG8_WAIT_V(8); PG8_WAIT_L(0); PG8_BAR; PG8_MMA(1, 0, At, B0); PG8_MMA(1, 1, At, B1); PG8_BAR; PG8_SCHED;
	s_add_i32 s36, s36, s20
	v_lshl_add_u64 v[156:157], v[156:157], 0, s[42:43]
	s_mov_b32 m0, s36
	ds_read_b128 v[200:203], v166 offset:49152
	ds_read_b128 v[204:207], v166 offset:50176
	ds_read_b128 v[208:211], v166 offset:51200
	ds_read_b128 v[212:215], v166 offset:52224
	ds_read_b128 v[216:219], v166 offset:53248
	ds_read_b128 v[220:223], v166 offset:54272
	ds_read_b128 v[224:227], v166 offset:55296
	ds_read_b128 v[228:231], v166 offset:56320
	global_load_lds_dwordx4 v[156:157], off
	s_add_i32 m0, s36, 0x2000
	s_add_u32 s40, s84, 0x80080
	v_lshl_add_u64 v[156:157], v[184:185], 0, s[42:43]
	s_addc_u32 s41, s85, 0
	s_add_i32 s36, s37, s20
	global_load_lds_dwordx4 v[156:157], off
	v_lshl_add_u64 v[156:157], s[40:41], 0, v[138:139]
	s_mov_b32 m0, s36
	s_nop 0
	global_load_lds_dwordx4 v[156:157], off
	v_lshl_add_u64 v[156:157], s[40:41], 0, v[142:143]
	s_add_i32 m0, s36, 0x2000
	s_nop 0
	global_load_lds_dwordx4 v[156:157], off
	v_lshl_add_u64 v[156:157], v[232:233], 0, s[42:43]
	s_mov_b32 m0, s60
	s_nop 0
	v_lshl_add_u64 v[156:157], v[234:235], 0, s[42:43]
	s_mov_b32 m0, s61
	s_nop 0
	s_waitcnt vmcnt(6)
	s_waitcnt lgkmcnt(0)
	s_setprio 1
	s_barrier
	v_mfma_f32_16x16x32_bf16 v[62:65], v[130:133], v[200:203], v[62:65]
	v_mfma_f32_16x16x32_bf16 v[58:61], v[172:175], v[200:203], v[58:61]
	v_mfma_f32_16x16x32_bf16 v[46:49], v[130:133], v[208:211], v[46:49]
	v_mfma_f32_16x16x32_bf16 v[42:45], v[172:175], v[208:211], v[42:45]
	v_mfma_f32_16x16x32_bf16 v[30:33], v[130:133], v[216:219], v[30:33]
	v_mfma_f32_16x16x32_bf16 v[26:29], v[172:175], v[216:219], v[26:29]
	v_mfma_f32_16x16x32_bf16 v[14:17], v[130:133], v[224:227], v[14:17]
	v_mfma_f32_16x16x32_bf16 v[10:13], v[172:175], v[224:227], v[10:13]
	v_mfma_f32_16x16x32_bf16 v[62:65], v[168:171], v[204:207], v[62:65]
	v_mfma_f32_16x16x32_bf16 v[58:61], v[176:179], v[204:207], v[58:61]
	v_mfma_f32_16x16x32_bf16 v[46:49], v[168:171], v[212:215], v[46:49]
	v_mfma_f32_16x16x32_bf16 v[42:45], v[176:179], v[212:215], v[42:45]
	v_mfma_f32_16x16x32_bf16 v[30:33], v[168:171], v[220:223], v[30:33]
	v_mfma_f32_16x16x32_bf16 v[26:29], v[176:179], v[220:223], v[26:29]
	v_mfma_f32_16x16x32_bf16 v[14:17], v[168:171], v[228:231], v[14:17]
	v_mfma_f32_16x16x32_bf16 v[10:13], v[176:179], v[228:231], v[10:13]
	v_mfma_f32_16x16x32_bf16 v[54:57], v[180:183], v[200:203], v[54:57]
	v_mfma_f32_16x16x32_bf16 v[50:53], v[192:195], v[200:203], v[50:53]
	v_mfma_f32_16x16x32_bf16 v[38:41], v[180:183], v[208:211], v[38:41]
	v_mfma_f32_16x16x32_bf16 v[34:37], v[192:195], v[208:211], v[34:37]
	v_mfma_f32_16x16x32_bf16 v[22:25], v[180:183], v[216:219], v[22:25]
	v_mfma_f32_16x16x32_bf16 v[18:21], v[192:195], v[216:219], v[18:21]
	v_mfma_f32_16x16x32_bf16 v[6:9], v[180:183], v[224:227], v[6:9]
	v_mfma_f32_16x16x32_bf16 v[2:5], v[192:195], v[224:227], v[2:5]
	v_mfma_f32_16x16x32_bf16 v[54:57], v[188:191], v[204:207], v[54:57]
	v_mfma_f32_16x16x32_bf16 v[50:53], v[196:199], v[204:207], v[50:53]
	v_mfma_f32_16x16x32_bf16 v[38:41], v[188:191], v[212:215], v[38:41]
	v_mfma_f32_16x16x32_bf16 v[34:37], v[196:199], v[212:215], v[34:37]
	v_mfma_f32_16x16x32_bf16 v[22:25], v[188:191], v[220:223], v[22:25]
	v_mfma_f32_16x16x32_bf16 v[18:21], v[196:199], v[220:223], v[18:21]
	v_mfma_f32_16x16x32_bf16 v[6:9], v[188:191], v[228:231], v[6:9]
	v_mfma_f32_16x16x32_bf16 v[2:5], v[196:199], v[228:231], v[2:5]
	s_setprio 0
	s_barrier
	s_add_i32 s7, s7, 2
	s_add_u32 s54, s54, 0x100
	s_addc_u32 s55, s55, 0
	s_add_u32 vcc_lo, vcc_lo, 0x100
	s_addc_u32 vcc_hi, vcc_hi, 0
	s_cmp_gt_u32 s7, 29
	s_cbranch_scc0 .LBB0_309
	s_and_b64 vcc, exec, s[72:73]
	s_cbranch_vccz .LBB0_312
	s_barrier

; #define PG8_STAGE(bufoff, gbase, voff) do { _Pragma("unroll") for (int _i = 0; _i < 2; ++_i) \
;         __builtin_amdgcn_global_load_lds((const unsigned*)((const char*)(gbase) + (voff)[_i]), (PG8_LAS unsigned*)(lds + (bufoff) + ldsw + _i * 8192), 16, 0, 0); } while (0)
; #define PG8_LDA(dst, b, h) do { _Pragma("unroll") for (int m = 0; m < 4; ++m) _Pragma("unroll") for (int k = 0; k < 2; ++k) dst[m][k] = *(const PG8_LAS bf16x8*)(lds + PG8_SA(b, h) + aoff + m * 2048 + k * 1024); } while (0)
; #define PG8_LDB(dst, b, h) do { _Pragma("unroll") for (int n = 0; n < 2; ++n) _Pragma("unroll") for (int k = 0; k < 2; ++k) dst[n][k] = *(const PG8_LAS bf16x8*)(lds + PG8_SB(b, h) + boff + n * 2048 + k * 1024); } while (0)
; #define PG8_MMA(ai, bj, At, Bt) do { __builtin_amdgcn_s_setprio(1); _Pragma("unroll") for (int m = 0; m < 4; ++m) _Pragma("unroll") for (int n = 0; n < 2; ++n) _Pragma("unroll") for (int k = 0; k < 2; ++k) \
;         acc[ai][bj][m][n] = __builtin_amdgcn_mfma_f32_16x16x32_bf16(Bt[n][k], At[m][k], acc[ai][bj][m][n], 0, 0, 0); __builtin_amdgcn_s_setprio(0); } while (0)
; #define PG8_WAIT_V(n) asm volatile("s_waitcnt vmcnt(" #n ")" ::: "memory")
; #define PG8_WAIT_L(n) asm volatile("s_waitcnt lgkmcnt(" #n ")" ::: "memory")
; #define PG8_BAR __builtin_amdgcn_s_barrier()
; #define PG8_SCHED __builtin_amdgcn_sched_barrier(0)
; template <class Epi, class Sched, bool ALIGN_EPI = false, bool SP2 = false>
; __device__ __forceinline__ void gemm_phase(PG8_LAS unsigned char* lds, const Gemm g, const Sched& S, const Epi& E) {
;     ...
;             PG8_LDB(B0, 0, 0); PG8_LDB(B1, 0, 1); PG8_SCHED; PG8_LDA(At, 0, 0); PG8_STAGE(PG8_SA(1, 1), a1 + hstep, voffA);
;             PG8_WAIT_V(8); PG8_WAIT_L(0); PG8_BAR; PG8_MMA(0, 0, At, B0); PG8_MMA(0, 1, At, B1); PG8_BAR; PG8_SCHED;
;             PG8_LDA(At, 0, 1); PG8_STAGE(PG8_SB(0, 0), b2, voffB); PG8_STAGE(PG8_SB(0, 1), b2 + hstep, voffB); PG8_STAGE(PG8_SA(0, 0), a2, voffA);
;             PG8_WAIT_V(8); PG8_WAIT_L(0); PG8_BAR; PG8_MMA(1, 0, At, B0); PG8_MMA(1, 1, At, B1); PG8_BAR; PG8_SCHED;
.LBB0_592:
	ds_read_b128 v[156:159], v152
	ds_read_b128 v[160:163], v152 offset:1024
	ds_read_b128 v[164:167], v152 offset:2048
	ds_read_b128 v[168:171], v152 offset:3072
	ds_read_b128 v[172:175], v153
	ds_read_b128 v[176:179], v153 offset:1024
	ds_read_b128 v[180:183], v153 offset:2048
	ds_read_b128 v[188:191], v153 offset:3072
	s_add_u32 s46, s44, 0xfff80080
	s_addc_u32 s47, s45, -1
	s_cmp_eq_u32 s55, 28
	s_cselect_b32 s49, s35, s47
	s_cselect_b32 s48, s51, s46
	s_cselect_b32 s47, s37, s54
	s_cselect_b32 s46, s52, s53
	v_lshl_add_u64 v[148:149], s[44:45], 0, v[140:141]
	s_add_i32 m0, s17, 0xc000
	ds_read_b128 v[192:195], v154
	ds_read_b128 v[200:203], v154 offset:2048
	ds_read_b128 v[208:211], v154 offset:4096
	ds_read_b128 v[216:219], v154 offset:6144
	ds_read_b128 v[196:199], v154 offset:1024
	ds_read_b128 v[204:207], v154 offset:3072
	ds_read_b128 v[212:215], v154 offset:5120
	ds_read_b128 v[220:223], v154 offset:7168
	s_add_u32 s98, s44, 0xfff80000
	s_addc_u32 s99, s45, -1
	s_mov_b32 m0, s21
	s_nop 0
	global_load_lds_dwordx4 v140, s[98:99]
	s_mov_b32 m0, s33
	s_nop 0
	global_load_lds_dwordx4 v142, s[98:99]
	s_add_i32 m0, s17, 0xc000
	s_nop 0
	global_load_lds_dwordx4 v[148:149], off
	v_lshl_add_u64 v[148:149], s[44:45], 0, v[142:143]
	s_add_i32 m0, s17, 0xe000
	s_nop 0
	global_load_lds_dwordx4 v[148:149], off
	s_waitcnt vmcnt(8)
	s_waitcnt lgkmcnt(4)
	s_setprio 1
	s_barrier
	v_mfma_f32_16x16x32_bf16 v[126:129], v[156:159], v[192:195], v[126:129]
	v_mfma_f32_16x16x32_bf16 v[122:125], v[164:167], v[192:195], v[122:125]
	v_mfma_f32_16x16x32_bf16 v[118:121], v[156:159], v[200:203], v[118:121]
	v_mfma_f32_16x16x32_bf16 v[110:113], v[164:167], v[200:203], v[110:113]
	v_mfma_f32_16x16x32_bf16 v[102:105], v[156:159], v[208:211], v[102:105]
	v_mfma_f32_16x16x32_bf16 v[94:97], v[164:167], v[208:211], v[94:97]
	v_mfma_f32_16x16x32_bf16 v[86:89], v[156:159], v[216:219], v[86:89]
	v_mfma_f32_16x16x32_bf16 v[78:81], v[164:167], v[216:219], v[78:81]
	v_mfma_f32_16x16x32_bf16 v[114:117], v[172:175], v[192:195], v[114:117]
	v_mfma_f32_16x16x32_bf16 v[106:109], v[180:183], v[192:195], v[106:109]
	v_mfma_f32_16x16x32_bf16 v[98:101], v[172:175], v[200:203], v[98:101]
	v_mfma_f32_16x16x32_bf16 v[90:93], v[180:183], v[200:203], v[90:93]
	v_mfma_f32_16x16x32_bf16 v[82:85], v[172:175], v[208:211], v[82:85]
	v_mfma_f32_16x16x32_bf16 v[74:77], v[180:183], v[208:211], v[74:77]
	v_mfma_f32_16x16x32_bf16 v[70:73], v[172:175], v[216:219], v[70:73]
	v_mfma_f32_16x16x32_bf16 v[66:69], v[180:183], v[216:219], v[66:69]
	s_waitcnt lgkmcnt(0)
	v_mfma_f32_16x16x32_bf16 v[126:129], v[160:163], v[196:199], v[126:129]
	v_mfma_f32_16x16x32_bf16 v[122:125], v[168:171], v[196:199], v[122:125]
	v_mfma_f32_16x16x32_bf16 v[118:121], v[160:163], v[204:207], v[118:121]
	v_mfma_f32_16x16x32_bf16 v[110:113], v[168:171], v[204:207], v[110:113]
	v_mfma_f32_16x16x32_bf16 v[102:105], v[160:163], v[212:215], v[102:105]
	v_mfma_f32_16x16x32_bf16 v[94:97], v[168:171], v[212:215], v[94:97]
	v_mfma_f32_16x16x32_bf16 v[86:89], v[160:163], v[220:223], v[86:89]
	v_mfma_f32_16x16x32_bf16 v[78:81], v[168:171], v[220:223], v[78:81]
	v_mfma_f32_16x16x32_bf16 v[114:117], v[176:179], v[196:199], v[114:117]
	v_mfma_f32_16x16x32_bf16 v[106:109], v[188:191], v[196:199], v[106:109]
	v_mfma_f32_16x16x32_bf16 v[98:101], v[176:179], v[204:207], v[98:101]
	v_mfma_f32_16x16x32_bf16 v[90:93], v[188:191], v[204:207], v[90:93]
	v_mfma_f32_16x16x32_bf16 v[82:85], v[176:179], v[212:215], v[82:85]
	v_mfma_f32_16x16x32_bf16 v[74:77], v[188:191], v[212:215], v[74:77]
	v_mfma_f32_16x16x32_bf16 v[70:73], v[176:179], v[220:223], v[70:73]
	v_mfma_f32_16x16x32_bf16 v[66:69], v[188:191], v[220:223], v[66:69]
	s_setprio 0
	s_barrier
	s_add_i32 s56, s43, s16
	v_lshl_add_u64 v[148:149], s[46:47], 0, v[132:133]
	s_mov_b32 m0, s56
	ds_read_b128 v[192:195], v154 offset:16384
	ds_read_b128 v[196:199], v154 offset:17408
	ds_read_b128 v[200:203], v154 offset:18432
	ds_read_b128 v[204:207], v154 offset:19456
	ds_read_b128 v[208:211], v154 offset:20480
	ds_read_b128 v[212:215], v154 offset:21504
	ds_read_b128 v[216:219], v154 offset:22528
	ds_read_b128 v[220:223], v154 offset:23552
	global_load_lds_dwordx4 v[148:149], off
	s_add_i32 m0, s56, 0x2000
	s_add_u32 s56, s46, 0x80000
	v_lshl_add_u64 v[184:185], s[46:47], 0, v[136:137]
	s_addc_u32 s57, s47, 0
	s_add_i32 s58, s50, s16
	global_load_lds_dwordx4 v[184:185], off
	v_lshl_add_u64 v[224:225], s[56:57], 0, v[132:133]
	s_mov_b32 m0, s58
	v_lshl_add_u64 v[226:227], s[48:49], 0, v[134:135]
	global_load_lds_dwordx4 v[224:225], off
	v_lshl_add_u64 v[224:225], s[56:57], 0, v[136:137]
	s_add_i32 m0, s58, 0x2000
	s_nop 0
	global_load_lds_dwordx4 v[224:225], off
	v_lshl_add_u64 v[224:225], s[48:49], 0, v[130:131]
	s_mov_b32 m0, s17
	s_nop 0
	s_mov_b32 m0, s18
	s_nop 0
	s_waitcnt vmcnt(6)
	s_waitcnt lgkmcnt(0)
	s_setprio 1
	s_barrier
; #define PG8_STAGE(bufoff, gbase, voff) do { _Pragma("unroll") for (int _i = 0; _i < 2; ++_i) \
;         __builtin_amdgcn_global_load_lds((const unsigned*)((const char*)(gbase) + (voff)[_i]), (PG8_LAS unsigned*)(lds + (bufoff) + ldsw + _i * 8192), 16, 0, 0); } while (0)
; #define PG8_LDA(dst, b, h) do { _Pragma("unroll") for (int m = 0; m < 4; ++m) _Pragma("unroll") for (int k = 0; k < 2; ++k) dst[m][k] = *(const PG8_LAS bf16x8*)(lds + PG8_SA(b, h) + aoff + m * 2048 + k * 1024); } while (0)
; #define PG8_LDB(dst, b, h) do { _Pragma("unroll") for (int n = 0; n < 2; ++n) _Pragma("unroll") for (int k = 0; k < 2; ++k) dst[n][k] = *(const PG8_LAS bf16x8*)(lds + PG8_SB(b, h) + boff + n * 2048 + k * 1024); } while (0)
; #define PG8_MMA(ai, bj, At, Bt) do { __builtin_amdgcn_s_setprio(1); _Pragma("unroll") for (int m = 0; m < 4; ++m) _Pragma("unroll") for (int n = 0; n < 2; ++n) _Pragma("unroll") for (int k = 0; k < 2; ++k) \
;         acc[ai][bj][m][n] = __builtin_amdgcn_mfma_f32_16x16x32_bf16(Bt[n][k], At[m][k], acc[ai][bj][m][n], 0, 0, 0); __builtin_amdgcn_s_setprio(0); } while (0)
; #define PG8_WAIT_V(n) asm volatile("s_waitcnt vmcnt(" #n ")" ::: "memory")
; #define PG8_WAIT_L(n) asm volatile("s_waitcnt lgkmcnt(" #n ")" ::: "memory")
; #define PG8_BAR __builtin_amdgcn_s_barrier()
; #define PG8_SCHED __builtin_amdgcn_sched_barrier(0)
; template <class Epi, class Sched, bool ALIGN_EPI = false, bool SP2 = false>
; __device__ __forceinline__ void gemm_phase(PG8_LAS unsigned char* lds, const Gemm g, const Sched& S, const Epi& E) {
;     ...
;             PG8_WAIT_V(8); PG8_WAIT_L(0); PG8_BAR; PG8_MMA(1, 0, At, B0); PG8_MMA(1, 1, At, B1); PG8_BAR; PG8_SCHED;
;             PG8_LDB(B0, 1, 0); PG8_LDB(B1, 1, 1); PG8_SCHED; PG8_LDA(At, 1, 0); PG8_STAGE(PG8_SA(0, 1), a2 + hstep, voffA);
;             PG8_WAIT_V(8); PG8_WAIT_L(0); PG8_BAR; PG8_MMA(0, 0, At, B0); PG8_MMA(0, 1, At, B1); PG8_BAR; PG8_SCHED;
	v_mfma_f32_16x16x32_bf16 v[62:65], v[156:159], v[192:195], v[62:65]
	v_mfma_f32_16x16x32_bf16 v[58:61], v[164:167], v[192:195], v[58:61]
	v_mfma_f32_16x16x32_bf16 v[54:57], v[156:159], v[200:203], v[54:57]
	v_mfma_f32_16x16x32_bf16 v[46:49], v[164:167], v[200:203], v[46:49]
	v_mfma_f32_16x16x32_bf16 v[38:41], v[156:159], v[208:211], v[38:41]
	v_mfma_f32_16x16x32_bf16 v[30:33], v[164:167], v[208:211], v[30:33]
	v_mfma_f32_16x16x32_bf16 v[22:25], v[156:159], v[216:219], v[22:25]
	v_mfma_f32_16x16x32_bf16 v[14:17], v[164:167], v[216:219], v[14:17]
	v_mfma_f32_16x16x32_bf16 v[62:65], v[160:163], v[196:199], v[62:65]
	v_mfma_f32_16x16x32_bf16 v[58:61], v[168:171], v[196:199], v[58:61]
	v_mfma_f32_16x16x32_bf16 v[54:57], v[160:163], v[204:207], v[54:57]
	v_mfma_f32_16x16x32_bf16 v[46:49], v[168:171], v[204:207], v[46:49]
	v_mfma_f32_16x16x32_bf16 v[38:41], v[160:163], v[212:215], v[38:41]
	v_mfma_f32_16x16x32_bf16 v[30:33], v[168:171], v[212:215], v[30:33]
	v_mfma_f32_16x16x32_bf16 v[22:25], v[160:163], v[220:223], v[22:25]
	v_mfma_f32_16x16x32_bf16 v[14:17], v[168:171], v[220:223], v[14:17]
	v_mfma_f32_16x16x32_bf16 v[50:53], v[172:175], v[192:195], v[50:53]
	v_mfma_f32_16x16x32_bf16 v[42:45], v[180:183], v[192:195], v[42:45]
	v_mfma_f32_16x16x32_bf16 v[34:37], v[172:175], v[200:203], v[34:37]
	v_mfma_f32_16x16x32_bf16 v[26:29], v[180:183], v[200:203], v[26:29]
	v_mfma_f32_16x16x32_bf16 v[18:21], v[172:175], v[208:211], v[18:21]
	v_mfma_f32_16x16x32_bf16 v[10:13], v[180:183], v[208:211], v[10:13]
	v_mfma_f32_16x16x32_bf16 v[6:9], v[172:175], v[216:219], v[6:9]
	v_mfma_f32_16x16x32_bf16 v[2:5], v[180:183], v[216:219], v[2:5]
	v_mfma_f32_16x16x32_bf16 v[50:53], v[176:179], v[196:199], v[50:53]
	v_mfma_f32_16x16x32_bf16 v[42:45], v[188:191], v[196:199], v[42:45]
	v_mfma_f32_16x16x32_bf16 v[34:37], v[176:179], v[204:207], v[34:37]
	v_mfma_f32_16x16x32_bf16 v[26:29], v[188:191], v[204:207], v[26:29]
	v_mfma_f32_16x16x32_bf16 v[18:21], v[176:179], v[212:215], v[18:21]
	v_mfma_f32_16x16x32_bf16 v[10:13], v[188:191], v[212:215], v[10:13]
	v_mfma_f32_16x16x32_bf16 v[6:9], v[176:179], v[220:223], v[6:9]
	v_mfma_f32_16x16x32_bf16 v[2:5], v[188:191], v[220:223], v[2:5]
	s_setprio 0
	s_barrier
	s_add_i32 s56, 0, 0x18000
	v_add_u32_e32 v155, s56, v151
	s_add_i32 s57, 0, 0x1c000
	ds_read_b128 v[156:159], v155
	ds_read_b128 v[160:163], v155 offset:1024
	ds_read_b128 v[164:167], v155 offset:2048
	ds_read_b128 v[168:171], v155 offset:3072
	v_add_u32_e32 v155, s57, v151
	ds_read_b128 v[172:175], v155
	ds_read_b128 v[176:179], v155 offset:1024
	ds_read_b128 v[180:183], v155 offset:2048
	ds_read_b128 v[188:191], v155 offset:3072
	s_add_u32 s48, s48, 0x80000
	s_addc_u32 s49, s49, 0
	s_mov_b32 m0, s19
	v_lshl_add_u64 v[228:229], s[48:49], 0, v[130:131]
	ds_read_b128 v[192:195], v154 offset:32768
	ds_read_b128 v[200:203], v154 offset:34816
	ds_read_b128 v[208:211], v154 offset:36864
	ds_read_b128 v[216:219], v154 offset:38912
	ds_read_b128 v[196:199], v154 offset:33792
	ds_read_b128 v[204:207], v154 offset:35840
	ds_read_b128 v[212:215], v154 offset:37888
	ds_read_b128 v[220:223], v154 offset:39936
	s_add_u32 s98, s48, 0xfff80000
	s_addc_u32 s99, s49, -1
	s_mov_b32 m0, s17
	s_nop 0
	global_load_lds_dwordx4 v130, s[98:99]
	s_mov_b32 m0, s18
	s_nop 0
	global_load_lds_dwordx4 v134, s[98:99]
	s_mov_b32 m0, s19
	s_nop 0
	global_load_lds_dwordx4 v[228:229], off
	v_lshl_add_u64 v[228:229], s[48:49], 0, v[134:135]
	s_mov_b32 m0, s20
	s_nop 0
	global_load_lds_dwordx4 v[228:229], off
	s_waitcnt vmcnt(8)
	s_waitcnt lgkmcnt(4)
	s_setprio 1
	s_barrier
	v_mfma_f32_16x16x32_bf16 v[126:129], v[156:159], v[192:195], v[126:129]
	v_mfma_f32_16x16x32_bf16 v[122:125], v[164:167], v[192:195], v[122:125]
	v_mfma_f32_16x16x32_bf16 v[118:121], v[156:159], v[200:203], v[118:121]
	v_mfma_f32_16x16x32_bf16 v[110:113], v[164:167], v[200:203], v[110:113]
	v_mfma_f32_16x16x32_bf16 v[102:105], v[156:159], v[208:211], v[102:105]
	v_mfma_f32_16x16x32_bf16 v[94:97], v[164:167], v[208:211], v[94:97]
	v_mfma_f32_16x16x32_bf16 v[86:89], v[156:159], v[216:219], v[86:89]
	v_mfma_f32_16x16x32_bf16 v[78:81], v[164:167], v[216:219], v[78:81]
	v_mfma_f32_16x16x32_bf16 v[114:117], v[172:175], v[192:195], v[114:117]
	v_mfma_f32_16x16x32_bf16 v[106:109], v[180:183], v[192:195], v[106:109]
	v_mfma_f32_16x16x32_bf16 v[98:101], v[172:175], v[200:203], v[98:101]
	v_mfma_f32_16x16x32_bf16 v[90:93], v[180:183], v[200:203], v[90:93]
	v_mfma_f32_16x16x32_bf16 v[82:85], v[172:175], v[208:211], v[82:85]
	v_mfma_f32_16x16x32_bf16 v[74:77], v[180:183], v[208:211], v[74:77]
	v_mfma_f32_16x16x32_bf16 v[70:73], v[172:175], v[216:219], v[70:73]
	v_mfma_f32_16x16x32_bf16 v[66:69], v[180:183], v[216:219], v[66:69]
	s_waitcnt lgkmcnt(0)
	v_mfma_f32_16x16x32_bf16 v[126:129], v[160:163], v[196:199], v[126:129]
	v_mfma_f32_16x16x32_bf16 v[122:125], v[168:171], v[196:199], v[122:125]
	v_mfma_f32_16x16x32_bf16 v[118:121], v[160:163], v[204:207], v[118:121]
	v_mfma_f32_16x16x32_bf16 v[110:113], v[168:171], v[204:207], v[110:113]
	v_mfma_f32_16x16x32_bf16 v[102:105], v[160:163], v[212:215], v[102:105]
	v_mfma_f32_16x16x32_bf16 v[94:97], v[168:171], v[212:215], v[94:97]
	v_mfma_f32_16x16x32_bf16 v[86:89], v[160:163], v[220:223], v[86:89]
	v_mfma_f32_16x16x32_bf16 v[78:81], v[168:171], v[220:223], v[78:81]
	v_mfma_f32_16x16x32_bf16 v[114:117], v[176:179], v[196:199], v[114:117]
	v_mfma_f32_16x16x32_bf16 v[106:109], v[188:191], v[196:199], v[106:109]
	v_mfma_f32_16x16x32_bf16 v[98:101], v[176:179], v[204:207], v[98:101]
	v_mfma_f32_16x16x32_bf16 v[90:93], v[188:191], v[204:207], v[90:93]
	v_mfma_f32_16x16x32_bf16 v[82:85], v[176:179], v[212:215], v[82:85]
	v_mfma_f32_16x16x32_bf16 v[74:77], v[188:191], v[212:215], v[74:77]
	v_mfma_f32_16x16x32_bf16 v[70:73], v[176:179], v[220:223], v[70:73]
	v_mfma_f32_16x16x32_bf16 v[66:69], v[188:191], v[220:223], v[66:69]
	s_setprio 0
	s_barrier
; #define PG8_STAGE(bufoff, gbase, voff) do { _Pragma("unroll") for (int _i = 0; _i < 2; ++_i) \
;         __builtin_amdgcn_global_load_lds((const unsigned*)((const char*)(gbase) + (voff)[_i]), (PG8_LAS unsigned*)(lds + (bufoff) + ldsw + _i * 8192), 16, 0, 0); } while (0)
; #define PG8_LDA(dst, b, h) do { _Pragma("unroll") for (int m = 0; m < 4; ++m) _Pragma("unroll") for (int k = 0; k < 2; ++k) dst[m][k] = *(const PG8_LAS bf16x8*)(lds + PG8_SA(b, h) + aoff + m * 2048 + k * 1024); } while (0)
; #define PG8_MMA(ai, bj, At, Bt) do { __builtin_amdgcn_s_setprio(1); _Pragma("unroll") for (int m = 0; m < 4; ++m) _Pragma("unroll") for (int n = 0; n < 2; ++n) _Pragma("unroll") for (int k = 0; k < 2; ++k) \
;         acc[ai][bj][m][n] = __builtin_amdgcn_mfma_f32_16x16x32_bf16(Bt[n][k], At[m][k], acc[ai][bj][m][n], 0, 0, 0); __builtin_amdgcn_s_setprio(0); } while (0)
; #define PG8_WAIT_V(n) asm volatile("s_waitcnt vmcnt(" #n ")" ::: "memory")
; #define PG8_WAIT_L(n) asm volatile("s_waitcnt lgkmcnt(" #n ")" ::: "memory")
; #define PG8_BAR __builtin_amdgcn_s_barrier()
; #define PG8_SCHED __builtin_amdgcn_sched_barrier(0)
; template <class Epi, class Sched, bool ALIGN_EPI = false, bool SP2 = false>
; __device__ __forceinline__ void gemm_phase(PG8_LAS unsigned char* lds, const Gemm g, const Sched& S, const Epi& E) {
;     ...
;         for (int t = 0; t < nt; t += 2) {
;     ...
;             PG8_WAIT_V(8); PG8_WAIT_L(0); PG8_BAR; PG8_MMA(0, 0, At, B0); PG8_MMA(0, 1, At, B1); PG8_BAR; PG8_SCHED;
;             PG8_LDA(At, 1, 1); PG8_STAGE(PG8_SB(1, 0), b3, voffB); PG8_STAGE(PG8_SB(1, 1), b3 + hstep, voffB); PG8_STAGE(PG8_SA(1, 0), a3, voffA);
;             PG8_WAIT_V(8); PG8_WAIT_L(0); PG8_BAR; PG8_MMA(1, 0, At, B0); PG8_MMA(1, 1, At, B1); PG8_BAR; PG8_SCHED;
	s_add_i32 s48, s56, s16
	v_lshl_add_u64 v[148:149], v[148:149], 0, s[26:27]
	s_mov_b32 m0, s48
	ds_read_b128 v[192:195], v154 offset:49152
	ds_read_b128 v[196:199], v154 offset:50176
	ds_read_b128 v[200:203], v154 offset:51200
	ds_read_b128 v[204:207], v154 offset:52224
	ds_read_b128 v[208:211], v154 offset:53248
	ds_read_b128 v[212:215], v154 offset:54272
	ds_read_b128 v[216:219], v154 offset:55296
	ds_read_b128 v[220:223], v154 offset:56320
	global_load_lds_dwordx4 v[148:149], off
	s_add_i32 m0, s48, 0x2000
	s_add_u32 s46, s46, 0x80080
	v_lshl_add_u64 v[148:149], v[184:185], 0, s[26:27]
	s_addc_u32 s47, s47, 0
	s_add_i32 s48, s57, s16
	global_load_lds_dwordx4 v[148:149], off
	v_lshl_add_u64 v[148:149], s[46:47], 0, v[132:133]
	s_mov_b32 m0, s48
	s_nop 0
	global_load_lds_dwordx4 v[148:149], off
	v_lshl_add_u64 v[148:149], s[46:47], 0, v[136:137]
	s_add_i32 m0, s48, 0x2000
	s_nop 0
	global_load_lds_dwordx4 v[148:149], off
	v_lshl_add_u64 v[148:149], v[224:225], 0, s[26:27]
	s_mov_b32 m0, s21
	s_nop 0
	v_lshl_add_u64 v[148:149], v[226:227], 0, s[26:27]
	s_mov_b32 m0, s33
	s_nop 0
	s_waitcnt vmcnt(6)
	s_waitcnt lgkmcnt(0)
	s_setprio 1
	s_barrier
	v_mfma_f32_16x16x32_bf16 v[62:65], v[156:159], v[192:195], v[62:65]
	v_mfma_f32_16x16x32_bf16 v[58:61], v[164:167], v[192:195], v[58:61]
	v_mfma_f32_16x16x32_bf16 v[54:57], v[156:159], v[200:203], v[54:57]
	v_mfma_f32_16x16x32_bf16 v[46:49], v[164:167], v[200:203], v[46:49]
	v_mfma_f32_16x16x32_bf16 v[38:41], v[156:159], v[208:211], v[38:41]
	v_mfma_f32_16x16x32_bf16 v[30:33], v[164:167], v[208:211], v[30:33]
	v_mfma_f32_16x16x32_bf16 v[22:25], v[156:159], v[216:219], v[22:25]
	v_mfma_f32_16x16x32_bf16 v[14:17], v[164:167], v[216:219], v[14:17]
	v_mfma_f32_16x16x32_bf16 v[62:65], v[160:163], v[196:199], v[62:65]
	v_mfma_f32_16x16x32_bf16 v[58:61], v[168:171], v[196:199], v[58:61]
	v_mfma_f32_16x16x32_bf16 v[54:57], v[160:163], v[204:207], v[54:57]
	v_mfma_f32_16x16x32_bf16 v[46:49], v[168:171], v[204:207], v[46:49]
	v_mfma_f32_16x16x32_bf16 v[38:41], v[160:163], v[212:215], v[38:41]
	v_mfma_f32_16x16x32_bf16 v[30:33], v[168:171], v[212:215], v[30:33]
	v_mfma_f32_16x16x32_bf16 v[22:25], v[160:163], v[220:223], v[22:25]
	v_mfma_f32_16x16x32_bf16 v[14:17], v[168:171], v[220:223], v[14:17]
	v_mfma_f32_16x16x32_bf16 v[50:53], v[172:175], v[192:195], v[50:53]
	v_mfma_f32_16x16x32_bf16 v[42:45], v[180:183], v[192:195], v[42:45]
	v_mfma_f32_16x16x32_bf16 v[34:37], v[172:175], v[200:203], v[34:37]
	v_mfma_f32_16x16x32_bf16 v[26:29], v[180:183], v[200:203], v[26:29]
	v_mfma_f32_16x16x32_bf16 v[18:21], v[172:175], v[208:211], v[18:21]
	v_mfma_f32_16x16x32_bf16 v[10:13], v[180:183], v[208:211], v[10:13]
	v_mfma_f32_16x16x32_bf16 v[6:9], v[172:175], v[216:219], v[6:9]
	v_mfma_f32_16x16x32_bf16 v[2:5], v[180:183], v[216:219], v[2:5]
	v_mfma_f32_16x16x32_bf16 v[50:53], v[176:179], v[196:199], v[50:53]
	v_mfma_f32_16x16x32_bf16 v[42:45], v[188:191], v[196:199], v[42:45]
	v_mfma_f32_16x16x32_bf16 v[34:37], v[176:179], v[204:207], v[34:37]
	v_mfma_f32_16x16x32_bf16 v[26:29], v[188:191], v[204:207], v[26:29]
	v_mfma_f32_16x16x32_bf16 v[18:21], v[176:179], v[212:215], v[18:21]
	v_mfma_f32_16x16x32_bf16 v[10:13], v[188:191], v[212:215], v[10:13]
	v_mfma_f32_16x16x32_bf16 v[6:9], v[176:179], v[220:223], v[6:9]
	v_mfma_f32_16x16x32_bf16 v[2:5], v[188:191], v[220:223], v[2:5]
	s_setprio 0
	s_barrier
	s_add_i32 s55, s55, 2
	s_add_u32 s44, s44, 0x100
	s_addc_u32 s45, s45, 0
	s_add_u32 s53, s53, 0x100
	s_addc_u32 s54, s54, 0
	s_cmp_gt_u32 s55, 29
	s_cbranch_scc0 .LBB0_592
	s_and_b64 vcc, exec, s[28:29]
	s_cbranch_vccz .LBB0_595
	s_barrier

; #define PG8_STAGE(bufoff, gbase, voff) do { _Pragma("unroll") for (int _i = 0; _i < 2; ++_i) \
;         __builtin_amdgcn_global_load_lds((const unsigned*)((const char*)(gbase) + (voff)[_i]), (PG8_LAS unsigned*)(lds + (bufoff) + ldsw + _i * 8192), 16, 0, 0); } while (0)
; #define PG8_LDA(dst, b, h) do { _Pragma("unroll") for (int m = 0; m < 4; ++m) _Pragma("unroll") for (int k = 0; k < 2; ++k) dst[m][k] = *(const PG8_LAS bf16x8*)(lds + PG8_SA(b, h) + aoff + m * 2048 + k * 1024); } while (0)
; #define PG8_LDB(dst, b, h) do { _Pragma("unroll") for (int n = 0; n < 2; ++n) _Pragma("unroll") for (int k = 0; k < 2; ++k) dst[n][k] = *(const PG8_LAS bf16x8*)(lds + PG8_SB(b, h) + boff + n * 2048 + k * 1024); } while (0)
; #define PG8_MMA(ai, bj, At, Bt) do { __builtin_amdgcn_s_setprio(1); _Pragma("unroll") for (int m = 0; m < 4; ++m) _Pragma("unroll") for (int n = 0; n < 2; ++n) _Pragma("unroll") for (int k = 0; k < 2; ++k) \
;         acc[ai][bj][m][n] = __builtin_amdgcn_mfma_f32_16x16x32_bf16(Bt[n][k], At[m][k], acc[ai][bj][m][n], 0, 0, 0); __builtin_amdgcn_s_setprio(0); } while (0)
; #define PG8_WAIT_V(n) asm volatile("s_waitcnt vmcnt(" #n ")" ::: "memory")
; #define PG8_WAIT_L(n) asm volatile("s_waitcnt lgkmcnt(" #n ")" ::: "memory")
; #define PG8_BAR __builtin_amdgcn_s_barrier()
; #define PG8_SCHED __builtin_amdgcn_sched_barrier(0)
; template <class Epi, class Sched, bool ALIGN_EPI = false, bool SP2 = false>
; __device__ __forceinline__ void gemm_phase(PG8_LAS unsigned char* lds, const Gemm g, const Sched& S, const Epi& E) {
;     ...
;             PG8_LDB(B0, 0, 0); PG8_LDB(B1, 0, 1); PG8_SCHED; PG8_LDA(At, 0, 0); PG8_STAGE(PG8_SA(1, 1), a1 + hstep, voffA);
;             PG8_WAIT_V(8); PG8_WAIT_L(0); PG8_BAR; PG8_MMA(0, 0, At, B0); PG8_MMA(0, 1, At, B1); PG8_BAR; PG8_SCHED;
;             PG8_LDA(At, 0, 1); PG8_STAGE(PG8_SB(0, 0), b2, voffB); PG8_STAGE(PG8_SB(0, 1), b2 + hstep, voffB); PG8_STAGE(PG8_SA(0, 0), a2, voffA);
;             PG8_WAIT_V(8); PG8_WAIT_L(0); PG8_BAR; PG8_MMA(1, 0, At, B0); PG8_MMA(1, 1, At, B1); PG8_BAR; PG8_SCHED;
.LBB0_650:
	ds_read_b128 v[154:157], v150
	ds_read_b128 v[158:161], v150 offset:1024
	ds_read_b128 v[162:165], v150 offset:2048
	ds_read_b128 v[166:169], v150 offset:3072
	ds_read_b128 v[170:173], v151
	ds_read_b128 v[174:177], v151 offset:1024
	ds_read_b128 v[178:181], v151 offset:2048
	ds_read_b128 v[182:185], v151 offset:3072
	s_add_u32 s44, s42, 0xfff80080
	s_addc_u32 s45, s43, -1
	s_cmp_eq_u32 s59, 28
	s_cselect_b32 s47, s35, s45
	s_cselect_b32 s46, s55, s44
	s_cselect_b32 s45, s31, s58
	s_cselect_b32 s44, s56, s57
	v_lshl_add_u64 v[146:147], s[42:43], 0, v[140:141]
	s_add_i32 m0, s17, 0xc000
	ds_read_b128 v[188:191], v152
	ds_read_b128 v[196:199], v152 offset:2048
	ds_read_b128 v[204:207], v152 offset:4096
	ds_read_b128 v[212:215], v152 offset:6144
	ds_read_b128 v[192:195], v152 offset:1024
	ds_read_b128 v[200:203], v152 offset:3072
	ds_read_b128 v[208:211], v152 offset:5120
	ds_read_b128 v[216:219], v152 offset:7168
	s_add_u32 s98, s42, 0xfff80000
	s_addc_u32 s99, s43, -1
	s_mov_b32 m0, s21
	s_nop 0
	global_load_lds_dwordx4 v140, s[98:99]
	s_mov_b32 m0, s33
	s_nop 0
	global_load_lds_dwordx4 v142, s[98:99]
	s_add_i32 m0, s17, 0xc000
	s_nop 0
	global_load_lds_dwordx4 v[146:147], off
	v_lshl_add_u64 v[146:147], s[42:43], 0, v[142:143]
	s_add_i32 m0, s17, 0xe000
	s_nop 0
	global_load_lds_dwordx4 v[146:147], off
	s_waitcnt vmcnt(8)
	s_waitcnt lgkmcnt(4)
	s_setprio 1
	s_barrier
	v_mfma_f32_16x16x32_bf16 v[126:129], v[154:157], v[188:191], v[126:129]
	v_mfma_f32_16x16x32_bf16 v[122:125], v[162:165], v[188:191], v[122:125]
	v_mfma_f32_16x16x32_bf16 v[118:121], v[154:157], v[196:199], v[118:121]
	v_mfma_f32_16x16x32_bf16 v[110:113], v[162:165], v[196:199], v[110:113]
	v_mfma_f32_16x16x32_bf16 v[102:105], v[154:157], v[204:207], v[102:105]
	v_mfma_f32_16x16x32_bf16 v[94:97], v[162:165], v[204:207], v[94:97]
	v_mfma_f32_16x16x32_bf16 v[86:89], v[154:157], v[212:215], v[86:89]
	v_mfma_f32_16x16x32_bf16 v[78:81], v[162:165], v[212:215], v[78:81]
	v_mfma_f32_16x16x32_bf16 v[114:117], v[170:173], v[188:191], v[114:117]
	v_mfma_f32_16x16x32_bf16 v[106:109], v[178:181], v[188:191], v[106:109]
	v_mfma_f32_16x16x32_bf16 v[98:101], v[170:173], v[196:199], v[98:101]
	v_mfma_f32_16x16x32_bf16 v[90:93], v[178:181], v[196:199], v[90:93]
	v_mfma_f32_16x16x32_bf16 v[82:85], v[170:173], v[204:207], v[82:85]
	v_mfma_f32_16x16x32_bf16 v[74:77], v[178:181], v[204:207], v[74:77]
	v_mfma_f32_16x16x32_bf16 v[70:73], v[170:173], v[212:215], v[70:73]
	v_mfma_f32_16x16x32_bf16 v[66:69], v[178:181], v[212:215], v[66:69]
	s_waitcnt lgkmcnt(0)
	v_mfma_f32_16x16x32_bf16 v[126:129], v[158:161], v[192:195], v[126:129]
	v_mfma_f32_16x16x32_bf16 v[122:125], v[166:169], v[192:195], v[122:125]
	v_mfma_f32_16x16x32_bf16 v[118:121], v[158:161], v[200:203], v[118:121]
	v_mfma_f32_16x16x32_bf16 v[110:113], v[166:169], v[200:203], v[110:113]
	v_mfma_f32_16x16x32_bf16 v[102:105], v[158:161], v[208:211], v[102:105]
	v_mfma_f32_16x16x32_bf16 v[94:97], v[166:169], v[208:211], v[94:97]
	v_mfma_f32_16x16x32_bf16 v[86:89], v[158:161], v[216:219], v[86:89]
	v_mfma_f32_16x16x32_bf16 v[78:81], v[166:169], v[216:219], v[78:81]
	v_mfma_f32_16x16x32_bf16 v[114:117], v[174:177], v[192:195], v[114:117]
	v_mfma_f32_16x16x32_bf16 v[106:109], v[182:185], v[192:195], v[106:109]
	v_mfma_f32_16x16x32_bf16 v[98:101], v[174:177], v[200:203], v[98:101]
	v_mfma_f32_16x16x32_bf16 v[90:93], v[182:185], v[200:203], v[90:93]
	v_mfma_f32_16x16x32_bf16 v[82:85], v[174:177], v[208:211], v[82:85]
	v_mfma_f32_16x16x32_bf16 v[74:77], v[182:185], v[208:211], v[74:77]
	v_mfma_f32_16x16x32_bf16 v[70:73], v[174:177], v[216:219], v[70:73]
	v_mfma_f32_16x16x32_bf16 v[66:69], v[182:185], v[216:219], v[66:69]
	s_setprio 0
	s_barrier
	s_add_i32 s60, s48, s16
	v_lshl_add_u64 v[146:147], s[44:45], 0, v[132:133]
	s_mov_b32 m0, s60
	ds_read_b128 v[188:191], v152 offset:16384
	ds_read_b128 v[192:195], v152 offset:17408
	ds_read_b128 v[196:199], v152 offset:18432
	ds_read_b128 v[200:203], v152 offset:19456
	ds_read_b128 v[204:207], v152 offset:20480
	ds_read_b128 v[208:211], v152 offset:21504
	ds_read_b128 v[212:215], v152 offset:22528
	ds_read_b128 v[216:219], v152 offset:23552
	global_load_lds_dwordx4 v[146:147], off
	s_add_i32 m0, s60, 0x2000
	s_add_u32 s60, s44, 0x80000
	v_lshl_add_u64 v[220:221], s[44:45], 0, v[136:137]
	s_addc_u32 s61, s45, 0
	s_add_i32 s62, s49, s16
	global_load_lds_dwordx4 v[220:221], off
	v_lshl_add_u64 v[222:223], s[60:61], 0, v[132:133]
	s_mov_b32 m0, s62
	v_lshl_add_u64 v[224:225], s[46:47], 0, v[134:135]
	global_load_lds_dwordx4 v[222:223], off
	v_lshl_add_u64 v[222:223], s[60:61], 0, v[136:137]
	s_add_i32 m0, s62, 0x2000
	s_nop 0
	global_load_lds_dwordx4 v[222:223], off
	v_lshl_add_u64 v[222:223], s[46:47], 0, v[130:131]
	s_mov_b32 m0, s17
	s_nop 0
	s_mov_b32 m0, s18
	s_nop 0
	s_waitcnt vmcnt(6)
	s_waitcnt lgkmcnt(0)
	s_setprio 1
	s_barrier
; #define PG8_STAGE(bufoff, gbase, voff) do { _Pragma("unroll") for (int _i = 0; _i < 2; ++_i) \
;         __builtin_amdgcn_global_load_lds((const unsigned*)((const char*)(gbase) + (voff)[_i]), (PG8_LAS unsigned*)(lds + (bufoff) + ldsw + _i * 8192), 16, 0, 0); } while (0)
; #define PG8_LDA(dst, b, h) do { _Pragma("unroll") for (int m = 0; m < 4; ++m) _Pragma("unroll") for (int k = 0; k < 2; ++k) dst[m][k] = *(const PG8_LAS bf16x8*)(lds + PG8_SA(b, h) + aoff + m * 2048 + k * 1024); } while (0)
; #define PG8_LDB(dst, b, h) do { _Pragma("unroll") for (int n = 0; n < 2; ++n) _Pragma("unroll") for (int k = 0; k < 2; ++k) dst[n][k] = *(const PG8_LAS bf16x8*)(lds + PG8_SB(b, h) + boff + n * 2048 + k * 1024); } while (0)
; #define PG8_MMA(ai, bj, At, Bt) do { __builtin_amdgcn_s_setprio(1); _Pragma("unroll") for (int m = 0; m < 4; ++m) _Pragma("unroll") for (int n = 0; n < 2; ++n) _Pragma("unroll") for (int k = 0; k < 2; ++k) \
;         acc[ai][bj][m][n] = __builtin_amdgcn_mfma_f32_16x16x32_bf16(Bt[n][k], At[m][k], acc[ai][bj][m][n], 0, 0, 0); __builtin_amdgcn_s_setprio(0); } while (0)
; #define PG8_WAIT_V(n) asm volatile("s_waitcnt vmcnt(" #n ")" ::: "memory")
; #define PG8_WAIT_L(n) asm volatile("s_waitcnt lgkmcnt(" #n ")" ::: "memory")
; #define PG8_BAR __builtin_amdgcn_s_barrier()
; #define PG8_SCHED __builtin_amdgcn_sched_barrier(0)
; template <class Epi, class Sched, bool ALIGN_EPI = false, bool SP2 = false>
; __device__ __forceinline__ void gemm_phase(PG8_LAS unsigned char* lds, const Gemm g, const Sched& S, const Epi& E) {
;     ...
;             PG8_WAIT_V(8); PG8_WAIT_L(0); PG8_BAR; PG8_MMA(1, 0, At, B0); PG8_MMA(1, 1, At, B1); PG8_BAR; PG8_SCHED;
;             PG8_LDB(B0, 1, 0); PG8_LDB(B1, 1, 1); PG8_SCHED; PG8_LDA(At, 1, 0); PG8_STAGE(PG8_SA(0, 1), a2 + hstep, voffA);
;             PG8_WAIT_V(8); PG8_WAIT_L(0); PG8_BAR; PG8_MMA(0, 0, At, B0); PG8_MMA(0, 1, At, B1); PG8_BAR; PG8_SCHED;
	v_mfma_f32_16x16x32_bf16 v[62:65], v[154:157], v[188:191], v[62:65]
	v_mfma_f32_16x16x32_bf16 v[58:61], v[162:165], v[188:191], v[58:61]
	v_mfma_f32_16x16x32_bf16 v[54:57], v[154:157], v[196:199], v[54:57]
	v_mfma_f32_16x16x32_bf16 v[46:49], v[162:165], v[196:199], v[46:49]
	v_mfma_f32_16x16x32_bf16 v[38:41], v[154:157], v[204:207], v[38:41]
	v_mfma_f32_16x16x32_bf16 v[30:33], v[162:165], v[204:207], v[30:33]
	v_mfma_f32_16x16x32_bf16 v[22:25], v[154:157], v[212:215], v[22:25]
	v_mfma_f32_16x16x32_bf16 v[14:17], v[162:165], v[212:215], v[14:17]
	v_mfma_f32_16x16x32_bf16 v[62:65], v[158:161], v[192:195], v[62:65]
	v_mfma_f32_16x16x32_bf16 v[58:61], v[166:169], v[192:195], v[58:61]
	v_mfma_f32_16x16x32_bf16 v[54:57], v[158:161], v[200:203], v[54:57]
	v_mfma_f32_16x16x32_bf16 v[46:49], v[166:169], v[200:203], v[46:49]
	v_mfma_f32_16x16x32_bf16 v[38:41], v[158:161], v[208:211], v[38:41]
	v_mfma_f32_16x16x32_bf16 v[30:33], v[166:169], v[208:211], v[30:33]
	v_mfma_f32_16x16x32_bf16 v[22:25], v[158:161], v[216:219], v[22:25]
	v_mfma_f32_16x16x32_bf16 v[14:17], v[166:169], v[216:219], v[14:17]
	v_mfma_f32_16x16x32_bf16 v[50:53], v[170:173], v[188:191], v[50:53]
	v_mfma_f32_16x16x32_bf16 v[42:45], v[178:181], v[188:191], v[42:45]
	v_mfma_f32_16x16x32_bf16 v[34:37], v[170:173], v[196:199], v[34:37]
	v_mfma_f32_16x16x32_bf16 v[26:29], v[178:181], v[196:199], v[26:29]
	v_mfma_f32_16x16x32_bf16 v[18:21], v[170:173], v[204:207], v[18:21]
	v_mfma_f32_16x16x32_bf16 v[10:13], v[178:181], v[204:207], v[10:13]
	v_mfma_f32_16x16x32_bf16 v[6:9], v[170:173], v[212:215], v[6:9]
	v_mfma_f32_16x16x32_bf16 v[2:5], v[178:181], v[212:215], v[2:5]
	v_mfma_f32_16x16x32_bf16 v[50:53], v[174:177], v[192:195], v[50:53]
	v_mfma_f32_16x16x32_bf16 v[42:45], v[182:185], v[192:195], v[42:45]
	v_mfma_f32_16x16x32_bf16 v[34:37], v[174:177], v[200:203], v[34:37]
	v_mfma_f32_16x16x32_bf16 v[26:29], v[182:185], v[200:203], v[26:29]
	v_mfma_f32_16x16x32_bf16 v[18:21], v[174:177], v[208:211], v[18:21]
	v_mfma_f32_16x16x32_bf16 v[10:13], v[182:185], v[208:211], v[10:13]
	v_mfma_f32_16x16x32_bf16 v[6:9], v[174:177], v[216:219], v[6:9]
	v_mfma_f32_16x16x32_bf16 v[2:5], v[182:185], v[216:219], v[2:5]
	s_setprio 0
	s_barrier
	s_add_i32 s60, 0, 0x18000
	v_add_u32_e32 v153, s60, v149
	s_add_i32 s61, 0, 0x1c000
	ds_read_b128 v[154:157], v153
	ds_read_b128 v[158:161], v153 offset:1024
	ds_read_b128 v[162:165], v153 offset:2048
	ds_read_b128 v[166:169], v153 offset:3072
	v_add_u32_e32 v153, s61, v149
	ds_read_b128 v[170:173], v153
	ds_read_b128 v[174:177], v153 offset:1024
	ds_read_b128 v[178:181], v153 offset:2048
	ds_read_b128 v[182:185], v153 offset:3072
	s_add_u32 s46, s46, 0x80000
	s_addc_u32 s47, s47, 0
	s_mov_b32 m0, s19
	v_lshl_add_u64 v[226:227], s[46:47], 0, v[130:131]
	ds_read_b128 v[188:191], v152 offset:32768
	ds_read_b128 v[196:199], v152 offset:34816
	ds_read_b128 v[204:207], v152 offset:36864
	ds_read_b128 v[212:215], v152 offset:38912
	ds_read_b128 v[192:195], v152 offset:33792
	ds_read_b128 v[200:203], v152 offset:35840
	ds_read_b128 v[208:211], v152 offset:37888
	ds_read_b128 v[216:219], v152 offset:39936
	s_add_u32 s98, s46, 0xfff80000
	s_addc_u32 s99, s47, -1
	s_mov_b32 m0, s17
	s_nop 0
	global_load_lds_dwordx4 v130, s[98:99]
	s_mov_b32 m0, s18
	s_nop 0
	global_load_lds_dwordx4 v134, s[98:99]
	s_mov_b32 m0, s19
	s_nop 0
	global_load_lds_dwordx4 v[226:227], off
	v_lshl_add_u64 v[226:227], s[46:47], 0, v[134:135]
	s_mov_b32 m0, s20
	s_nop 0
	global_load_lds_dwordx4 v[226:227], off
	s_waitcnt vmcnt(8)
	s_waitcnt lgkmcnt(4)
	s_setprio 1
	s_barrier
	v_mfma_f32_16x16x32_bf16 v[126:129], v[154:157], v[188:191], v[126:129]
	v_mfma_f32_16x16x32_bf16 v[122:125], v[162:165], v[188:191], v[122:125]
	v_mfma_f32_16x16x32_bf16 v[118:121], v[154:157], v[196:199], v[118:121]
	v_mfma_f32_16x16x32_bf16 v[110:113], v[162:165], v[196:199], v[110:113]
	v_mfma_f32_16x16x32_bf16 v[102:105], v[154:157], v[204:207], v[102:105]
	v_mfma_f32_16x16x32_bf16 v[94:97], v[162:165], v[204:207], v[94:97]
	v_mfma_f32_16x16x32_bf16 v[86:89], v[154:157], v[212:215], v[86:89]
	v_mfma_f32_16x16x32_bf16 v[78:81], v[162:165], v[212:215], v[78:81]
	v_mfma_f32_16x16x32_bf16 v[114:117], v[170:173], v[188:191], v[114:117]
	v_mfma_f32_16x16x32_bf16 v[106:109], v[178:181], v[188:191], v[106:109]
	v_mfma_f32_16x16x32_bf16 v[98:101], v[170:173], v[196:199], v[98:101]
	v_mfma_f32_16x16x32_bf16 v[90:93], v[178:181], v[196:199], v[90:93]
	v_mfma_f32_16x16x32_bf16 v[82:85], v[170:173], v[204:207], v[82:85]
	v_mfma_f32_16x16x32_bf16 v[74:77], v[178:181], v[204:207], v[74:77]
	v_mfma_f32_16x16x32_bf16 v[70:73], v[170:173], v[212:215], v[70:73]
	v_mfma_f32_16x16x32_bf16 v[66:69], v[178:181], v[212:215], v[66:69]
	s_waitcnt lgkmcnt(0)
	v_mfma_f32_16x16x32_bf16 v[126:129], v[158:161], v[192:195], v[126:129]
	v_mfma_f32_16x16x32_bf16 v[122:125], v[166:169], v[192:195], v[122:125]
	v_mfma_f32_16x16x32_bf16 v[118:121], v[158:161], v[200:203], v[118:121]
	v_mfma_f32_16x16x32_bf16 v[110:113], v[166:169], v[200:203], v[110:113]
	v_mfma_f32_16x16x32_bf16 v[102:105], v[158:161], v[208:211], v[102:105]
	v_mfma_f32_16x16x32_bf16 v[94:97], v[166:169], v[208:211], v[94:97]
	v_mfma_f32_16x16x32_bf16 v[86:89], v[158:161], v[216:219], v[86:89]
	v_mfma_f32_16x16x32_bf16 v[78:81], v[166:169], v[216:219], v[78:81]
	v_mfma_f32_16x16x32_bf16 v[114:117], v[174:177], v[192:195], v[114:117]
	v_mfma_f32_16x16x32_bf16 v[106:109], v[182:185], v[192:195], v[106:109]
	v_mfma_f32_16x16x32_bf16 v[98:101], v[174:177], v[200:203], v[98:101]
	v_mfma_f32_16x16x32_bf16 v[90:93], v[182:185], v[200:203], v[90:93]
	v_mfma_f32_16x16x32_bf16 v[82:85], v[174:177], v[208:211], v[82:85]
	v_mfma_f32_16x16x32_bf16 v[74:77], v[182:185], v[208:211], v[74:77]
	v_mfma_f32_16x16x32_bf16 v[70:73], v[174:177], v[216:219], v[70:73]
	v_mfma_f32_16x16x32_bf16 v[66:69], v[182:185], v[216:219], v[66:69]
	s_setprio 0
	s_barrier
; #define PG8_STAGE(bufoff, gbase, voff) do { _Pragma("unroll") for (int _i = 0; _i < 2; ++_i) \
;         __builtin_amdgcn_global_load_lds((const unsigned*)((const char*)(gbase) + (voff)[_i]), (PG8_LAS unsigned*)(lds + (bufoff) + ldsw + _i * 8192), 16, 0, 0); } while (0)
; #define PG8_LDA(dst, b, h) do { _Pragma("unroll") for (int m = 0; m < 4; ++m) _Pragma("unroll") for (int k = 0; k < 2; ++k) dst[m][k] = *(const PG8_LAS bf16x8*)(lds + PG8_SA(b, h) + aoff + m * 2048 + k * 1024); } while (0)
; #define PG8_MMA(ai, bj, At, Bt) do { __builtin_amdgcn_s_setprio(1); _Pragma("unroll") for (int m = 0; m < 4; ++m) _Pragma("unroll") for (int n = 0; n < 2; ++n) _Pragma("unroll") for (int k = 0; k < 2; ++k) \
;         acc[ai][bj][m][n] = __builtin_amdgcn_mfma_f32_16x16x32_bf16(Bt[n][k], At[m][k], acc[ai][bj][m][n], 0, 0, 0); __builtin_amdgcn_s_setprio(0); } while (0)
; #define PG8_WAIT_V(n) asm volatile("s_waitcnt vmcnt(" #n ")" ::: "memory")
; #define PG8_WAIT_L(n) asm volatile("s_waitcnt lgkmcnt(" #n ")" ::: "memory")
; #define PG8_BAR __builtin_amdgcn_s_barrier()
; #define PG8_SCHED __builtin_amdgcn_sched_barrier(0)
; template <class Epi, class Sched, bool ALIGN_EPI = false, bool SP2 = false>
; __device__ __forceinline__ void gemm_phase(PG8_LAS unsigned char* lds, const Gemm g, const Sched& S, const Epi& E) {
;     ...
;         for (int t = 0; t < nt; t += 2) {
;     ...
;             PG8_WAIT_V(8); PG8_WAIT_L(0); PG8_BAR; PG8_MMA(0, 0, At, B0); PG8_MMA(0, 1, At, B1); PG8_BAR; PG8_SCHED;
;             PG8_LDA(At, 1, 1); PG8_STAGE(PG8_SB(1, 0), b3, voffB); PG8_STAGE(PG8_SB(1, 1), b3 + hstep, voffB); PG8_STAGE(PG8_SA(1, 0), a3, voffA);
;             PG8_WAIT_V(8); PG8_WAIT_L(0); PG8_BAR; PG8_MMA(1, 0, At, B0); PG8_MMA(1, 1, At, B1); PG8_BAR; PG8_SCHED;
	s_add_i32 s46, s60, s16
	v_lshl_add_u64 v[146:147], v[146:147], 0, s[26:27]
	s_mov_b32 m0, s46
	ds_read_b128 v[188:191], v152 offset:49152
	ds_read_b128 v[192:195], v152 offset:50176
	ds_read_b128 v[196:199], v152 offset:51200
	ds_read_b128 v[200:203], v152 offset:52224
	ds_read_b128 v[204:207], v152 offset:53248
	ds_read_b128 v[208:211], v152 offset:54272
	ds_read_b128 v[212:215], v152 offset:55296
	ds_read_b128 v[216:219], v152 offset:56320
	global_load_lds_dwordx4 v[146:147], off
	s_add_i32 m0, s46, 0x2000
	s_add_u32 s44, s44, 0x80080
	v_lshl_add_u64 v[146:147], v[220:221], 0, s[26:27]
	s_addc_u32 s45, s45, 0
	s_add_i32 s46, s61, s16
	global_load_lds_dwordx4 v[146:147], off
	v_lshl_add_u64 v[146:147], s[44:45], 0, v[132:133]
	s_mov_b32 m0, s46
	s_nop 0
	global_load_lds_dwordx4 v[146:147], off
	v_lshl_add_u64 v[146:147], s[44:45], 0, v[136:137]
	s_add_i32 m0, s46, 0x2000
	s_nop 0
	global_load_lds_dwordx4 v[146:147], off
	v_lshl_add_u64 v[146:147], v[222:223], 0, s[26:27]
	s_mov_b32 m0, s21
	s_nop 0
	v_lshl_add_u64 v[146:147], v[224:225], 0, s[26:27]
	s_mov_b32 m0, s33
	s_nop 0
	s_waitcnt vmcnt(6)
	s_waitcnt lgkmcnt(0)
	s_setprio 1
	s_barrier
	v_mfma_f32_16x16x32_bf16 v[62:65], v[154:157], v[188:191], v[62:65]
	v_mfma_f32_16x16x32_bf16 v[58:61], v[162:165], v[188:191], v[58:61]
	v_mfma_f32_16x16x32_bf16 v[54:57], v[154:157], v[196:199], v[54:57]
	v_mfma_f32_16x16x32_bf16 v[46:49], v[162:165], v[196:199], v[46:49]
	v_mfma_f32_16x16x32_bf16 v[38:41], v[154:157], v[204:207], v[38:41]
	v_mfma_f32_16x16x32_bf16 v[30:33], v[162:165], v[204:207], v[30:33]
	v_mfma_f32_16x16x32_bf16 v[22:25], v[154:157], v[212:215], v[22:25]
	v_mfma_f32_16x16x32_bf16 v[14:17], v[162:165], v[212:215], v[14:17]
	v_mfma_f32_16x16x32_bf16 v[62:65], v[158:161], v[192:195], v[62:65]
	v_mfma_f32_16x16x32_bf16 v[58:61], v[166:169], v[192:195], v[58:61]
	v_mfma_f32_16x16x32_bf16 v[54:57], v[158:161], v[200:203], v[54:57]
	v_mfma_f32_16x16x32_bf16 v[46:49], v[166:169], v[200:203], v[46:49]
	v_mfma_f32_16x16x32_bf16 v[38:41], v[158:161], v[208:211], v[38:41]
	v_mfma_f32_16x16x32_bf16 v[30:33], v[166:169], v[208:211], v[30:33]
	v_mfma_f32_16x16x32_bf16 v[22:25], v[158:161], v[216:219], v[22:25]
	v_mfma_f32_16x16x32_bf16 v[14:17], v[166:169], v[216:219], v[14:17]
	v_mfma_f32_16x16x32_bf16 v[50:53], v[170:173], v[188:191], v[50:53]
	v_mfma_f32_16x16x32_bf16 v[42:45], v[178:181], v[188:191], v[42:45]
	v_mfma_f32_16x16x32_bf16 v[34:37], v[170:173], v[196:199], v[34:37]
	v_mfma_f32_16x16x32_bf16 v[26:29], v[178:181], v[196:199], v[26:29]
	v_mfma_f32_16x16x32_bf16 v[18:21], v[170:173], v[204:207], v[18:21]
	v_mfma_f32_16x16x32_bf16 v[10:13], v[178:181], v[204:207], v[10:13]
	v_mfma_f32_16x16x32_bf16 v[6:9], v[170:173], v[212:215], v[6:9]
	v_mfma_f32_16x16x32_bf16 v[2:5], v[178:181], v[212:215], v[2:5]
	v_mfma_f32_16x16x32_bf16 v[50:53], v[174:177], v[192:195], v[50:53]
	v_mfma_f32_16x16x32_bf16 v[42:45], v[182:185], v[192:195], v[42:45]
	v_mfma_f32_16x16x32_bf16 v[34:37], v[174:177], v[200:203], v[34:37]
	v_mfma_f32_16x16x32_bf16 v[26:29], v[182:185], v[200:203], v[26:29]
	v_mfma_f32_16x16x32_bf16 v[18:21], v[174:177], v[208:211], v[18:21]
	v_mfma_f32_16x16x32_bf16 v[10:13], v[182:185], v[208:211], v[10:13]
	v_mfma_f32_16x16x32_bf16 v[6:9], v[174:177], v[216:219], v[6:9]
	v_mfma_f32_16x16x32_bf16 v[2:5], v[182:185], v[216:219], v[2:5]
	s_setprio 0
	s_barrier
	s_add_i32 s59, s59, 2
	s_add_u32 s42, s42, 0x100
	s_addc_u32 s43, s43, 0
	s_add_u32 s57, s57, 0x100
	s_addc_u32 s58, s58, 0
	s_cmp_gt_u32 s59, 29
	s_cbranch_scc0 .LBB0_650
	s_and_b64 vcc, exec, s[28:29]
	s_cbranch_vccz .LBB0_653
	s_barrier

; #define PG8_STAGE(bufoff, gbase, voff) do { _Pragma("unroll") for (int _i = 0; _i < 2; ++_i) \
;         __builtin_amdgcn_global_load_lds((const unsigned*)((const char*)(gbase) + (voff)[_i]), (PG8_LAS unsigned*)(lds + (bufoff) + ldsw + _i * 8192), 16, 0, 0); } while (0)
; #define PG8_LDA(dst, b, h) do { _Pragma("unroll") for (int m = 0; m < 4; ++m) _Pragma("unroll") for (int k = 0; k < 2; ++k) dst[m][k] = *(const PG8_LAS bf16x8*)(lds + PG8_SA(b, h) + aoff + m * 2048 + k * 1024); } while (0)
; #define PG8_LDB(dst, b, h) do { _Pragma("unroll") for (int n = 0; n < 2; ++n) _Pragma("unroll") for (int k = 0; k < 2; ++k) dst[n][k] = *(const PG8_LAS bf16x8*)(lds + PG8_SB(b, h) + boff + n * 2048 + k * 1024); } while (0)
; #define PG8_MMA(ai, bj, At, Bt) do { __builtin_amdgcn_s_setprio(1); _Pragma("unroll") for (int m = 0; m < 4; ++m) _Pragma("unroll") for (int n = 0; n < 2; ++n) _Pragma("unroll") for (int k = 0; k < 2; ++k) \
;         acc[ai][bj][m][n] = __builtin_amdgcn_mfma_f32_16x16x32_bf16(Bt[n][k], At[m][k], acc[ai][bj][m][n], 0, 0, 0); __builtin_amdgcn_s_setprio(0); } while (0)
; #define PG8_WAIT_V(n) asm volatile("s_waitcnt vmcnt(" #n ")" ::: "memory")
; #define PG8_WAIT_L(n) asm volatile("s_waitcnt lgkmcnt(" #n ")" ::: "memory")
; #define PG8_BAR __builtin_amdgcn_s_barrier()
; #define PG8_SCHED __builtin_amdgcn_sched_barrier(0)
; template <class Epi, class Sched, bool ALIGN_EPI = false, bool SP2 = false>
; __device__ __forceinline__ void gemm_phase(PG8_LAS unsigned char* lds, const Gemm g, const Sched& S, const Epi& E) {
;     ...
;             PG8_LDB(B0, 0, 0); PG8_LDB(B1, 0, 1); PG8_SCHED; PG8_LDA(At, 0, 0); PG8_STAGE(PG8_SA(1, 1), a1 + hstep, voffA);
;             PG8_WAIT_V(8); PG8_WAIT_L(0); PG8_BAR; PG8_MMA(0, 0, At, B0); PG8_MMA(0, 1, At, B1); PG8_BAR; PG8_SCHED;
;             PG8_LDA(At, 0, 1); PG8_STAGE(PG8_SB(0, 0), b2, voffB); PG8_STAGE(PG8_SB(0, 1), b2 + hstep, voffB); PG8_STAGE(PG8_SA(0, 0), a2, voffA);
;             PG8_WAIT_V(8); PG8_WAIT_L(0); PG8_BAR; PG8_MMA(1, 0, At, B0); PG8_MMA(1, 1, At, B1); PG8_BAR; PG8_SCHED;
.LBB0_816:
	s_add_u32 s46, s44, 0xfffc0080
	s_addc_u32 s47, s45, -1
	s_add_i32 s63, 0, 0x10000
	s_cmp_eq_u32 s62, 12
	s_cselect_b32 s49, s7, s47
	s_cselect_b32 s48, s37, s46
	v_add_u32_e32 v138, s63, v170
	s_cselect_b32 s47, s35, s61
	s_cselect_b32 s46, s59, s60
	s_add_i32 s66, 0, 0x14000
	ds_read_b128 v[130:133], v138
	ds_read_b128 v[134:137], v138 offset:1024
	ds_read_b128 v[156:159], v138 offset:2048
	ds_read_b128 v[160:163], v138 offset:3072
	v_add_u32_e32 v138, s66, v170
	ds_read_b128 v[174:177], v138
	ds_read_b128 v[178:181], v138 offset:1024
	ds_read_b128 v[182:185], v138 offset:2048
	ds_read_b128 v[188:191], v138 offset:3072
	v_lshl_add_u64 v[138:139], s[44:45], 0, v[148:149]
	s_add_i32 m0, s43, 0xc000
	ds_read_b128 v[192:195], v172
	ds_read_b128 v[200:203], v172 offset:2048
	ds_read_b128 v[208:211], v172 offset:4096
	ds_read_b128 v[216:219], v172 offset:6144
	ds_read_b128 v[196:199], v172 offset:1024
	ds_read_b128 v[204:207], v172 offset:3072
	ds_read_b128 v[212:215], v172 offset:5120
	ds_read_b128 v[220:223], v172 offset:7168
	s_add_u32 s98, s44, 0xfffc0000
	s_addc_u32 s99, s45, -1
	s_mov_b32 m0, s56
	s_nop 0
	global_load_lds_dwordx4 v148, s[98:99]
	s_mov_b32 m0, s57
	s_nop 0
	global_load_lds_dwordx4 v150, s[98:99]
	s_add_i32 m0, s43, 0xc000
	s_nop 0
	global_load_lds_dwordx4 v[138:139], off
	v_lshl_add_u64 v[138:139], s[44:45], 0, v[150:151]
	s_add_i32 m0, s43, 0xe000
	s_nop 0
	global_load_lds_dwordx4 v[138:139], off
	s_waitcnt vmcnt(8)
	s_waitcnt lgkmcnt(4)
	s_setprio 1
	s_barrier
	v_mfma_f32_16x16x32_bf16 v[126:129], v[130:133], v[192:195], v[126:129]
	v_mfma_f32_16x16x32_bf16 v[122:125], v[156:159], v[192:195], v[122:125]
	v_mfma_f32_16x16x32_bf16 v[110:113], v[130:133], v[200:203], v[110:113]
	v_mfma_f32_16x16x32_bf16 v[106:109], v[156:159], v[200:203], v[106:109]
	v_mfma_f32_16x16x32_bf16 v[94:97], v[130:133], v[208:211], v[94:97]
	v_mfma_f32_16x16x32_bf16 v[90:93], v[156:159], v[208:211], v[90:93]
	v_mfma_f32_16x16x32_bf16 v[78:81], v[130:133], v[216:219], v[78:81]
	v_mfma_f32_16x16x32_bf16 v[74:77], v[156:159], v[216:219], v[74:77]
	v_mfma_f32_16x16x32_bf16 v[118:121], v[174:177], v[192:195], v[118:121]
	v_mfma_f32_16x16x32_bf16 v[114:117], v[182:185], v[192:195], v[114:117]
	v_mfma_f32_16x16x32_bf16 v[102:105], v[174:177], v[200:203], v[102:105]
	v_mfma_f32_16x16x32_bf16 v[98:101], v[182:185], v[200:203], v[98:101]
	v_mfma_f32_16x16x32_bf16 v[86:89], v[174:177], v[208:211], v[86:89]
	v_mfma_f32_16x16x32_bf16 v[82:85], v[182:185], v[208:211], v[82:85]
	v_mfma_f32_16x16x32_bf16 v[70:73], v[174:177], v[216:219], v[70:73]
	v_mfma_f32_16x16x32_bf16 v[66:69], v[182:185], v[216:219], v[66:69]
	s_waitcnt lgkmcnt(0)
	v_mfma_f32_16x16x32_bf16 v[126:129], v[134:137], v[196:199], v[126:129]
	v_mfma_f32_16x16x32_bf16 v[122:125], v[160:163], v[196:199], v[122:125]
	v_mfma_f32_16x16x32_bf16 v[110:113], v[134:137], v[204:207], v[110:113]
	v_mfma_f32_16x16x32_bf16 v[106:109], v[160:163], v[204:207], v[106:109]
	v_mfma_f32_16x16x32_bf16 v[94:97], v[134:137], v[212:215], v[94:97]
	v_mfma_f32_16x16x32_bf16 v[90:93], v[160:163], v[212:215], v[90:93]
	v_mfma_f32_16x16x32_bf16 v[78:81], v[134:137], v[220:223], v[78:81]
	v_mfma_f32_16x16x32_bf16 v[74:77], v[160:163], v[220:223], v[74:77]
	v_mfma_f32_16x16x32_bf16 v[118:121], v[178:181], v[196:199], v[118:121]
	v_mfma_f32_16x16x32_bf16 v[114:117], v[188:191], v[196:199], v[114:117]
	v_mfma_f32_16x16x32_bf16 v[102:105], v[178:181], v[204:207], v[102:105]
	v_mfma_f32_16x16x32_bf16 v[98:101], v[188:191], v[204:207], v[98:101]
	v_mfma_f32_16x16x32_bf16 v[86:89], v[178:181], v[212:215], v[86:89]
	v_mfma_f32_16x16x32_bf16 v[82:85], v[188:191], v[212:215], v[82:85]
	v_mfma_f32_16x16x32_bf16 v[70:73], v[178:181], v[220:223], v[70:73]
	v_mfma_f32_16x16x32_bf16 v[66:69], v[188:191], v[220:223], v[66:69]
	s_setprio 0
	s_barrier
	s_add_i32 s63, s63, s52
	v_lshl_add_u64 v[138:139], s[46:47], 0, v[142:143]
	s_mov_b32 m0, s63
	ds_read_b128 v[192:195], v172 offset:16384
	ds_read_b128 v[196:199], v172 offset:17408
	ds_read_b128 v[200:203], v172 offset:18432
	ds_read_b128 v[204:207], v172 offset:19456
	ds_read_b128 v[208:211], v172 offset:20480
	ds_read_b128 v[212:215], v172 offset:21504
	ds_read_b128 v[216:219], v172 offset:22528
	ds_read_b128 v[220:223], v172 offset:23552
	global_load_lds_dwordx4 v[138:139], off
	s_add_i32 m0, s63, 0x2000
	s_add_u32 s64, s46, 0x40000
	v_lshl_add_u64 v[224:225], s[46:47], 0, v[146:147]
	s_addc_u32 s65, s47, 0
	s_add_i32 s63, s66, s52
	global_load_lds_dwordx4 v[224:225], off
	v_lshl_add_u64 v[226:227], s[64:65], 0, v[142:143]
	s_mov_b32 m0, s63
	v_lshl_add_u64 v[228:229], s[48:49], 0, v[144:145]
	global_load_lds_dwordx4 v[226:227], off
	v_lshl_add_u64 v[226:227], s[64:65], 0, v[146:147]
	s_add_i32 m0, s63, 0x2000
	s_nop 0
	global_load_lds_dwordx4 v[226:227], off
	v_lshl_add_u64 v[226:227], s[48:49], 0, v[140:141]
	s_mov_b32 m0, s43
	s_nop 0
	s_mov_b32 m0, s53
	s_nop 0
	s_waitcnt vmcnt(6)
	s_waitcnt lgkmcnt(0)
	s_setprio 1
	s_barrier
; #define PG8_STAGE(bufoff, gbase, voff) do { _Pragma("unroll") for (int _i = 0; _i < 2; ++_i) \
;         __builtin_amdgcn_global_load_lds((const unsigned*)((const char*)(gbase) + (voff)[_i]), (PG8_LAS unsigned*)(lds + (bufoff) + ldsw + _i * 8192), 16, 0, 0); } while (0)
; #define PG8_LDA(dst, b, h) do { _Pragma("unroll") for (int m = 0; m < 4; ++m) _Pragma("unroll") for (int k = 0; k < 2; ++k) dst[m][k] = *(const PG8_LAS bf16x8*)(lds + PG8_SA(b, h) + aoff + m * 2048 + k * 1024); } while (0)
; #define PG8_LDB(dst, b, h) do { _Pragma("unroll") for (int n = 0; n < 2; ++n) _Pragma("unroll") for (int k = 0; k < 2; ++k) dst[n][k] = *(const PG8_LAS bf16x8*)(lds + PG8_SB(b, h) + boff + n * 2048 + k * 1024); } while (0)
; #define PG8_MMA(ai, bj, At, Bt) do { __builtin_amdgcn_s_setprio(1); _Pragma("unroll") for (int m = 0; m < 4; ++m) _Pragma("unroll") for (int n = 0; n < 2; ++n) _Pragma("unroll") for (int k = 0; k < 2; ++k) \
;         acc[ai][bj][m][n] = __builtin_amdgcn_mfma_f32_16x16x32_bf16(Bt[n][k], At[m][k], acc[ai][bj][m][n], 0, 0, 0); __builtin_amdgcn_s_setprio(0); } while (0)
; #define PG8_WAIT_V(n) asm volatile("s_waitcnt vmcnt(" #n ")" ::: "memory")
; #define PG8_WAIT_L(n) asm volatile("s_waitcnt lgkmcnt(" #n ")" ::: "memory")
; #define PG8_BAR __builtin_amdgcn_s_barrier()
; #define PG8_SCHED __builtin_amdgcn_sched_barrier(0)
; template <class Epi, class Sched, bool ALIGN_EPI = false, bool SP2 = false>
; __device__ __forceinline__ void gemm_phase(PG8_LAS unsigned char* lds, const Gemm g, const Sched& S, const Epi& E) {
;     ...
;             PG8_WAIT_V(8); PG8_WAIT_L(0); PG8_BAR; PG8_MMA(1, 0, At, B0); PG8_MMA(1, 1, At, B1); PG8_BAR; PG8_SCHED;
;             PG8_LDB(B0, 1, 0); PG8_LDB(B1, 1, 1); PG8_SCHED; PG8_LDA(At, 1, 0); PG8_STAGE(PG8_SA(0, 1), a2 + hstep, voffA);
;             PG8_WAIT_V(8); PG8_WAIT_L(0); PG8_BAR; PG8_MMA(0, 0, At, B0); PG8_MMA(0, 1, At, B1); PG8_BAR; PG8_SCHED;
	v_mfma_f32_16x16x32_bf16 v[62:65], v[130:133], v[192:195], v[62:65]
	v_mfma_f32_16x16x32_bf16 v[58:61], v[156:159], v[192:195], v[58:61]
	v_mfma_f32_16x16x32_bf16 v[46:49], v[130:133], v[200:203], v[46:49]
	v_mfma_f32_16x16x32_bf16 v[42:45], v[156:159], v[200:203], v[42:45]
	v_mfma_f32_16x16x32_bf16 v[30:33], v[130:133], v[208:211], v[30:33]
	v_mfma_f32_16x16x32_bf16 v[26:29], v[156:159], v[208:211], v[26:29]
	v_mfma_f32_16x16x32_bf16 v[14:17], v[130:133], v[216:219], v[14:17]
	v_mfma_f32_16x16x32_bf16 v[10:13], v[156:159], v[216:219], v[10:13]
	v_mfma_f32_16x16x32_bf16 v[62:65], v[134:137], v[196:199], v[62:65]
	v_mfma_f32_16x16x32_bf16 v[58:61], v[160:163], v[196:199], v[58:61]
	v_mfma_f32_16x16x32_bf16 v[46:49], v[134:137], v[204:207], v[46:49]
	v_mfma_f32_16x16x32_bf16 v[42:45], v[160:163], v[204:207], v[42:45]
	v_mfma_f32_16x16x32_bf16 v[30:33], v[134:137], v[212:215], v[30:33]
	v_mfma_f32_16x16x32_bf16 v[26:29], v[160:163], v[212:215], v[26:29]
	v_mfma_f32_16x16x32_bf16 v[14:17], v[134:137], v[220:223], v[14:17]
	v_mfma_f32_16x16x32_bf16 v[10:13], v[160:163], v[220:223], v[10:13]
	v_mfma_f32_16x16x32_bf16 v[54:57], v[174:177], v[192:195], v[54:57]
	v_mfma_f32_16x16x32_bf16 v[50:53], v[182:185], v[192:195], v[50:53]
	v_mfma_f32_16x16x32_bf16 v[38:41], v[174:177], v[200:203], v[38:41]
	v_mfma_f32_16x16x32_bf16 v[34:37], v[182:185], v[200:203], v[34:37]
	v_mfma_f32_16x16x32_bf16 v[22:25], v[174:177], v[208:211], v[22:25]
	v_mfma_f32_16x16x32_bf16 v[18:21], v[182:185], v[208:211], v[18:21]
	v_mfma_f32_16x16x32_bf16 v[6:9], v[174:177], v[216:219], v[6:9]
	v_mfma_f32_16x16x32_bf16 v[2:5], v[182:185], v[216:219], v[2:5]
	v_mfma_f32_16x16x32_bf16 v[54:57], v[178:181], v[196:199], v[54:57]
	v_mfma_f32_16x16x32_bf16 v[50:53], v[188:191], v[196:199], v[50:53]
	v_mfma_f32_16x16x32_bf16 v[38:41], v[178:181], v[204:207], v[38:41]
	v_mfma_f32_16x16x32_bf16 v[34:37], v[188:191], v[204:207], v[34:37]
	v_mfma_f32_16x16x32_bf16 v[22:25], v[178:181], v[212:215], v[22:25]
	v_mfma_f32_16x16x32_bf16 v[18:21], v[188:191], v[212:215], v[18:21]
	v_mfma_f32_16x16x32_bf16 v[6:9], v[178:181], v[220:223], v[6:9]
	v_mfma_f32_16x16x32_bf16 v[2:5], v[188:191], v[220:223], v[2:5]
	s_setprio 0
	s_barrier
	s_add_i32 s63, 0, 0x18000
	s_add_i32 s64, 0, 0x1c000
	v_add_u32_e32 v160, s63, v170
	v_add_u32_e32 v173, s64, v170
	ds_read_b128 v[130:133], v160
	ds_read_b128 v[134:137], v160 offset:1024
	ds_read_b128 v[156:159], v160 offset:2048
	ds_read_b128 v[160:163], v160 offset:3072
	ds_read_b128 v[174:177], v173
	ds_read_b128 v[178:181], v173 offset:1024
	ds_read_b128 v[182:185], v173 offset:2048
	ds_read_b128 v[188:191], v173 offset:3072
	s_add_u32 s48, s48, 0x40000
	s_addc_u32 s49, s49, 0
	s_mov_b32 m0, s54
	v_lshl_add_u64 v[230:231], s[48:49], 0, v[140:141]
	ds_read_b128 v[192:195], v172 offset:32768
	ds_read_b128 v[200:203], v172 offset:34816
	ds_read_b128 v[208:211], v172 offset:36864
	ds_read_b128 v[216:219], v172 offset:38912
	ds_read_b128 v[196:199], v172 offset:33792
	ds_read_b128 v[204:207], v172 offset:35840
	ds_read_b128 v[212:215], v172 offset:37888
	ds_read_b128 v[220:223], v172 offset:39936
	s_add_u32 s98, s48, 0xfffc0000
	s_addc_u32 s99, s49, -1
	s_mov_b32 m0, s43
	s_nop 0
	global_load_lds_dwordx4 v140, s[98:99]
	s_mov_b32 m0, s53
	s_nop 0
	global_load_lds_dwordx4 v144, s[98:99]
	s_mov_b32 m0, s54
	s_nop 0
	global_load_lds_dwordx4 v[230:231], off
	v_lshl_add_u64 v[230:231], s[48:49], 0, v[144:145]
	s_mov_b32 m0, s55
	s_nop 0
	global_load_lds_dwordx4 v[230:231], off
	s_waitcnt vmcnt(8)
	s_waitcnt lgkmcnt(4)
	s_setprio 1
	s_barrier
	v_mfma_f32_16x16x32_bf16 v[126:129], v[130:133], v[192:195], v[126:129]
	v_mfma_f32_16x16x32_bf16 v[122:125], v[156:159], v[192:195], v[122:125]
	v_mfma_f32_16x16x32_bf16 v[110:113], v[130:133], v[200:203], v[110:113]
	v_mfma_f32_16x16x32_bf16 v[106:109], v[156:159], v[200:203], v[106:109]
	v_mfma_f32_16x16x32_bf16 v[94:97], v[130:133], v[208:211], v[94:97]
	v_mfma_f32_16x16x32_bf16 v[90:93], v[156:159], v[208:211], v[90:93]
	v_mfma_f32_16x16x32_bf16 v[78:81], v[130:133], v[216:219], v[78:81]
	v_mfma_f32_16x16x32_bf16 v[74:77], v[156:159], v[216:219], v[74:77]
	v_mfma_f32_16x16x32_bf16 v[118:121], v[174:177], v[192:195], v[118:121]
	v_mfma_f32_16x16x32_bf16 v[114:117], v[182:185], v[192:195], v[114:117]
	v_mfma_f32_16x16x32_bf16 v[102:105], v[174:177], v[200:203], v[102:105]
	v_mfma_f32_16x16x32_bf16 v[98:101], v[182:185], v[200:203], v[98:101]
	v_mfma_f32_16x16x32_bf16 v[86:89], v[174:177], v[208:211], v[86:89]
	v_mfma_f32_16x16x32_bf16 v[82:85], v[182:185], v[208:211], v[82:85]
	v_mfma_f32_16x16x32_bf16 v[70:73], v[174:177], v[216:219], v[70:73]
	v_mfma_f32_16x16x32_bf16 v[66:69], v[182:185], v[216:219], v[66:69]
	s_waitcnt lgkmcnt(0)
	v_mfma_f32_16x16x32_bf16 v[126:129], v[134:137], v[196:199], v[126:129]
	v_mfma_f32_16x16x32_bf16 v[122:125], v[160:163], v[196:199], v[122:125]
	v_mfma_f32_16x16x32_bf16 v[110:113], v[134:137], v[204:207], v[110:113]
	v_mfma_f32_16x16x32_bf16 v[106:109], v[160:163], v[204:207], v[106:109]
	v_mfma_f32_16x16x32_bf16 v[94:97], v[134:137], v[212:215], v[94:97]
	v_mfma_f32_16x16x32_bf16 v[90:93], v[160:163], v[212:215], v[90:93]
	v_mfma_f32_16x16x32_bf16 v[78:81], v[134:137], v[220:223], v[78:81]
	v_mfma_f32_16x16x32_bf16 v[74:77], v[160:163], v[220:223], v[74:77]
	v_mfma_f32_16x16x32_bf16 v[118:121], v[178:181], v[196:199], v[118:121]
	v_mfma_f32_16x16x32_bf16 v[114:117], v[188:191], v[196:199], v[114:117]
	v_mfma_f32_16x16x32_bf16 v[102:105], v[178:181], v[204:207], v[102:105]
	v_mfma_f32_16x16x32_bf16 v[98:101], v[188:191], v[204:207], v[98:101]
	v_mfma_f32_16x16x32_bf16 v[86:89], v[178:181], v[212:215], v[86:89]
	v_mfma_f32_16x16x32_bf16 v[82:85], v[188:191], v[212:215], v[82:85]
	v_mfma_f32_16x16x32_bf16 v[70:73], v[178:181], v[220:223], v[70:73]
	v_mfma_f32_16x16x32_bf16 v[66:69], v[188:191], v[220:223], v[66:69]
	s_setprio 0
	s_barrier
; #define PG8_STAGE(bufoff, gbase, voff) do { _Pragma("unroll") for (int _i = 0; _i < 2; ++_i) \
;         __builtin_amdgcn_global_load_lds((const unsigned*)((const char*)(gbase) + (voff)[_i]), (PG8_LAS unsigned*)(lds + (bufoff) + ldsw + _i * 8192), 16, 0, 0); } while (0)
; #define PG8_LDA(dst, b, h) do { _Pragma("unroll") for (int m = 0; m < 4; ++m) _Pragma("unroll") for (int k = 0; k < 2; ++k) dst[m][k] = *(const PG8_LAS bf16x8*)(lds + PG8_SA(b, h) + aoff + m * 2048 + k * 1024); } while (0)
; #define PG8_MMA(ai, bj, At, Bt) do { __builtin_amdgcn_s_setprio(1); _Pragma("unroll") for (int m = 0; m < 4; ++m) _Pragma("unroll") for (int n = 0; n < 2; ++n) _Pragma("unroll") for (int k = 0; k < 2; ++k) \
;         acc[ai][bj][m][n] = __builtin_amdgcn_mfma_f32_16x16x32_bf16(Bt[n][k], At[m][k], acc[ai][bj][m][n], 0, 0, 0); __builtin_amdgcn_s_setprio(0); } while (0)
; #define PG8_WAIT_V(n) asm volatile("s_waitcnt vmcnt(" #n ")" ::: "memory")
; #define PG8_WAIT_L(n) asm volatile("s_waitcnt lgkmcnt(" #n ")" ::: "memory")
; #define PG8_BAR __builtin_amdgcn_s_barrier()
; #define PG8_SCHED __builtin_amdgcn_sched_barrier(0)
; template <class Epi, class Sched, bool ALIGN_EPI = false, bool SP2 = false>
; __device__ __forceinline__ void gemm_phase(PG8_LAS unsigned char* lds, const Gemm g, const Sched& S, const Epi& E) {
;     ...
;         for (int t = 0; t < nt; t += 2) {
;     ...
;             PG8_WAIT_V(8); PG8_WAIT_L(0); PG8_BAR; PG8_MMA(0, 0, At, B0); PG8_MMA(0, 1, At, B1); PG8_BAR; PG8_SCHED;
;             PG8_LDA(At, 1, 1); PG8_STAGE(PG8_SB(1, 0), b3, voffB); PG8_STAGE(PG8_SB(1, 1), b3 + hstep, voffB); PG8_STAGE(PG8_SA(1, 0), a3, voffA);
;             PG8_WAIT_V(8); PG8_WAIT_L(0); PG8_BAR; PG8_MMA(1, 0, At, B0); PG8_MMA(1, 1, At, B1); PG8_BAR; PG8_SCHED;
	s_add_i32 s48, s63, s52
	v_lshl_add_u64 v[138:139], v[138:139], 0, s[22:23]
	s_mov_b32 m0, s48
	ds_read_b128 v[192:195], v172 offset:49152
	ds_read_b128 v[196:199], v172 offset:50176
	ds_read_b128 v[200:203], v172 offset:51200
	ds_read_b128 v[204:207], v172 offset:52224
	ds_read_b128 v[208:211], v172 offset:53248
	ds_read_b128 v[212:215], v172 offset:54272
	ds_read_b128 v[216:219], v172 offset:55296
	ds_read_b128 v[220:223], v172 offset:56320
	global_load_lds_dwordx4 v[138:139], off
	s_add_i32 m0, s48, 0x2000
	s_add_u32 s46, s46, 0x40080
	v_lshl_add_u64 v[138:139], v[224:225], 0, s[22:23]
	s_addc_u32 s47, s47, 0
	s_add_i32 s48, s64, s52
	global_load_lds_dwordx4 v[138:139], off
	v_lshl_add_u64 v[138:139], s[46:47], 0, v[142:143]
	s_mov_b32 m0, s48
	s_nop 0
	global_load_lds_dwordx4 v[138:139], off
	v_lshl_add_u64 v[138:139], s[46:47], 0, v[146:147]
	s_add_i32 m0, s48, 0x2000
	s_nop 0
	global_load_lds_dwordx4 v[138:139], off
	v_lshl_add_u64 v[138:139], v[226:227], 0, s[22:23]
	s_mov_b32 m0, s56
	s_nop 0
	v_lshl_add_u64 v[138:139], v[228:229], 0, s[22:23]
	s_mov_b32 m0, s57
	s_nop 0
	s_waitcnt vmcnt(6)
	s_waitcnt lgkmcnt(0)
	s_setprio 1
	s_barrier
	v_mfma_f32_16x16x32_bf16 v[62:65], v[130:133], v[192:195], v[62:65]
	v_mfma_f32_16x16x32_bf16 v[58:61], v[156:159], v[192:195], v[58:61]
	v_mfma_f32_16x16x32_bf16 v[46:49], v[130:133], v[200:203], v[46:49]
	v_mfma_f32_16x16x32_bf16 v[42:45], v[156:159], v[200:203], v[42:45]
	v_mfma_f32_16x16x32_bf16 v[30:33], v[130:133], v[208:211], v[30:33]
	v_mfma_f32_16x16x32_bf16 v[26:29], v[156:159], v[208:211], v[26:29]
	v_mfma_f32_16x16x32_bf16 v[14:17], v[130:133], v[216:219], v[14:17]
	v_mfma_f32_16x16x32_bf16 v[10:13], v[156:159], v[216:219], v[10:13]
	v_mfma_f32_16x16x32_bf16 v[62:65], v[134:137], v[196:199], v[62:65]
	v_mfma_f32_16x16x32_bf16 v[58:61], v[160:163], v[196:199], v[58:61]
	v_mfma_f32_16x16x32_bf16 v[46:49], v[134:137], v[204:207], v[46:49]
	v_mfma_f32_16x16x32_bf16 v[42:45], v[160:163], v[204:207], v[42:45]
	v_mfma_f32_16x16x32_bf16 v[30:33], v[134:137], v[212:215], v[30:33]
	v_mfma_f32_16x16x32_bf16 v[26:29], v[160:163], v[212:215], v[26:29]
	v_mfma_f32_16x16x32_bf16 v[14:17], v[134:137], v[220:223], v[14:17]
	v_mfma_f32_16x16x32_bf16 v[10:13], v[160:163], v[220:223], v[10:13]
	v_mfma_f32_16x16x32_bf16 v[54:57], v[174:177], v[192:195], v[54:57]
	v_mfma_f32_16x16x32_bf16 v[50:53], v[182:185], v[192:195], v[50:53]
	v_mfma_f32_16x16x32_bf16 v[38:41], v[174:177], v[200:203], v[38:41]
	v_mfma_f32_16x16x32_bf16 v[34:37], v[182:185], v[200:203], v[34:37]
	v_mfma_f32_16x16x32_bf16 v[22:25], v[174:177], v[208:211], v[22:25]
	v_mfma_f32_16x16x32_bf16 v[18:21], v[182:185], v[208:211], v[18:21]
	v_mfma_f32_16x16x32_bf16 v[6:9], v[174:177], v[216:219], v[6:9]
	v_mfma_f32_16x16x32_bf16 v[2:5], v[182:185], v[216:219], v[2:5]
	v_mfma_f32_16x16x32_bf16 v[54:57], v[178:181], v[196:199], v[54:57]
	v_mfma_f32_16x16x32_bf16 v[50:53], v[188:191], v[196:199], v[50:53]
	v_mfma_f32_16x16x32_bf16 v[38:41], v[178:181], v[204:207], v[38:41]
	v_mfma_f32_16x16x32_bf16 v[34:37], v[188:191], v[204:207], v[34:37]
	v_mfma_f32_16x16x32_bf16 v[22:25], v[178:181], v[212:215], v[22:25]
	v_mfma_f32_16x16x32_bf16 v[18:21], v[188:191], v[212:215], v[18:21]
	v_mfma_f32_16x16x32_bf16 v[6:9], v[178:181], v[220:223], v[6:9]
	v_mfma_f32_16x16x32_bf16 v[2:5], v[188:191], v[220:223], v[2:5]
	s_setprio 0
	s_barrier
	s_add_i32 s62, s62, 2
	s_add_u32 s44, s44, 0x100
	s_addc_u32 s45, s45, 0
	s_add_u32 s60, s60, 0x100
	s_addc_u32 s61, s61, 0
	s_cmp_gt_u32 s62, 13
	s_cbranch_scc0 .LBB0_816
	s_and_b64 vcc, exec, s[30:31]
	s_cbranch_vccz .LBB0_819
	s_barrier

; #define PG8_STAGE(bufoff, gbase, voff) do { _Pragma("unroll") for (int _i = 0; _i < 2; ++_i) \
;         __builtin_amdgcn_global_load_lds((const unsigned*)((const char*)(gbase) + (voff)[_i]), (PG8_LAS unsigned*)(lds + (bufoff) + ldsw + _i * 8192), 16, 0, 0); } while (0)
; #define PG8_LDA(dst, b, h) do { _Pragma("unroll") for (int m = 0; m < 4; ++m) _Pragma("unroll") for (int k = 0; k < 2; ++k) dst[m][k] = *(const PG8_LAS bf16x8*)(lds + PG8_SA(b, h) + aoff + m * 2048 + k * 1024); } while (0)
; #define PG8_LDB(dst, b, h) do { _Pragma("unroll") for (int n = 0; n < 2; ++n) _Pragma("unroll") for (int k = 0; k < 2; ++k) dst[n][k] = *(const PG8_LAS bf16x8*)(lds + PG8_SB(b, h) + boff + n * 2048 + k * 1024); } while (0)
; #define PG8_MMA(ai, bj, At, Bt) do { __builtin_amdgcn_s_setprio(1); _Pragma("unroll") for (int m = 0; m < 4; ++m) _Pragma("unroll") for (int n = 0; n < 2; ++n) _Pragma("unroll") for (int k = 0; k < 2; ++k) \
;         acc[ai][bj][m][n] = __builtin_amdgcn_mfma_f32_16x16x32_bf16(Bt[n][k], At[m][k], acc[ai][bj][m][n], 0, 0, 0); __builtin_amdgcn_s_setprio(0); } while (0)
; #define PG8_WAIT_V(n) asm volatile("s_waitcnt vmcnt(" #n ")" ::: "memory")
; #define PG8_WAIT_L(n) asm volatile("s_waitcnt lgkmcnt(" #n ")" ::: "memory")
; #define PG8_BAR __builtin_amdgcn_s_barrier()
; #define PG8_SCHED __builtin_amdgcn_sched_barrier(0)
; template <class Epi, class Sched, bool ALIGN_EPI = false, bool SP2 = false>
; __device__ __forceinline__ void gemm_phase(PG8_LAS unsigned char* lds, const Gemm g, const Sched& S, const Epi& E) {
;     ...
;             PG8_LDB(B0, 0, 0); PG8_LDB(B1, 0, 1); PG8_SCHED; PG8_LDA(At, 0, 0); PG8_STAGE(PG8_SA(1, 1), a1 + hstep, voffA);
;             PG8_WAIT_V(8); PG8_WAIT_L(0); PG8_BAR; PG8_MMA(0, 0, At, B0); PG8_MMA(0, 1, At, B1); PG8_BAR; PG8_SCHED;
;             PG8_LDA(At, 0, 1); PG8_STAGE(PG8_SB(0, 0), b2, voffB); PG8_STAGE(PG8_SB(0, 1), b2 + hstep, voffB); PG8_STAGE(PG8_SA(0, 0), a2, voffA);
;             PG8_WAIT_V(8); PG8_WAIT_L(0); PG8_BAR; PG8_MMA(1, 0, At, B0); PG8_MMA(1, 1, At, B1); PG8_BAR; PG8_SCHED;
.LBB0_941:
	ds_read_b128 v[130:133], v165
	ds_read_b128 v[134:137], v165 offset:1024
	ds_read_b128 v[138:141], v165 offset:2048
	ds_read_b128 v[142:145], v165 offset:3072
	ds_read_b128 v[158:161], v166
	ds_read_b128 v[168:171], v166 offset:1024
	ds_read_b128 v[172:175], v166 offset:2048
	ds_read_b128 v[176:179], v166 offset:3072
	s_add_u32 s34, s30, 0xfff80080
	s_addc_u32 s35, s31, -1
	s_cmp_eq_u32 s53, 28
	s_cselect_b32 s37, s23, s35
	s_cselect_b32 s36, s49, s34
	s_cselect_b32 s35, s21, s52
	s_cselect_b32 s34, s50, s51
	v_lshl_add_u64 v[184:185], s[30:31], 0, v[150:151]
	s_add_i32 m0, s17, 0xc000
	ds_read_b128 v[180:183], v167
	ds_read_b128 v[192:195], v167 offset:2048
	ds_read_b128 v[200:203], v167 offset:4096
	ds_read_b128 v[208:211], v167 offset:6144
	ds_read_b128 v[188:191], v167 offset:1024
	ds_read_b128 v[196:199], v167 offset:3072
	ds_read_b128 v[204:207], v167 offset:5120
	ds_read_b128 v[212:215], v167 offset:7168
	s_add_u32 s98, s30, 0xfff80000
	s_addc_u32 s99, s31, -1
	s_mov_b32 m0, s42
	s_nop 0
	global_load_lds_dwordx4 v150, s[98:99]
	s_mov_b32 m0, s43
	s_nop 0
	global_load_lds_dwordx4 v152, s[98:99]
	s_add_i32 m0, s17, 0xc000
	s_nop 0
	global_load_lds_dwordx4 v[184:185], off
	v_lshl_add_u64 v[184:185], s[30:31], 0, v[152:153]
	s_add_i32 m0, s17, 0xe000
	s_nop 0
	global_load_lds_dwordx4 v[184:185], off
	s_waitcnt vmcnt(8)
	s_waitcnt lgkmcnt(4)
	s_setprio 1
	s_barrier
	v_mfma_f32_16x16x32_bf16 v[126:129], v[130:133], v[180:183], v[126:129]
	v_mfma_f32_16x16x32_bf16 v[122:125], v[138:141], v[180:183], v[122:125]
	v_mfma_f32_16x16x32_bf16 v[114:117], v[130:133], v[192:195], v[114:117]
	v_mfma_f32_16x16x32_bf16 v[110:113], v[138:141], v[192:195], v[110:113]
	v_mfma_f32_16x16x32_bf16 v[98:101], v[130:133], v[200:203], v[98:101]
	v_mfma_f32_16x16x32_bf16 v[94:97], v[138:141], v[200:203], v[94:97]
	v_mfma_f32_16x16x32_bf16 v[82:85], v[130:133], v[208:211], v[82:85]
	v_mfma_f32_16x16x32_bf16 v[78:81], v[138:141], v[208:211], v[78:81]
	v_mfma_f32_16x16x32_bf16 v[118:121], v[158:161], v[180:183], v[118:121]
	v_mfma_f32_16x16x32_bf16 v[106:109], v[172:175], v[180:183], v[106:109]
	v_mfma_f32_16x16x32_bf16 v[102:105], v[158:161], v[192:195], v[102:105]
	v_mfma_f32_16x16x32_bf16 v[90:93], v[172:175], v[192:195], v[90:93]
	v_mfma_f32_16x16x32_bf16 v[86:89], v[158:161], v[200:203], v[86:89]
	v_mfma_f32_16x16x32_bf16 v[74:77], v[172:175], v[200:203], v[74:77]
	v_mfma_f32_16x16x32_bf16 v[70:73], v[158:161], v[208:211], v[70:73]
	v_mfma_f32_16x16x32_bf16 v[66:69], v[172:175], v[208:211], v[66:69]
	s_waitcnt lgkmcnt(0)
	v_mfma_f32_16x16x32_bf16 v[126:129], v[134:137], v[188:191], v[126:129]
	v_mfma_f32_16x16x32_bf16 v[122:125], v[142:145], v[188:191], v[122:125]
	v_mfma_f32_16x16x32_bf16 v[114:117], v[134:137], v[196:199], v[114:117]
	v_mfma_f32_16x16x32_bf16 v[110:113], v[142:145], v[196:199], v[110:113]
	v_mfma_f32_16x16x32_bf16 v[98:101], v[134:137], v[204:207], v[98:101]
	v_mfma_f32_16x16x32_bf16 v[94:97], v[142:145], v[204:207], v[94:97]
	v_mfma_f32_16x16x32_bf16 v[82:85], v[134:137], v[212:215], v[82:85]
	v_mfma_f32_16x16x32_bf16 v[78:81], v[142:145], v[212:215], v[78:81]
	v_mfma_f32_16x16x32_bf16 v[118:121], v[168:171], v[188:191], v[118:121]
	v_mfma_f32_16x16x32_bf16 v[106:109], v[176:179], v[188:191], v[106:109]
	v_mfma_f32_16x16x32_bf16 v[102:105], v[168:171], v[196:199], v[102:105]
	v_mfma_f32_16x16x32_bf16 v[90:93], v[176:179], v[196:199], v[90:93]
	v_mfma_f32_16x16x32_bf16 v[86:89], v[168:171], v[204:207], v[86:89]
	v_mfma_f32_16x16x32_bf16 v[74:77], v[176:179], v[204:207], v[74:77]
	v_mfma_f32_16x16x32_bf16 v[70:73], v[168:171], v[212:215], v[70:73]
	v_mfma_f32_16x16x32_bf16 v[66:69], v[176:179], v[212:215], v[66:69]
	s_setprio 0
	s_barrier
	s_add_i32 s54, s46, s16
	v_lshl_add_u64 v[184:185], s[34:35], 0, v[146:147]
	s_mov_b32 m0, s54
	ds_read_b128 v[180:183], v167 offset:16384
	ds_read_b128 v[188:191], v167 offset:17408
	ds_read_b128 v[192:195], v167 offset:18432
	ds_read_b128 v[196:199], v167 offset:19456
	ds_read_b128 v[200:203], v167 offset:20480
	ds_read_b128 v[204:207], v167 offset:21504
	ds_read_b128 v[208:211], v167 offset:22528
	ds_read_b128 v[212:215], v167 offset:23552
	global_load_lds_dwordx4 v[184:185], off
	s_add_i32 m0, s54, 0x2000
	s_add_u32 s54, s34, 0x80000
	v_lshl_add_u64 v[216:217], s[34:35], 0, v[148:149]
	s_addc_u32 s55, s35, 0
	s_add_i32 s56, s47, s16
	global_load_lds_dwordx4 v[216:217], off
	v_lshl_add_u64 v[218:219], s[54:55], 0, v[146:147]
	s_mov_b32 m0, s56
	v_lshl_add_u64 v[220:221], s[36:37], 0, v[148:149]
	global_load_lds_dwordx4 v[218:219], off
	v_lshl_add_u64 v[218:219], s[54:55], 0, v[148:149]
	s_add_i32 m0, s56, 0x2000
	s_nop 0
	global_load_lds_dwordx4 v[218:219], off
	v_lshl_add_u64 v[218:219], s[36:37], 0, v[146:147]
	s_mov_b32 m0, s17
	s_nop 0
	s_mov_b32 m0, s29
	s_nop 0
	s_waitcnt vmcnt(6)
	s_waitcnt lgkmcnt(0)
	s_setprio 1
	s_barrier
; #define PG8_STAGE(bufoff, gbase, voff) do { _Pragma("unroll") for (int _i = 0; _i < 2; ++_i) \
;         __builtin_amdgcn_global_load_lds((const unsigned*)((const char*)(gbase) + (voff)[_i]), (PG8_LAS unsigned*)(lds + (bufoff) + ldsw + _i * 8192), 16, 0, 0); } while (0)
; #define PG8_LDA(dst, b, h) do { _Pragma("unroll") for (int m = 0; m < 4; ++m) _Pragma("unroll") for (int k = 0; k < 2; ++k) dst[m][k] = *(const PG8_LAS bf16x8*)(lds + PG8_SA(b, h) + aoff + m * 2048 + k * 1024); } while (0)
; #define PG8_LDB(dst, b, h) do { _Pragma("unroll") for (int n = 0; n < 2; ++n) _Pragma("unroll") for (int k = 0; k < 2; ++k) dst[n][k] = *(const PG8_LAS bf16x8*)(lds + PG8_SB(b, h) + boff + n * 2048 + k * 1024); } while (0)
; #define PG8_MMA(ai, bj, At, Bt) do { __builtin_amdgcn_s_setprio(1); _Pragma("unroll") for (int m = 0; m < 4; ++m) _Pragma("unroll") for (int n = 0; n < 2; ++n) _Pragma("unroll") for (int k = 0; k < 2; ++k) \
;         acc[ai][bj][m][n] = __builtin_amdgcn_mfma_f32_16x16x32_bf16(Bt[n][k], At[m][k], acc[ai][bj][m][n], 0, 0, 0); __builtin_amdgcn_s_setprio(0); } while (0)
; #define PG8_WAIT_V(n) asm volatile("s_waitcnt vmcnt(" #n ")" ::: "memory")
; #define PG8_WAIT_L(n) asm volatile("s_waitcnt lgkmcnt(" #n ")" ::: "memory")
; #define PG8_BAR __builtin_amdgcn_s_barrier()
; #define PG8_SCHED __builtin_amdgcn_sched_barrier(0)
; template <class Epi, class Sched, bool ALIGN_EPI = false, bool SP2 = false>
; __device__ __forceinline__ void gemm_phase(PG8_LAS unsigned char* lds, const Gemm g, const Sched& S, const Epi& E) {
;     ...
;             PG8_WAIT_V(8); PG8_WAIT_L(0); PG8_BAR; PG8_MMA(1, 0, At, B0); PG8_MMA(1, 1, At, B1); PG8_BAR; PG8_SCHED;
;             PG8_LDB(B0, 1, 0); PG8_LDB(B1, 1, 1); PG8_SCHED; PG8_LDA(At, 1, 0); PG8_STAGE(PG8_SA(0, 1), a2 + hstep, voffA);
;             PG8_WAIT_V(8); PG8_WAIT_L(0); PG8_BAR; PG8_MMA(0, 0, At, B0); PG8_MMA(0, 1, At, B1); PG8_BAR; PG8_SCHED;
	v_mfma_f32_16x16x32_bf16 v[62:65], v[130:133], v[180:183], v[62:65]
	v_mfma_f32_16x16x32_bf16 v[58:61], v[138:141], v[180:183], v[58:61]
	v_mfma_f32_16x16x32_bf16 v[50:53], v[130:133], v[192:195], v[50:53]
	v_mfma_f32_16x16x32_bf16 v[46:49], v[138:141], v[192:195], v[46:49]
	v_mfma_f32_16x16x32_bf16 v[34:37], v[130:133], v[200:203], v[34:37]
	v_mfma_f32_16x16x32_bf16 v[30:33], v[138:141], v[200:203], v[30:33]
	v_mfma_f32_16x16x32_bf16 v[18:21], v[130:133], v[208:211], v[18:21]
	v_mfma_f32_16x16x32_bf16 v[14:17], v[138:141], v[208:211], v[14:17]
	v_mfma_f32_16x16x32_bf16 v[62:65], v[134:137], v[188:191], v[62:65]
	v_mfma_f32_16x16x32_bf16 v[58:61], v[142:145], v[188:191], v[58:61]
	v_mfma_f32_16x16x32_bf16 v[50:53], v[134:137], v[196:199], v[50:53]
	v_mfma_f32_16x16x32_bf16 v[46:49], v[142:145], v[196:199], v[46:49]
	v_mfma_f32_16x16x32_bf16 v[34:37], v[134:137], v[204:207], v[34:37]
	v_mfma_f32_16x16x32_bf16 v[30:33], v[142:145], v[204:207], v[30:33]
	v_mfma_f32_16x16x32_bf16 v[18:21], v[134:137], v[212:215], v[18:21]
	v_mfma_f32_16x16x32_bf16 v[14:17], v[142:145], v[212:215], v[14:17]
	v_mfma_f32_16x16x32_bf16 v[54:57], v[158:161], v[180:183], v[54:57]
	v_mfma_f32_16x16x32_bf16 v[42:45], v[172:175], v[180:183], v[42:45]
	v_mfma_f32_16x16x32_bf16 v[38:41], v[158:161], v[192:195], v[38:41]
	v_mfma_f32_16x16x32_bf16 v[26:29], v[172:175], v[192:195], v[26:29]
	v_mfma_f32_16x16x32_bf16 v[22:25], v[158:161], v[200:203], v[22:25]
	v_mfma_f32_16x16x32_bf16 v[10:13], v[172:175], v[200:203], v[10:13]
	v_mfma_f32_16x16x32_bf16 v[6:9], v[158:161], v[208:211], v[6:9]
	v_mfma_f32_16x16x32_bf16 v[2:5], v[172:175], v[208:211], v[2:5]
	v_mfma_f32_16x16x32_bf16 v[54:57], v[168:171], v[188:191], v[54:57]
	v_mfma_f32_16x16x32_bf16 v[42:45], v[176:179], v[188:191], v[42:45]
	v_mfma_f32_16x16x32_bf16 v[38:41], v[168:171], v[196:199], v[38:41]
	v_mfma_f32_16x16x32_bf16 v[26:29], v[176:179], v[196:199], v[26:29]
	v_mfma_f32_16x16x32_bf16 v[22:25], v[168:171], v[204:207], v[22:25]
	v_mfma_f32_16x16x32_bf16 v[10:13], v[176:179], v[204:207], v[10:13]
	v_mfma_f32_16x16x32_bf16 v[6:9], v[168:171], v[212:215], v[6:9]
	v_mfma_f32_16x16x32_bf16 v[2:5], v[176:179], v[212:215], v[2:5]
	s_setprio 0
	s_barrier
	s_add_i32 s54, 0, 0x18000
	s_add_i32 s55, 0, 0x1c000
	v_add_u32_e32 v142, s54, v163
	v_add_u32_e32 v176, s55, v163
	ds_read_b128 v[130:133], v142
	ds_read_b128 v[134:137], v142 offset:1024
	ds_read_b128 v[138:141], v142 offset:2048
	ds_read_b128 v[142:145], v142 offset:3072
	ds_read_b128 v[158:161], v176
	ds_read_b128 v[168:171], v176 offset:1024
	ds_read_b128 v[172:175], v176 offset:2048
	ds_read_b128 v[176:179], v176 offset:3072
	s_add_u32 s36, s36, 0x80000
	s_addc_u32 s37, s37, 0
	s_mov_b32 m0, s33
	v_lshl_add_u64 v[222:223], s[36:37], 0, v[146:147]
	ds_read_b128 v[180:183], v167 offset:32768
	ds_read_b128 v[192:195], v167 offset:34816
	ds_read_b128 v[200:203], v167 offset:36864
	ds_read_b128 v[208:211], v167 offset:38912
	ds_read_b128 v[188:191], v167 offset:33792
	ds_read_b128 v[196:199], v167 offset:35840
	ds_read_b128 v[204:207], v167 offset:37888
	ds_read_b128 v[212:215], v167 offset:39936
	s_add_u32 s98, s36, 0xfff80000
	s_addc_u32 s99, s37, -1
	s_mov_b32 m0, s17
	s_nop 0
	global_load_lds_dwordx4 v146, s[98:99]
	s_mov_b32 m0, s29
	s_nop 0
	global_load_lds_dwordx4 v148, s[98:99]
	s_mov_b32 m0, s33
	s_nop 0
	global_load_lds_dwordx4 v[222:223], off
	v_lshl_add_u64 v[222:223], s[36:37], 0, v[148:149]
	s_mov_b32 m0, s38
	s_nop 0
	global_load_lds_dwordx4 v[222:223], off
	s_waitcnt vmcnt(8)
	s_waitcnt lgkmcnt(4)
	s_setprio 1
	s_barrier
	v_mfma_f32_16x16x32_bf16 v[126:129], v[130:133], v[180:183], v[126:129]
	v_mfma_f32_16x16x32_bf16 v[122:125], v[138:141], v[180:183], v[122:125]
	v_mfma_f32_16x16x32_bf16 v[114:117], v[130:133], v[192:195], v[114:117]
	v_mfma_f32_16x16x32_bf16 v[110:113], v[138:141], v[192:195], v[110:113]
	v_mfma_f32_16x16x32_bf16 v[98:101], v[130:133], v[200:203], v[98:101]
	v_mfma_f32_16x16x32_bf16 v[94:97], v[138:141], v[200:203], v[94:97]
	v_mfma_f32_16x16x32_bf16 v[82:85], v[130:133], v[208:211], v[82:85]
	v_mfma_f32_16x16x32_bf16 v[78:81], v[138:141], v[208:211], v[78:81]
	v_mfma_f32_16x16x32_bf16 v[118:121], v[158:161], v[180:183], v[118:121]
	v_mfma_f32_16x16x32_bf16 v[106:109], v[172:175], v[180:183], v[106:109]
	v_mfma_f32_16x16x32_bf16 v[102:105], v[158:161], v[192:195], v[102:105]
	v_mfma_f32_16x16x32_bf16 v[90:93], v[172:175], v[192:195], v[90:93]
	v_mfma_f32_16x16x32_bf16 v[86:89], v[158:161], v[200:203], v[86:89]
	v_mfma_f32_16x16x32_bf16 v[74:77], v[172:175], v[200:203], v[74:77]
	v_mfma_f32_16x16x32_bf16 v[70:73], v[158:161], v[208:211], v[70:73]
	v_mfma_f32_16x16x32_bf16 v[66:69], v[172:175], v[208:211], v[66:69]
	s_waitcnt lgkmcnt(0)
	v_mfma_f32_16x16x32_bf16 v[126:129], v[134:137], v[188:191], v[126:129]
	v_mfma_f32_16x16x32_bf16 v[122:125], v[142:145], v[188:191], v[122:125]
	v_mfma_f32_16x16x32_bf16 v[114:117], v[134:137], v[196:199], v[114:117]
	v_mfma_f32_16x16x32_bf16 v[110:113], v[142:145], v[196:199], v[110:113]
	v_mfma_f32_16x16x32_bf16 v[98:101], v[134:137], v[204:207], v[98:101]
	v_mfma_f32_16x16x32_bf16 v[94:97], v[142:145], v[204:207], v[94:97]
	v_mfma_f32_16x16x32_bf16 v[82:85], v[134:137], v[212:215], v[82:85]
	v_mfma_f32_16x16x32_bf16 v[78:81], v[142:145], v[212:215], v[78:81]
	v_mfma_f32_16x16x32_bf16 v[118:121], v[168:171], v[188:191], v[118:121]
	v_mfma_f32_16x16x32_bf16 v[106:109], v[176:179], v[188:191], v[106:109]
	v_mfma_f32_16x16x32_bf16 v[102:105], v[168:171], v[196:199], v[102:105]
	v_mfma_f32_16x16x32_bf16 v[90:93], v[176:179], v[196:199], v[90:93]
	v_mfma_f32_16x16x32_bf16 v[86:89], v[168:171], v[204:207], v[86:89]
	v_mfma_f32_16x16x32_bf16 v[74:77], v[176:179], v[204:207], v[74:77]
	v_mfma_f32_16x16x32_bf16 v[70:73], v[168:171], v[212:215], v[70:73]
	v_mfma_f32_16x16x32_bf16 v[66:69], v[176:179], v[212:215], v[66:69]
	s_setprio 0
	s_barrier
; #define PG8_STAGE(bufoff, gbase, voff) do { _Pragma("unroll") for (int _i = 0; _i < 2; ++_i) \
;         __builtin_amdgcn_global_load_lds((const unsigned*)((const char*)(gbase) + (voff)[_i]), (PG8_LAS unsigned*)(lds + (bufoff) + ldsw + _i * 8192), 16, 0, 0); } while (0)
; #define PG8_LDA(dst, b, h) do { _Pragma("unroll") for (int m = 0; m < 4; ++m) _Pragma("unroll") for (int k = 0; k < 2; ++k) dst[m][k] = *(const PG8_LAS bf16x8*)(lds + PG8_SA(b, h) + aoff + m * 2048 + k * 1024); } while (0)
; #define PG8_MMA(ai, bj, At, Bt) do { __builtin_amdgcn_s_setprio(1); _Pragma("unroll") for (int m = 0; m < 4; ++m) _Pragma("unroll") for (int n = 0; n < 2; ++n) _Pragma("unroll") for (int k = 0; k < 2; ++k) \
;         acc[ai][bj][m][n] = __builtin_amdgcn_mfma_f32_16x16x32_bf16(Bt[n][k], At[m][k], acc[ai][bj][m][n], 0, 0, 0); __builtin_amdgcn_s_setprio(0); } while (0)
; #define PG8_WAIT_V(n) asm volatile("s_waitcnt vmcnt(" #n ")" ::: "memory")
; #define PG8_WAIT_L(n) asm volatile("s_waitcnt lgkmcnt(" #n ")" ::: "memory")
; #define PG8_BAR __builtin_amdgcn_s_barrier()
; #define PG8_SCHED __builtin_amdgcn_sched_barrier(0)
; template <class Epi, class Sched, bool ALIGN_EPI = false, bool SP2 = false>
; __device__ __forceinline__ void gemm_phase(PG8_LAS unsigned char* lds, const Gemm g, const Sched& S, const Epi& E) {
;     ...
;         for (int t = 0; t < nt; t += 2) {
;             const bool last = (t == nt - 2);
;     ...
;             PG8_LDA(At, 1, 1); PG8_STAGE(PG8_SB(1, 0), b3, voffB); PG8_STAGE(PG8_SB(1, 1), b3 + hstep, voffB); PG8_STAGE(PG8_SA(1, 0), a3, voffA);
;             PG8_WAIT_V(8); PG8_WAIT_L(0); PG8_BAR; PG8_MMA(1, 0, At, B0); PG8_MMA(1, 1, At, B1); PG8_BAR; PG8_SCHED;
	s_add_i32 s36, s54, s16
	v_lshl_add_u64 v[184:185], v[184:185], 0, s[8:9]
	s_mov_b32 m0, s36
	ds_read_b128 v[180:183], v167 offset:49152
	ds_read_b128 v[188:191], v167 offset:50176
	ds_read_b128 v[192:195], v167 offset:51200
	ds_read_b128 v[196:199], v167 offset:52224
	ds_read_b128 v[200:203], v167 offset:53248
	ds_read_b128 v[204:207], v167 offset:54272
	ds_read_b128 v[208:211], v167 offset:55296
	ds_read_b128 v[212:215], v167 offset:56320
	global_load_lds_dwordx4 v[184:185], off
	s_add_i32 m0, s36, 0x2000
	s_add_u32 s34, s34, 0x80080
	v_lshl_add_u64 v[184:185], v[216:217], 0, s[8:9]
	s_addc_u32 s35, s35, 0
	s_add_i32 s36, s55, s16
	global_load_lds_dwordx4 v[184:185], off
	v_lshl_add_u64 v[184:185], s[34:35], 0, v[146:147]
	s_mov_b32 m0, s36
	s_nop 0
	global_load_lds_dwordx4 v[184:185], off
	v_lshl_add_u64 v[184:185], s[34:35], 0, v[148:149]
	s_add_i32 m0, s36, 0x2000
	s_nop 0
	global_load_lds_dwordx4 v[184:185], off
	v_lshl_add_u64 v[184:185], v[218:219], 0, s[8:9]
	s_mov_b32 m0, s42
	s_nop 0
	v_lshl_add_u64 v[184:185], v[220:221], 0, s[8:9]
	s_mov_b32 m0, s43
	s_nop 0
	s_waitcnt vmcnt(6)
	s_waitcnt lgkmcnt(0)
	s_setprio 1
	s_barrier
	v_mfma_f32_16x16x32_bf16 v[62:65], v[130:133], v[180:183], v[62:65]
	v_mfma_f32_16x16x32_bf16 v[58:61], v[138:141], v[180:183], v[58:61]
	v_mfma_f32_16x16x32_bf16 v[50:53], v[130:133], v[192:195], v[50:53]
	v_mfma_f32_16x16x32_bf16 v[46:49], v[138:141], v[192:195], v[46:49]
	v_mfma_f32_16x16x32_bf16 v[34:37], v[130:133], v[200:203], v[34:37]
	v_mfma_f32_16x16x32_bf16 v[30:33], v[138:141], v[200:203], v[30:33]
	v_mfma_f32_16x16x32_bf16 v[18:21], v[130:133], v[208:211], v[18:21]
	v_mfma_f32_16x16x32_bf16 v[14:17], v[138:141], v[208:211], v[14:17]
	v_mfma_f32_16x16x32_bf16 v[62:65], v[134:137], v[188:191], v[62:65]
	v_mfma_f32_16x16x32_bf16 v[58:61], v[142:145], v[188:191], v[58:61]
	v_mfma_f32_16x16x32_bf16 v[50:53], v[134:137], v[196:199], v[50:53]
	v_mfma_f32_16x16x32_bf16 v[46:49], v[142:145], v[196:199], v[46:49]
	v_mfma_f32_16x16x32_bf16 v[34:37], v[134:137], v[204:207], v[34:37]
	v_mfma_f32_16x16x32_bf16 v[30:33], v[142:145], v[204:207], v[30:33]
	v_mfma_f32_16x16x32_bf16 v[18:21], v[134:137], v[212:215], v[18:21]
	v_mfma_f32_16x16x32_bf16 v[14:17], v[142:145], v[212:215], v[14:17]
	v_mfma_f32_16x16x32_bf16 v[54:57], v[158:161], v[180:183], v[54:57]
	v_mfma_f32_16x16x32_bf16 v[42:45], v[172:175], v[180:183], v[42:45]
	v_mfma_f32_16x16x32_bf16 v[38:41], v[158:161], v[192:195], v[38:41]
	v_mfma_f32_16x16x32_bf16 v[26:29], v[172:175], v[192:195], v[26:29]
	v_mfma_f32_16x16x32_bf16 v[22:25], v[158:161], v[200:203], v[22:25]
	v_mfma_f32_16x16x32_bf16 v[10:13], v[172:175], v[200:203], v[10:13]
	v_mfma_f32_16x16x32_bf16 v[6:9], v[158:161], v[208:211], v[6:9]
	v_mfma_f32_16x16x32_bf16 v[2:5], v[172:175], v[208:211], v[2:5]
	v_mfma_f32_16x16x32_bf16 v[54:57], v[168:171], v[188:191], v[54:57]
	v_mfma_f32_16x16x32_bf16 v[42:45], v[176:179], v[188:191], v[42:45]
	v_mfma_f32_16x16x32_bf16 v[38:41], v[168:171], v[196:199], v[38:41]
	v_mfma_f32_16x16x32_bf16 v[26:29], v[176:179], v[196:199], v[26:29]
	v_mfma_f32_16x16x32_bf16 v[22:25], v[168:171], v[204:207], v[22:25]
	v_mfma_f32_16x16x32_bf16 v[10:13], v[176:179], v[204:207], v[10:13]
	v_mfma_f32_16x16x32_bf16 v[6:9], v[168:171], v[212:215], v[6:9]
	v_mfma_f32_16x16x32_bf16 v[2:5], v[176:179], v[212:215], v[2:5]
	s_setprio 0
	s_barrier
	s_add_i32 s53, s53, 2
	s_add_u32 s30, s30, 0x100
	s_addc_u32 s31, s31, 0
	s_add_u32 s51, s51, 0x100
	s_addc_u32 s52, s52, 0
	s_cmp_gt_u32 s53, 29
	s_cbranch_scc0 .LBB0_941
	s_and_b64 vcc, exec, s[18:19]
	s_cbranch_vccz .LBB0_944
	s_barrier

; #define PG8_STAGE(bufoff, gbase, voff) do { _Pragma("unroll") for (int _i = 0; _i < 2; ++_i) \
;         __builtin_amdgcn_global_load_lds((const unsigned*)((const char*)(gbase) + (voff)[_i]), (PG8_LAS unsigned*)(lds + (bufoff) + ldsw + _i * 8192), 16, 0, 0); } while (0)
; #define PG8_LDA(dst, b, h) do { _Pragma("unroll") for (int m = 0; m < 4; ++m) _Pragma("unroll") for (int k = 0; k < 2; ++k) dst[m][k] = *(const PG8_LAS bf16x8*)(lds + PG8_SA(b, h) + aoff + m * 2048 + k * 1024); } while (0)
; #define PG8_LDB(dst, b, h) do { _Pragma("unroll") for (int n = 0; n < 2; ++n) _Pragma("unroll") for (int k = 0; k < 2; ++k) dst[n][k] = *(const PG8_LAS bf16x8*)(lds + PG8_SB(b, h) + boff + n * 2048 + k * 1024); } while (0)
; #define PG8_MMA(ai, bj, At, Bt) do { __builtin_amdgcn_s_setprio(1); _Pragma("unroll") for (int m = 0; m < 4; ++m) _Pragma("unroll") for (int n = 0; n < 2; ++n) _Pragma("unroll") for (int k = 0; k < 2; ++k) \
;         acc[ai][bj][m][n] = __builtin_amdgcn_mfma_f32_16x16x32_bf16(Bt[n][k], At[m][k], acc[ai][bj][m][n], 0, 0, 0); __builtin_amdgcn_s_setprio(0); } while (0)
; #define PG8_WAIT_V(n) asm volatile("s_waitcnt vmcnt(" #n ")" ::: "memory")
; #define PG8_WAIT_L(n) asm volatile("s_waitcnt lgkmcnt(" #n ")" ::: "memory")
; #define PG8_BAR __builtin_amdgcn_s_barrier()
; #define PG8_SCHED __builtin_amdgcn_sched_barrier(0)
; template <class Epi, class Sched, bool ALIGN_EPI = false, bool SP2 = false>
; __device__ __forceinline__ void gemm_phase(PG8_LAS unsigned char* lds, const Gemm g, const Sched& S, const Epi& E) {
;     ...
;             PG8_LDB(B0, 0, 0); PG8_LDB(B1, 0, 1); PG8_SCHED; PG8_LDA(At, 0, 0); PG8_STAGE(PG8_SA(1, 1), a1 + hstep, voffA);
;             PG8_WAIT_V(8); PG8_WAIT_L(0); PG8_BAR; PG8_MMA(0, 0, At, B0); PG8_MMA(0, 1, At, B1); PG8_BAR; PG8_SCHED;
;             PG8_LDA(At, 0, 1); PG8_STAGE(PG8_SB(0, 0), b2, voffB); PG8_STAGE(PG8_SB(0, 1), b2 + hstep, voffB); PG8_STAGE(PG8_SA(0, 0), a2, voffA);
;             PG8_WAIT_V(8); PG8_WAIT_L(0); PG8_BAR; PG8_MMA(1, 0, At, B0); PG8_MMA(1, 1, At, B1); PG8_BAR; PG8_SCHED;
.LBB0_1098:
	ds_read_b128 v[154:157], v151
	ds_read_b128 v[158:161], v151 offset:1024
	ds_read_b128 v[162:165], v151 offset:2048
	ds_read_b128 v[166:169], v151 offset:3072
	ds_read_b128 v[170:173], v152
	ds_read_b128 v[174:177], v152 offset:1024
	ds_read_b128 v[178:181], v152 offset:2048
	ds_read_b128 v[182:185], v152 offset:3072
	s_add_u32 s30, s28, 0xfff80080
	s_addc_u32 s31, s29, -1
	s_cmp_eq_u32 s53, 28
	s_cselect_b32 s35, s21, s31
	s_cselect_b32 s34, s49, s30
	s_cselect_b32 s31, s19, s52
	s_cselect_b32 s30, s50, s51
	v_lshl_add_u64 v[146:147], s[28:29], 0, v[138:139]
	s_add_i32 m0, s27, 0xc000
	ds_read_b128 v[188:191], v153
	ds_read_b128 v[196:199], v153 offset:2048
	ds_read_b128 v[204:207], v153 offset:4096
	ds_read_b128 v[212:215], v153 offset:6144
	ds_read_b128 v[192:195], v153 offset:1024
	ds_read_b128 v[200:203], v153 offset:3072
	ds_read_b128 v[208:211], v153 offset:5120
	ds_read_b128 v[216:219], v153 offset:7168
	s_add_u32 s98, s28, 0xfff80000
	s_addc_u32 s99, s29, -1
	s_mov_b32 m0, s41
	s_nop 0
	global_load_lds_dwordx4 v138, s[98:99]
	s_mov_b32 m0, s42
	s_nop 0
	global_load_lds_dwordx4 v140, s[98:99]
	s_add_i32 m0, s27, 0xc000
	s_nop 0
	global_load_lds_dwordx4 v[146:147], off
	v_lshl_add_u64 v[146:147], s[28:29], 0, v[140:141]
	s_add_i32 m0, s27, 0xe000
	s_nop 0
	global_load_lds_dwordx4 v[146:147], off
	s_waitcnt vmcnt(8)
	s_waitcnt lgkmcnt(4)
	s_setprio 1
	s_barrier
	v_mfma_f32_16x16x32_bf16 v[126:129], v[154:157], v[188:191], v[126:129]
	v_mfma_f32_16x16x32_bf16 v[122:125], v[162:165], v[188:191], v[122:125]
	v_mfma_f32_16x16x32_bf16 v[110:113], v[154:157], v[196:199], v[110:113]
	v_mfma_f32_16x16x32_bf16 v[106:109], v[162:165], v[196:199], v[106:109]
	v_mfma_f32_16x16x32_bf16 v[94:97], v[154:157], v[204:207], v[94:97]
	v_mfma_f32_16x16x32_bf16 v[90:93], v[162:165], v[204:207], v[90:93]
	v_mfma_f32_16x16x32_bf16 v[78:81], v[154:157], v[212:215], v[78:81]
	v_mfma_f32_16x16x32_bf16 v[74:77], v[162:165], v[212:215], v[74:77]
	v_mfma_f32_16x16x32_bf16 v[118:121], v[170:173], v[188:191], v[118:121]
	v_mfma_f32_16x16x32_bf16 v[114:117], v[178:181], v[188:191], v[114:117]
	v_mfma_f32_16x16x32_bf16 v[102:105], v[170:173], v[196:199], v[102:105]
	v_mfma_f32_16x16x32_bf16 v[98:101], v[178:181], v[196:199], v[98:101]
	v_mfma_f32_16x16x32_bf16 v[86:89], v[170:173], v[204:207], v[86:89]
	v_mfma_f32_16x16x32_bf16 v[82:85], v[178:181], v[204:207], v[82:85]
	v_mfma_f32_16x16x32_bf16 v[70:73], v[170:173], v[212:215], v[70:73]
	v_mfma_f32_16x16x32_bf16 v[66:69], v[178:181], v[212:215], v[66:69]
	s_waitcnt lgkmcnt(0)
	v_mfma_f32_16x16x32_bf16 v[126:129], v[158:161], v[192:195], v[126:129]
	v_mfma_f32_16x16x32_bf16 v[122:125], v[166:169], v[192:195], v[122:125]
	v_mfma_f32_16x16x32_bf16 v[110:113], v[158:161], v[200:203], v[110:113]
	v_mfma_f32_16x16x32_bf16 v[106:109], v[166:169], v[200:203], v[106:109]
	v_mfma_f32_16x16x32_bf16 v[94:97], v[158:161], v[208:211], v[94:97]
	v_mfma_f32_16x16x32_bf16 v[90:93], v[166:169], v[208:211], v[90:93]
	v_mfma_f32_16x16x32_bf16 v[78:81], v[158:161], v[216:219], v[78:81]
	v_mfma_f32_16x16x32_bf16 v[74:77], v[166:169], v[216:219], v[74:77]
	v_mfma_f32_16x16x32_bf16 v[118:121], v[174:177], v[192:195], v[118:121]
	v_mfma_f32_16x16x32_bf16 v[114:117], v[182:185], v[192:195], v[114:117]
	v_mfma_f32_16x16x32_bf16 v[102:105], v[174:177], v[200:203], v[102:105]
	v_mfma_f32_16x16x32_bf16 v[98:101], v[182:185], v[200:203], v[98:101]
	v_mfma_f32_16x16x32_bf16 v[86:89], v[174:177], v[208:211], v[86:89]
	v_mfma_f32_16x16x32_bf16 v[82:85], v[182:185], v[208:211], v[82:85]
	v_mfma_f32_16x16x32_bf16 v[70:73], v[174:177], v[216:219], v[70:73]
	v_mfma_f32_16x16x32_bf16 v[66:69], v[182:185], v[216:219], v[66:69]
	s_setprio 0
	s_barrier
	s_add_i32 s54, s45, s3
	v_lshl_add_u64 v[146:147], s[30:31], 0, v[134:135]
	s_mov_b32 m0, s54
	ds_read_b128 v[188:191], v153 offset:16384
	ds_read_b128 v[192:195], v153 offset:17408
	ds_read_b128 v[196:199], v153 offset:18432
	ds_read_b128 v[200:203], v153 offset:19456
	ds_read_b128 v[204:207], v153 offset:20480
	ds_read_b128 v[208:211], v153 offset:21504
	ds_read_b128 v[212:215], v153 offset:22528
	ds_read_b128 v[216:219], v153 offset:23552
	global_load_lds_dwordx4 v[146:147], off
	s_add_i32 m0, s54, 0x2000
	s_add_u32 s54, s30, 0x80000
	v_lshl_add_u64 v[220:221], s[30:31], 0, v[130:131]
	s_addc_u32 s55, s31, 0
	s_add_i32 s56, s46, s3
	global_load_lds_dwordx4 v[220:221], off
	v_lshl_add_u64 v[222:223], s[54:55], 0, v[134:135]
	s_mov_b32 m0, s56
	v_lshl_add_u64 v[224:225], s[34:35], 0, v[132:133]
	global_load_lds_dwordx4 v[222:223], off
	v_lshl_add_u64 v[222:223], s[54:55], 0, v[130:131]
	s_add_i32 m0, s56, 0x2000
	s_nop 0
	global_load_lds_dwordx4 v[222:223], off
	v_lshl_add_u64 v[222:223], s[34:35], 0, v[136:137]
	s_mov_b32 m0, s27
	s_nop 0
	s_mov_b32 m0, s37
	s_nop 0
	s_waitcnt vmcnt(6)
	s_waitcnt lgkmcnt(0)
	s_setprio 1
	s_barrier
; #define PG8_STAGE(bufoff, gbase, voff) do { _Pragma("unroll") for (int _i = 0; _i < 2; ++_i) \
;         __builtin_amdgcn_global_load_lds((const unsigned*)((const char*)(gbase) + (voff)[_i]), (PG8_LAS unsigned*)(lds + (bufoff) + ldsw + _i * 8192), 16, 0, 0); } while (0)
; #define PG8_LDA(dst, b, h) do { _Pragma("unroll") for (int m = 0; m < 4; ++m) _Pragma("unroll") for (int k = 0; k < 2; ++k) dst[m][k] = *(const PG8_LAS bf16x8*)(lds + PG8_SA(b, h) + aoff + m * 2048 + k * 1024); } while (0)
; #define PG8_LDB(dst, b, h) do { _Pragma("unroll") for (int n = 0; n < 2; ++n) _Pragma("unroll") for (int k = 0; k < 2; ++k) dst[n][k] = *(const PG8_LAS bf16x8*)(lds + PG8_SB(b, h) + boff + n * 2048 + k * 1024); } while (0)
; #define PG8_MMA(ai, bj, At, Bt) do { __builtin_amdgcn_s_setprio(1); _Pragma("unroll") for (int m = 0; m < 4; ++m) _Pragma("unroll") for (int n = 0; n < 2; ++n) _Pragma("unroll") for (int k = 0; k < 2; ++k) \
;         acc[ai][bj][m][n] = __builtin_amdgcn_mfma_f32_16x16x32_bf16(Bt[n][k], At[m][k], acc[ai][bj][m][n], 0, 0, 0); __builtin_amdgcn_s_setprio(0); } while (0)
; #define PG8_WAIT_V(n) asm volatile("s_waitcnt vmcnt(" #n ")" ::: "memory")
; #define PG8_WAIT_L(n) asm volatile("s_waitcnt lgkmcnt(" #n ")" ::: "memory")
; #define PG8_BAR __builtin_amdgcn_s_barrier()
; #define PG8_SCHED __builtin_amdgcn_sched_barrier(0)
; template <class Epi, class Sched, bool ALIGN_EPI = false, bool SP2 = false>
; __device__ __forceinline__ void gemm_phase(PG8_LAS unsigned char* lds, const Gemm g, const Sched& S, const Epi& E) {
;     ...
;             PG8_WAIT_V(8); PG8_WAIT_L(0); PG8_BAR; PG8_MMA(1, 0, At, B0); PG8_MMA(1, 1, At, B1); PG8_BAR; PG8_SCHED;
;             PG8_LDB(B0, 1, 0); PG8_LDB(B1, 1, 1); PG8_SCHED; PG8_LDA(At, 1, 0); PG8_STAGE(PG8_SA(0, 1), a2 + hstep, voffA);
;             PG8_WAIT_V(8); PG8_WAIT_L(0); PG8_BAR; PG8_MMA(0, 0, At, B0); PG8_MMA(0, 1, At, B1); PG8_BAR; PG8_SCHED;
	v_mfma_f32_16x16x32_bf16 v[62:65], v[154:157], v[188:191], v[62:65]
	v_mfma_f32_16x16x32_bf16 v[58:61], v[162:165], v[188:191], v[58:61]
	v_mfma_f32_16x16x32_bf16 v[46:49], v[154:157], v[196:199], v[46:49]
	v_mfma_f32_16x16x32_bf16 v[42:45], v[162:165], v[196:199], v[42:45]
	v_mfma_f32_16x16x32_bf16 v[30:33], v[154:157], v[204:207], v[30:33]
	v_mfma_f32_16x16x32_bf16 v[26:29], v[162:165], v[204:207], v[26:29]
	v_mfma_f32_16x16x32_bf16 v[14:17], v[154:157], v[212:215], v[14:17]
	v_mfma_f32_16x16x32_bf16 v[10:13], v[162:165], v[212:215], v[10:13]
	v_mfma_f32_16x16x32_bf16 v[62:65], v[158:161], v[192:195], v[62:65]
	v_mfma_f32_16x16x32_bf16 v[58:61], v[166:169], v[192:195], v[58:61]
	v_mfma_f32_16x16x32_bf16 v[46:49], v[158:161], v[200:203], v[46:49]
	v_mfma_f32_16x16x32_bf16 v[42:45], v[166:169], v[200:203], v[42:45]
	v_mfma_f32_16x16x32_bf16 v[30:33], v[158:161], v[208:211], v[30:33]
	v_mfma_f32_16x16x32_bf16 v[26:29], v[166:169], v[208:211], v[26:29]
	v_mfma_f32_16x16x32_bf16 v[14:17], v[158:161], v[216:219], v[14:17]
	v_mfma_f32_16x16x32_bf16 v[10:13], v[166:169], v[216:219], v[10:13]
	v_mfma_f32_16x16x32_bf16 v[54:57], v[170:173], v[188:191], v[54:57]
	v_mfma_f32_16x16x32_bf16 v[50:53], v[178:181], v[188:191], v[50:53]
	v_mfma_f32_16x16x32_bf16 v[38:41], v[170:173], v[196:199], v[38:41]
	v_mfma_f32_16x16x32_bf16 v[34:37], v[178:181], v[196:199], v[34:37]
	v_mfma_f32_16x16x32_bf16 v[22:25], v[170:173], v[204:207], v[22:25]
	v_mfma_f32_16x16x32_bf16 v[18:21], v[178:181], v[204:207], v[18:21]
	v_mfma_f32_16x16x32_bf16 v[6:9], v[170:173], v[212:215], v[6:9]
	v_mfma_f32_16x16x32_bf16 v[2:5], v[178:181], v[212:215], v[2:5]
	v_mfma_f32_16x16x32_bf16 v[54:57], v[174:177], v[192:195], v[54:57]
	v_mfma_f32_16x16x32_bf16 v[50:53], v[182:185], v[192:195], v[50:53]
	v_mfma_f32_16x16x32_bf16 v[38:41], v[174:177], v[200:203], v[38:41]
	v_mfma_f32_16x16x32_bf16 v[34:37], v[182:185], v[200:203], v[34:37]
	v_mfma_f32_16x16x32_bf16 v[22:25], v[174:177], v[208:211], v[22:25]
	v_mfma_f32_16x16x32_bf16 v[18:21], v[182:185], v[208:211], v[18:21]
	v_mfma_f32_16x16x32_bf16 v[6:9], v[174:177], v[216:219], v[6:9]
	v_mfma_f32_16x16x32_bf16 v[2:5], v[182:185], v[216:219], v[2:5]
	s_setprio 0
	s_barrier
	s_add_i32 s54, 0, 0x18000
	s_add_i32 s55, 0, 0x1c000
	v_add_u32_e32 v166, s54, v149
	v_add_u32_e32 v182, s55, v149
	ds_read_b128 v[154:157], v166
	ds_read_b128 v[158:161], v166 offset:1024
	ds_read_b128 v[162:165], v166 offset:2048
	ds_read_b128 v[166:169], v166 offset:3072
	ds_read_b128 v[170:173], v182
	ds_read_b128 v[174:177], v182 offset:1024
	ds_read_b128 v[178:181], v182 offset:2048
	ds_read_b128 v[182:185], v182 offset:3072
	s_add_u32 s34, s34, 0x80000
	s_addc_u32 s35, s35, 0
	s_mov_b32 m0, s38
	v_lshl_add_u64 v[226:227], s[34:35], 0, v[136:137]
	ds_read_b128 v[188:191], v153 offset:32768
	ds_read_b128 v[196:199], v153 offset:34816
	ds_read_b128 v[204:207], v153 offset:36864
	ds_read_b128 v[212:215], v153 offset:38912
	ds_read_b128 v[192:195], v153 offset:33792
	ds_read_b128 v[200:203], v153 offset:35840
	ds_read_b128 v[208:211], v153 offset:37888
	ds_read_b128 v[216:219], v153 offset:39936
	s_add_u32 s98, s34, 0xfff80000
	s_addc_u32 s99, s35, -1
	s_mov_b32 m0, s27
	s_nop 0
	global_load_lds_dwordx4 v136, s[98:99]
	s_mov_b32 m0, s37
	s_nop 0
	global_load_lds_dwordx4 v132, s[98:99]
	s_mov_b32 m0, s38
	s_nop 0
	global_load_lds_dwordx4 v[226:227], off
	v_lshl_add_u64 v[226:227], s[34:35], 0, v[132:133]
	s_mov_b32 m0, s39
	s_nop 0
	global_load_lds_dwordx4 v[226:227], off
	s_waitcnt vmcnt(8)
	s_waitcnt lgkmcnt(4)
	s_setprio 1
	s_barrier
	v_mfma_f32_16x16x32_bf16 v[126:129], v[154:157], v[188:191], v[126:129]
	v_mfma_f32_16x16x32_bf16 v[122:125], v[162:165], v[188:191], v[122:125]
	v_mfma_f32_16x16x32_bf16 v[110:113], v[154:157], v[196:199], v[110:113]
	v_mfma_f32_16x16x32_bf16 v[106:109], v[162:165], v[196:199], v[106:109]
	v_mfma_f32_16x16x32_bf16 v[94:97], v[154:157], v[204:207], v[94:97]
	v_mfma_f32_16x16x32_bf16 v[90:93], v[162:165], v[204:207], v[90:93]
	v_mfma_f32_16x16x32_bf16 v[78:81], v[154:157], v[212:215], v[78:81]
	v_mfma_f32_16x16x32_bf16 v[74:77], v[162:165], v[212:215], v[74:77]
	v_mfma_f32_16x16x32_bf16 v[118:121], v[170:173], v[188:191], v[118:121]
	v_mfma_f32_16x16x32_bf16 v[114:117], v[178:181], v[188:191], v[114:117]
	v_mfma_f32_16x16x32_bf16 v[102:105], v[170:173], v[196:199], v[102:105]
	v_mfma_f32_16x16x32_bf16 v[98:101], v[178:181], v[196:199], v[98:101]
	v_mfma_f32_16x16x32_bf16 v[86:89], v[170:173], v[204:207], v[86:89]
	v_mfma_f32_16x16x32_bf16 v[82:85], v[178:181], v[204:207], v[82:85]
	v_mfma_f32_16x16x32_bf16 v[70:73], v[170:173], v[212:215], v[70:73]
	v_mfma_f32_16x16x32_bf16 v[66:69], v[178:181], v[212:215], v[66:69]
	s_waitcnt lgkmcnt(0)
	v_mfma_f32_16x16x32_bf16 v[126:129], v[158:161], v[192:195], v[126:129]
	v_mfma_f32_16x16x32_bf16 v[122:125], v[166:169], v[192:195], v[122:125]
	v_mfma_f32_16x16x32_bf16 v[110:113], v[158:161], v[200:203], v[110:113]
	v_mfma_f32_16x16x32_bf16 v[106:109], v[166:169], v[200:203], v[106:109]
	v_mfma_f32_16x16x32_bf16 v[94:97], v[158:161], v[208:211], v[94:97]
	v_mfma_f32_16x16x32_bf16 v[90:93], v[166:169], v[208:211], v[90:93]
	v_mfma_f32_16x16x32_bf16 v[78:81], v[158:161], v[216:219], v[78:81]
	v_mfma_f32_16x16x32_bf16 v[74:77], v[166:169], v[216:219], v[74:77]
	v_mfma_f32_16x16x32_bf16 v[118:121], v[174:177], v[192:195], v[118:121]
	v_mfma_f32_16x16x32_bf16 v[114:117], v[182:185], v[192:195], v[114:117]
	v_mfma_f32_16x16x32_bf16 v[102:105], v[174:177], v[200:203], v[102:105]
	v_mfma_f32_16x16x32_bf16 v[98:101], v[182:185], v[200:203], v[98:101]
	v_mfma_f32_16x16x32_bf16 v[86:89], v[174:177], v[208:211], v[86:89]
	v_mfma_f32_16x16x32_bf16 v[82:85], v[182:185], v[208:211], v[82:85]
	v_mfma_f32_16x16x32_bf16 v[70:73], v[174:177], v[216:219], v[70:73]
	v_mfma_f32_16x16x32_bf16 v[66:69], v[182:185], v[216:219], v[66:69]
	s_setprio 0
	s_barrier
; #define PG8_STAGE(bufoff, gbase, voff) do { _Pragma("unroll") for (int _i = 0; _i < 2; ++_i) \
;         __builtin_amdgcn_global_load_lds((const unsigned*)((const char*)(gbase) + (voff)[_i]), (PG8_LAS unsigned*)(lds + (bufoff) + ldsw + _i * 8192), 16, 0, 0); } while (0)
; #define PG8_LDA(dst, b, h) do { _Pragma("unroll") for (int m = 0; m < 4; ++m) _Pragma("unroll") for (int k = 0; k < 2; ++k) dst[m][k] = *(const PG8_LAS bf16x8*)(lds + PG8_SA(b, h) + aoff + m * 2048 + k * 1024); } while (0)
; #define PG8_MMA(ai, bj, At, Bt) do { __builtin_amdgcn_s_setprio(1); _Pragma("unroll") for (int m = 0; m < 4; ++m) _Pragma("unroll") for (int n = 0; n < 2; ++n) _Pragma("unroll") for (int k = 0; k < 2; ++k) \
;         acc[ai][bj][m][n] = __builtin_amdgcn_mfma_f32_16x16x32_bf16(Bt[n][k], At[m][k], acc[ai][bj][m][n], 0, 0, 0); __builtin_amdgcn_s_setprio(0); } while (0)
; #define PG8_WAIT_V(n) asm volatile("s_waitcnt vmcnt(" #n ")" ::: "memory")
; #define PG8_WAIT_L(n) asm volatile("s_waitcnt lgkmcnt(" #n ")" ::: "memory")
; #define PG8_BAR __builtin_amdgcn_s_barrier()
; #define PG8_SCHED __builtin_amdgcn_sched_barrier(0)
; template <class Epi, class Sched, bool ALIGN_EPI = false, bool SP2 = false>
; __device__ __forceinline__ void gemm_phase(PG8_LAS unsigned char* lds, const Gemm g, const Sched& S, const Epi& E) {
;     ...
;         for (int t = 0; t < nt; t += 2) {
;             const bool last = (t == nt - 2);
;     ...
;             PG8_LDA(At, 1, 1); PG8_STAGE(PG8_SB(1, 0), b3, voffB); PG8_STAGE(PG8_SB(1, 1), b3 + hstep, voffB); PG8_STAGE(PG8_SA(1, 0), a3, voffA);
;             PG8_WAIT_V(8); PG8_WAIT_L(0); PG8_BAR; PG8_MMA(1, 0, At, B0); PG8_MMA(1, 1, At, B1); PG8_BAR; PG8_SCHED;
	s_add_i32 s34, s54, s3
	v_lshl_add_u64 v[146:147], v[146:147], 0, s[8:9]
	s_mov_b32 m0, s34
	ds_read_b128 v[188:191], v153 offset:49152
	ds_read_b128 v[192:195], v153 offset:50176
	ds_read_b128 v[196:199], v153 offset:51200
	ds_read_b128 v[200:203], v153 offset:52224
	ds_read_b128 v[204:207], v153 offset:53248
	ds_read_b128 v[208:211], v153 offset:54272
	ds_read_b128 v[212:215], v153 offset:55296
	ds_read_b128 v[216:219], v153 offset:56320
	global_load_lds_dwordx4 v[146:147], off
	s_add_i32 m0, s34, 0x2000
	s_add_u32 s30, s30, 0x80080
	v_lshl_add_u64 v[146:147], v[220:221], 0, s[8:9]
	s_addc_u32 s31, s31, 0
	s_add_i32 s34, s55, s3
	global_load_lds_dwordx4 v[146:147], off
	v_lshl_add_u64 v[146:147], s[30:31], 0, v[134:135]
	s_mov_b32 m0, s34
	s_nop 0
	global_load_lds_dwordx4 v[146:147], off
	v_lshl_add_u64 v[146:147], s[30:31], 0, v[130:131]
	s_add_i32 m0, s34, 0x2000
	s_nop 0
	global_load_lds_dwordx4 v[146:147], off
	v_lshl_add_u64 v[146:147], v[222:223], 0, s[8:9]
	s_mov_b32 m0, s41
	s_nop 0
	v_lshl_add_u64 v[146:147], v[224:225], 0, s[8:9]
	s_mov_b32 m0, s42
	s_nop 0
	s_waitcnt vmcnt(6)
	s_waitcnt lgkmcnt(0)
	s_setprio 1
	s_barrier
	v_mfma_f32_16x16x32_bf16 v[62:65], v[154:157], v[188:191], v[62:65]
	v_mfma_f32_16x16x32_bf16 v[58:61], v[162:165], v[188:191], v[58:61]
	v_mfma_f32_16x16x32_bf16 v[46:49], v[154:157], v[196:199], v[46:49]
	v_mfma_f32_16x16x32_bf16 v[42:45], v[162:165], v[196:199], v[42:45]
	v_mfma_f32_16x16x32_bf16 v[30:33], v[154:157], v[204:207], v[30:33]
	v_mfma_f32_16x16x32_bf16 v[26:29], v[162:165], v[204:207], v[26:29]
	v_mfma_f32_16x16x32_bf16 v[14:17], v[154:157], v[212:215], v[14:17]
	v_mfma_f32_16x16x32_bf16 v[10:13], v[162:165], v[212:215], v[10:13]
	v_mfma_f32_16x16x32_bf16 v[62:65], v[158:161], v[192:195], v[62:65]
	v_mfma_f32_16x16x32_bf16 v[58:61], v[166:169], v[192:195], v[58:61]
	v_mfma_f32_16x16x32_bf16 v[46:49], v[158:161], v[200:203], v[46:49]
	v_mfma_f32_16x16x32_bf16 v[42:45], v[166:169], v[200:203], v[42:45]
	v_mfma_f32_16x16x32_bf16 v[30:33], v[158:161], v[208:211], v[30:33]
	v_mfma_f32_16x16x32_bf16 v[26:29], v[166:169], v[208:211], v[26:29]
	v_mfma_f32_16x16x32_bf16 v[14:17], v[158:161], v[216:219], v[14:17]
	v_mfma_f32_16x16x32_bf16 v[10:13], v[166:169], v[216:219], v[10:13]
	v_mfma_f32_16x16x32_bf16 v[54:57], v[170:173], v[188:191], v[54:57]
	v_mfma_f32_16x16x32_bf16 v[50:53], v[178:181], v[188:191], v[50:53]
	v_mfma_f32_16x16x32_bf16 v[38:41], v[170:173], v[196:199], v[38:41]
	v_mfma_f32_16x16x32_bf16 v[34:37], v[178:181], v[196:199], v[34:37]
	v_mfma_f32_16x16x32_bf16 v[22:25], v[170:173], v[204:207], v[22:25]
	v_mfma_f32_16x16x32_bf16 v[18:21], v[178:181], v[204:207], v[18:21]
	v_mfma_f32_16x16x32_bf16 v[6:9], v[170:173], v[212:215], v[6:9]
	v_mfma_f32_16x16x32_bf16 v[2:5], v[178:181], v[212:215], v[2:5]
	v_mfma_f32_16x16x32_bf16 v[54:57], v[174:177], v[192:195], v[54:57]
	v_mfma_f32_16x16x32_bf16 v[50:53], v[182:185], v[192:195], v[50:53]
	v_mfma_f32_16x16x32_bf16 v[38:41], v[174:177], v[200:203], v[38:41]
	v_mfma_f32_16x16x32_bf16 v[34:37], v[182:185], v[200:203], v[34:37]
	v_mfma_f32_16x16x32_bf16 v[22:25], v[174:177], v[208:211], v[22:25]
	v_mfma_f32_16x16x32_bf16 v[18:21], v[182:185], v[208:211], v[18:21]
	v_mfma_f32_16x16x32_bf16 v[6:9], v[174:177], v[216:219], v[6:9]
	v_mfma_f32_16x16x32_bf16 v[2:5], v[182:185], v[216:219], v[2:5]
	s_setprio 0
	s_barrier
	s_add_i32 s53, s53, 2
	s_add_u32 s28, s28, 0x100
	s_addc_u32 s29, s29, 0
	s_add_u32 s51, s51, 0x100
	s_addc_u32 s52, s52, 0
	s_cmp_gt_u32 s53, 29
	s_cbranch_scc0 .LBB0_1098
	s_and_b64 vcc, exec, s[16:17]
	s_cbranch_vccz .LBB0_1101
	s_barrier

; #define PG8_STAGE(bufoff, gbase, voff) do { _Pragma("unroll") for (int _i = 0; _i < 2; ++_i) \
;         __builtin_amdgcn_global_load_lds((const unsigned*)((const char*)(gbase) + (voff)[_i]), (PG8_LAS unsigned*)(lds + (bufoff) + ldsw + _i * 8192), 16, 0, 0); } while (0)
; #define PG8_LDA(dst, b, h) do { _Pragma("unroll") for (int m = 0; m < 4; ++m) _Pragma("unroll") for (int k = 0; k < 2; ++k) dst[m][k] = *(const PG8_LAS bf16x8*)(lds + PG8_SA(b, h) + aoff + m * 2048 + k * 1024); } while (0)
; #define PG8_LDB(dst, b, h) do { _Pragma("unroll") for (int n = 0; n < 2; ++n) _Pragma("unroll") for (int k = 0; k < 2; ++k) dst[n][k] = *(const PG8_LAS bf16x8*)(lds + PG8_SB(b, h) + boff + n * 2048 + k * 1024); } while (0)
; #define PG8_MMA(ai, bj, At, Bt) do { __builtin_amdgcn_s_setprio(1); _Pragma("unroll") for (int m = 0; m < 4; ++m) _Pragma("unroll") for (int n = 0; n < 2; ++n) _Pragma("unroll") for (int k = 0; k < 2; ++k) \
;         acc[ai][bj][m][n] = __builtin_amdgcn_mfma_f32_16x16x32_bf16(Bt[n][k], At[m][k], acc[ai][bj][m][n], 0, 0, 0); __builtin_amdgcn_s_setprio(0); } while (0)
; #define PG8_WAIT_V(n) asm volatile("s_waitcnt vmcnt(" #n ")" ::: "memory")
; #define PG8_WAIT_L(n) asm volatile("s_waitcnt lgkmcnt(" #n ")" ::: "memory")
; #define PG8_BAR __builtin_amdgcn_s_barrier()
; #define PG8_SCHED __builtin_amdgcn_sched_barrier(0)
; template <class Epi, class Sched, bool ALIGN_EPI = false, bool SP2 = false>
; __device__ __forceinline__ void gemm_phase(PG8_LAS unsigned char* lds, const Gemm g, const Sched& S, const Epi& E) {
;     ...
;             PG8_LDB(B0, 0, 0); PG8_LDB(B1, 0, 1); PG8_SCHED; PG8_LDA(At, 0, 0); PG8_STAGE(PG8_SA(1, 1), a1 + hstep, voffA);
;             PG8_WAIT_V(8); PG8_WAIT_L(0); PG8_BAR; PG8_MMA(0, 0, At, B0); PG8_MMA(0, 1, At, B1); PG8_BAR; PG8_SCHED;
;             PG8_LDA(At, 0, 1); PG8_STAGE(PG8_SB(0, 0), b2, voffB); PG8_STAGE(PG8_SB(0, 1), b2 + hstep, voffB); PG8_STAGE(PG8_SA(0, 0), a2, voffA);
;             PG8_WAIT_V(8); PG8_WAIT_L(0); PG8_BAR; PG8_MMA(1, 0, At, B0); PG8_MMA(1, 1, At, B1); PG8_BAR; PG8_SCHED;
.LBB0_1195:
	ds_read_b128 v[130:133], v165
	ds_read_b128 v[134:137], v165 offset:1024
	ds_read_b128 v[138:141], v165 offset:2048
	ds_read_b128 v[142:145], v165 offset:3072
	ds_read_b128 v[158:161], v166
	ds_read_b128 v[168:171], v166 offset:1024
	ds_read_b128 v[172:175], v166 offset:2048
	ds_read_b128 v[176:179], v166 offset:3072
	s_add_u32 s24, s22, 0xffea0080
	s_addc_u32 s25, s23, -1
	s_cmpk_eq_i32 s49, 0x54
	s_cselect_b32 s27, s5, s25
	s_cselect_b32 s26, s4, s24
	s_cselect_b32 s25, s21, s48
	s_cselect_b32 s24, s20, s47
	v_lshl_add_u64 v[184:185], s[22:23], 0, v[150:151]
	s_add_i32 m0, s29, 0xc000
	ds_read_b128 v[180:183], v167
	ds_read_b128 v[192:195], v167 offset:2048
	ds_read_b128 v[200:203], v167 offset:4096
	ds_read_b128 v[208:211], v167 offset:6144
	ds_read_b128 v[188:191], v167 offset:1024
	ds_read_b128 v[196:199], v167 offset:3072
	ds_read_b128 v[204:207], v167 offset:5120
	ds_read_b128 v[212:215], v167 offset:7168
	s_add_u32 s98, s22, 0xffea0000
	s_addc_u32 s99, s23, -1
	s_mov_b32 m0, s37
	s_nop 0
	global_load_lds_dwordx4 v150, s[98:99]
	s_mov_b32 m0, s38
	s_nop 0
	global_load_lds_dwordx4 v152, s[98:99]
	s_add_i32 m0, s29, 0xc000
	s_nop 0
	global_load_lds_dwordx4 v[184:185], off
	v_lshl_add_u64 v[184:185], s[22:23], 0, v[152:153]
	s_add_i32 m0, s29, 0xe000
	s_nop 0
	global_load_lds_dwordx4 v[184:185], off
	s_waitcnt vmcnt(8)
	s_waitcnt lgkmcnt(4)
	s_setprio 1
	s_barrier
	v_mfma_f32_16x16x32_bf16 v[126:129], v[130:133], v[180:183], v[126:129]
	v_mfma_f32_16x16x32_bf16 v[122:125], v[138:141], v[180:183], v[122:125]
	v_mfma_f32_16x16x32_bf16 v[118:121], v[130:133], v[192:195], v[118:121]
	v_mfma_f32_16x16x32_bf16 v[114:117], v[138:141], v[192:195], v[114:117]
	v_mfma_f32_16x16x32_bf16 v[94:97], v[130:133], v[200:203], v[94:97]
	v_mfma_f32_16x16x32_bf16 v[90:93], v[138:141], v[200:203], v[90:93]
	v_mfma_f32_16x16x32_bf16 v[86:89], v[130:133], v[208:211], v[86:89]
	v_mfma_f32_16x16x32_bf16 v[82:85], v[138:141], v[208:211], v[82:85]
	v_mfma_f32_16x16x32_bf16 v[110:113], v[158:161], v[180:183], v[110:113]
	v_mfma_f32_16x16x32_bf16 v[106:109], v[172:175], v[180:183], v[106:109]
	v_mfma_f32_16x16x32_bf16 v[102:105], v[158:161], v[192:195], v[102:105]
	v_mfma_f32_16x16x32_bf16 v[98:101], v[172:175], v[192:195], v[98:101]
	v_mfma_f32_16x16x32_bf16 v[78:81], v[158:161], v[200:203], v[78:81]
	v_mfma_f32_16x16x32_bf16 v[74:77], v[172:175], v[200:203], v[74:77]
	v_mfma_f32_16x16x32_bf16 v[70:73], v[158:161], v[208:211], v[70:73]
	v_mfma_f32_16x16x32_bf16 v[66:69], v[172:175], v[208:211], v[66:69]
	s_waitcnt lgkmcnt(0)
	v_mfma_f32_16x16x32_bf16 v[126:129], v[134:137], v[188:191], v[126:129]
	v_mfma_f32_16x16x32_bf16 v[122:125], v[142:145], v[188:191], v[122:125]
	v_mfma_f32_16x16x32_bf16 v[118:121], v[134:137], v[196:199], v[118:121]
	v_mfma_f32_16x16x32_bf16 v[114:117], v[142:145], v[196:199], v[114:117]
	v_mfma_f32_16x16x32_bf16 v[94:97], v[134:137], v[204:207], v[94:97]
	v_mfma_f32_16x16x32_bf16 v[90:93], v[142:145], v[204:207], v[90:93]
	v_mfma_f32_16x16x32_bf16 v[86:89], v[134:137], v[212:215], v[86:89]
	v_mfma_f32_16x16x32_bf16 v[82:85], v[142:145], v[212:215], v[82:85]
	v_mfma_f32_16x16x32_bf16 v[110:113], v[168:171], v[188:191], v[110:113]
	v_mfma_f32_16x16x32_bf16 v[106:109], v[176:179], v[188:191], v[106:109]
	v_mfma_f32_16x16x32_bf16 v[102:105], v[168:171], v[196:199], v[102:105]
	v_mfma_f32_16x16x32_bf16 v[98:101], v[176:179], v[196:199], v[98:101]
	v_mfma_f32_16x16x32_bf16 v[78:81], v[168:171], v[204:207], v[78:81]
	v_mfma_f32_16x16x32_bf16 v[74:77], v[176:179], v[204:207], v[74:77]
	v_mfma_f32_16x16x32_bf16 v[70:73], v[168:171], v[212:215], v[70:73]
	v_mfma_f32_16x16x32_bf16 v[66:69], v[176:179], v[212:215], v[66:69]
	s_setprio 0
	s_barrier
	s_add_i32 s50, s41, s28
	v_lshl_add_u64 v[184:185], s[24:25], 0, v[146:147]
	s_mov_b32 m0, s50
	ds_read_b128 v[180:183], v167 offset:16384
	ds_read_b128 v[188:191], v167 offset:17408
	ds_read_b128 v[192:195], v167 offset:18432
	ds_read_b128 v[196:199], v167 offset:19456
	ds_read_b128 v[200:203], v167 offset:20480
	ds_read_b128 v[204:207], v167 offset:21504
	ds_read_b128 v[208:211], v167 offset:22528
	ds_read_b128 v[212:215], v167 offset:23552
	global_load_lds_dwordx4 v[184:185], off
	s_add_i32 m0, s50, 0x2000
	s_add_u32 s50, s24, 0x160000
	v_lshl_add_u64 v[216:217], s[24:25], 0, v[148:149]
	s_addc_u32 s51, s25, 0
	s_add_i32 s52, s42, s28
	global_load_lds_dwordx4 v[216:217], off
	v_lshl_add_u64 v[218:219], s[50:51], 0, v[146:147]
	s_mov_b32 m0, s52
	v_lshl_add_u64 v[220:221], s[26:27], 0, v[148:149]
	global_load_lds_dwordx4 v[218:219], off
	v_lshl_add_u64 v[218:219], s[50:51], 0, v[148:149]
	s_add_i32 m0, s52, 0x2000
	s_nop 0
	global_load_lds_dwordx4 v[218:219], off
	v_lshl_add_u64 v[218:219], s[26:27], 0, v[146:147]
	s_mov_b32 m0, s29
	s_nop 0
	s_mov_b32 m0, s30
	s_nop 0
	s_waitcnt vmcnt(6)
	s_waitcnt lgkmcnt(0)
	s_setprio 1
	s_barrier
; #define PG8_STAGE(bufoff, gbase, voff) do { _Pragma("unroll") for (int _i = 0; _i < 2; ++_i) \
;         __builtin_amdgcn_global_load_lds((const unsigned*)((const char*)(gbase) + (voff)[_i]), (PG8_LAS unsigned*)(lds + (bufoff) + ldsw + _i * 8192), 16, 0, 0); } while (0)
; #define PG8_LDA(dst, b, h) do { _Pragma("unroll") for (int m = 0; m < 4; ++m) _Pragma("unroll") for (int k = 0; k < 2; ++k) dst[m][k] = *(const PG8_LAS bf16x8*)(lds + PG8_SA(b, h) + aoff + m * 2048 + k * 1024); } while (0)
; #define PG8_LDB(dst, b, h) do { _Pragma("unroll") for (int n = 0; n < 2; ++n) _Pragma("unroll") for (int k = 0; k < 2; ++k) dst[n][k] = *(const PG8_LAS bf16x8*)(lds + PG8_SB(b, h) + boff + n * 2048 + k * 1024); } while (0)
; #define PG8_MMA(ai, bj, At, Bt) do { __builtin_amdgcn_s_setprio(1); _Pragma("unroll") for (int m = 0; m < 4; ++m) _Pragma("unroll") for (int n = 0; n < 2; ++n) _Pragma("unroll") for (int k = 0; k < 2; ++k) \
;         acc[ai][bj][m][n] = __builtin_amdgcn_mfma_f32_16x16x32_bf16(Bt[n][k], At[m][k], acc[ai][bj][m][n], 0, 0, 0); __builtin_amdgcn_s_setprio(0); } while (0)
; #define PG8_WAIT_V(n) asm volatile("s_waitcnt vmcnt(" #n ")" ::: "memory")
; #define PG8_WAIT_L(n) asm volatile("s_waitcnt lgkmcnt(" #n ")" ::: "memory")
; #define PG8_BAR __builtin_amdgcn_s_barrier()
; #define PG8_SCHED __builtin_amdgcn_sched_barrier(0)
; template <class Epi, class Sched, bool ALIGN_EPI = false, bool SP2 = false>
; __device__ __forceinline__ void gemm_phase(PG8_LAS unsigned char* lds, const Gemm g, const Sched& S, const Epi& E) {
;     ...
;             PG8_WAIT_V(8); PG8_WAIT_L(0); PG8_BAR; PG8_MMA(1, 0, At, B0); PG8_MMA(1, 1, At, B1); PG8_BAR; PG8_SCHED;
;             PG8_LDB(B0, 1, 0); PG8_LDB(B1, 1, 1); PG8_SCHED; PG8_LDA(At, 1, 0); PG8_STAGE(PG8_SA(0, 1), a2 + hstep, voffA);
;             PG8_WAIT_V(8); PG8_WAIT_L(0); PG8_BAR; PG8_MMA(0, 0, At, B0); PG8_MMA(0, 1, At, B1); PG8_BAR; PG8_SCHED;
	v_mfma_f32_16x16x32_bf16 v[62:65], v[130:133], v[180:183], v[62:65]
	v_mfma_f32_16x16x32_bf16 v[58:61], v[138:141], v[180:183], v[58:61]
	v_mfma_f32_16x16x32_bf16 v[54:57], v[130:133], v[192:195], v[54:57]
	v_mfma_f32_16x16x32_bf16 v[50:53], v[138:141], v[192:195], v[50:53]
	v_mfma_f32_16x16x32_bf16 v[30:33], v[130:133], v[200:203], v[30:33]
	v_mfma_f32_16x16x32_bf16 v[26:29], v[138:141], v[200:203], v[26:29]
	v_mfma_f32_16x16x32_bf16 v[22:25], v[130:133], v[208:211], v[22:25]
	v_mfma_f32_16x16x32_bf16 v[18:21], v[138:141], v[208:211], v[18:21]
	v_mfma_f32_16x16x32_bf16 v[62:65], v[134:137], v[188:191], v[62:65]
	v_mfma_f32_16x16x32_bf16 v[58:61], v[142:145], v[188:191], v[58:61]
	v_mfma_f32_16x16x32_bf16 v[54:57], v[134:137], v[196:199], v[54:57]
	v_mfma_f32_16x16x32_bf16 v[50:53], v[142:145], v[196:199], v[50:53]
	v_mfma_f32_16x16x32_bf16 v[30:33], v[134:137], v[204:207], v[30:33]
	v_mfma_f32_16x16x32_bf16 v[26:29], v[142:145], v[204:207], v[26:29]
	v_mfma_f32_16x16x32_bf16 v[22:25], v[134:137], v[212:215], v[22:25]
	v_mfma_f32_16x16x32_bf16 v[18:21], v[142:145], v[212:215], v[18:21]
	v_mfma_f32_16x16x32_bf16 v[46:49], v[158:161], v[180:183], v[46:49]
	v_mfma_f32_16x16x32_bf16 v[42:45], v[172:175], v[180:183], v[42:45]
	v_mfma_f32_16x16x32_bf16 v[38:41], v[158:161], v[192:195], v[38:41]
	v_mfma_f32_16x16x32_bf16 v[34:37], v[172:175], v[192:195], v[34:37]
	v_mfma_f32_16x16x32_bf16 v[14:17], v[158:161], v[200:203], v[14:17]
	v_mfma_f32_16x16x32_bf16 v[10:13], v[172:175], v[200:203], v[10:13]
	v_mfma_f32_16x16x32_bf16 v[6:9], v[158:161], v[208:211], v[6:9]
	v_mfma_f32_16x16x32_bf16 v[2:5], v[172:175], v[208:211], v[2:5]
	v_mfma_f32_16x16x32_bf16 v[46:49], v[168:171], v[188:191], v[46:49]
	v_mfma_f32_16x16x32_bf16 v[42:45], v[176:179], v[188:191], v[42:45]
	v_mfma_f32_16x16x32_bf16 v[38:41], v[168:171], v[196:199], v[38:41]
	v_mfma_f32_16x16x32_bf16 v[34:37], v[176:179], v[196:199], v[34:37]
	v_mfma_f32_16x16x32_bf16 v[14:17], v[168:171], v[204:207], v[14:17]
	v_mfma_f32_16x16x32_bf16 v[10:13], v[176:179], v[204:207], v[10:13]
	v_mfma_f32_16x16x32_bf16 v[6:9], v[168:171], v[212:215], v[6:9]
	v_mfma_f32_16x16x32_bf16 v[2:5], v[176:179], v[212:215], v[2:5]
	s_setprio 0
	s_barrier
	s_add_i32 s50, 0, 0x18000
	s_add_i32 s51, 0, 0x1c000
	v_add_u32_e32 v142, s50, v163
	v_add_u32_e32 v176, s51, v163
	ds_read_b128 v[130:133], v142
	ds_read_b128 v[134:137], v142 offset:1024
	ds_read_b128 v[138:141], v142 offset:2048
	ds_read_b128 v[142:145], v142 offset:3072
	ds_read_b128 v[158:161], v176
	ds_read_b128 v[168:171], v176 offset:1024
	ds_read_b128 v[172:175], v176 offset:2048
	ds_read_b128 v[176:179], v176 offset:3072
	s_add_u32 s26, s26, 0x160000
	s_addc_u32 s27, s27, 0
	s_mov_b32 m0, s31
	v_lshl_add_u64 v[222:223], s[26:27], 0, v[146:147]
	ds_read_b128 v[180:183], v167 offset:32768
	ds_read_b128 v[192:195], v167 offset:34816
	ds_read_b128 v[200:203], v167 offset:36864
	ds_read_b128 v[208:211], v167 offset:38912
	ds_read_b128 v[188:191], v167 offset:33792
	ds_read_b128 v[196:199], v167 offset:35840
	ds_read_b128 v[204:207], v167 offset:37888
	ds_read_b128 v[212:215], v167 offset:39936
	s_add_u32 s98, s26, 0xffea0000
	s_addc_u32 s99, s27, -1
	s_mov_b32 m0, s29
	s_nop 0
	global_load_lds_dwordx4 v146, s[98:99]
	s_mov_b32 m0, s30
	s_nop 0
	global_load_lds_dwordx4 v148, s[98:99]
	s_mov_b32 m0, s31
	s_nop 0
	global_load_lds_dwordx4 v[222:223], off
	v_lshl_add_u64 v[222:223], s[26:27], 0, v[148:149]
	s_mov_b32 m0, s33
	s_nop 0
	global_load_lds_dwordx4 v[222:223], off
	s_waitcnt vmcnt(8)
	s_waitcnt lgkmcnt(4)
	s_setprio 1
	s_barrier
	v_mfma_f32_16x16x32_bf16 v[126:129], v[130:133], v[180:183], v[126:129]
	v_mfma_f32_16x16x32_bf16 v[122:125], v[138:141], v[180:183], v[122:125]
	v_mfma_f32_16x16x32_bf16 v[118:121], v[130:133], v[192:195], v[118:121]
	v_mfma_f32_16x16x32_bf16 v[114:117], v[138:141], v[192:195], v[114:117]
	v_mfma_f32_16x16x32_bf16 v[94:97], v[130:133], v[200:203], v[94:97]
	v_mfma_f32_16x16x32_bf16 v[90:93], v[138:141], v[200:203], v[90:93]
	v_mfma_f32_16x16x32_bf16 v[86:89], v[130:133], v[208:211], v[86:89]
	v_mfma_f32_16x16x32_bf16 v[82:85], v[138:141], v[208:211], v[82:85]
	v_mfma_f32_16x16x32_bf16 v[110:113], v[158:161], v[180:183], v[110:113]
	v_mfma_f32_16x16x32_bf16 v[106:109], v[172:175], v[180:183], v[106:109]
	v_mfma_f32_16x16x32_bf16 v[102:105], v[158:161], v[192:195], v[102:105]
	v_mfma_f32_16x16x32_bf16 v[98:101], v[172:175], v[192:195], v[98:101]
	v_mfma_f32_16x16x32_bf16 v[78:81], v[158:161], v[200:203], v[78:81]
	v_mfma_f32_16x16x32_bf16 v[74:77], v[172:175], v[200:203], v[74:77]
	v_mfma_f32_16x16x32_bf16 v[70:73], v[158:161], v[208:211], v[70:73]
	v_mfma_f32_16x16x32_bf16 v[66:69], v[172:175], v[208:211], v[66:69]
	s_waitcnt lgkmcnt(0)
	v_mfma_f32_16x16x32_bf16 v[126:129], v[134:137], v[188:191], v[126:129]
	v_mfma_f32_16x16x32_bf16 v[122:125], v[142:145], v[188:191], v[122:125]
	v_mfma_f32_16x16x32_bf16 v[118:121], v[134:137], v[196:199], v[118:121]
	v_mfma_f32_16x16x32_bf16 v[114:117], v[142:145], v[196:199], v[114:117]
	v_mfma_f32_16x16x32_bf16 v[94:97], v[134:137], v[204:207], v[94:97]
	v_mfma_f32_16x16x32_bf16 v[90:93], v[142:145], v[204:207], v[90:93]
	v_mfma_f32_16x16x32_bf16 v[86:89], v[134:137], v[212:215], v[86:89]
	v_mfma_f32_16x16x32_bf16 v[82:85], v[142:145], v[212:215], v[82:85]
	v_mfma_f32_16x16x32_bf16 v[110:113], v[168:171], v[188:191], v[110:113]
	v_mfma_f32_16x16x32_bf16 v[106:109], v[176:179], v[188:191], v[106:109]
	v_mfma_f32_16x16x32_bf16 v[102:105], v[168:171], v[196:199], v[102:105]
	v_mfma_f32_16x16x32_bf16 v[98:101], v[176:179], v[196:199], v[98:101]
	v_mfma_f32_16x16x32_bf16 v[78:81], v[168:171], v[204:207], v[78:81]
	v_mfma_f32_16x16x32_bf16 v[74:77], v[176:179], v[204:207], v[74:77]
	v_mfma_f32_16x16x32_bf16 v[70:73], v[168:171], v[212:215], v[70:73]
	v_mfma_f32_16x16x32_bf16 v[66:69], v[176:179], v[212:215], v[66:69]
	s_setprio 0
	s_barrier
; #define PG8_STAGE(bufoff, gbase, voff) do { _Pragma("unroll") for (int _i = 0; _i < 2; ++_i) \
;         __builtin_amdgcn_global_load_lds((const unsigned*)((const char*)(gbase) + (voff)[_i]), (PG8_LAS unsigned*)(lds + (bufoff) + ldsw + _i * 8192), 16, 0, 0); } while (0)
; #define PG8_LDA(dst, b, h) do { _Pragma("unroll") for (int m = 0; m < 4; ++m) _Pragma("unroll") for (int k = 0; k < 2; ++k) dst[m][k] = *(const PG8_LAS bf16x8*)(lds + PG8_SA(b, h) + aoff + m * 2048 + k * 1024); } while (0)
; #define PG8_MMA(ai, bj, At, Bt) do { __builtin_amdgcn_s_setprio(1); _Pragma("unroll") for (int m = 0; m < 4; ++m) _Pragma("unroll") for (int n = 0; n < 2; ++n) _Pragma("unroll") for (int k = 0; k < 2; ++k) \
;         acc[ai][bj][m][n] = __builtin_amdgcn_mfma_f32_16x16x32_bf16(Bt[n][k], At[m][k], acc[ai][bj][m][n], 0, 0, 0); __builtin_amdgcn_s_setprio(0); } while (0)
; #define PG8_WAIT_V(n) asm volatile("s_waitcnt vmcnt(" #n ")" ::: "memory")
; #define PG8_WAIT_L(n) asm volatile("s_waitcnt lgkmcnt(" #n ")" ::: "memory")
; #define PG8_BAR __builtin_amdgcn_s_barrier()
; #define PG8_SCHED __builtin_amdgcn_sched_barrier(0)
; template <class Epi, class Sched, bool ALIGN_EPI = false, bool SP2 = false>
; __device__ __forceinline__ void gemm_phase(PG8_LAS unsigned char* lds, const Gemm g, const Sched& S, const Epi& E) {
;     ...
;         for (int t = 0; t < nt; t += 2) {
;             const bool last = (t == nt - 2);
;     ...
;             PG8_LDA(At, 1, 1); PG8_STAGE(PG8_SB(1, 0), b3, voffB); PG8_STAGE(PG8_SB(1, 1), b3 + hstep, voffB); PG8_STAGE(PG8_SA(1, 0), a3, voffA);
;             PG8_WAIT_V(8); PG8_WAIT_L(0); PG8_BAR; PG8_MMA(1, 0, At, B0); PG8_MMA(1, 1, At, B1); PG8_BAR; PG8_SCHED;
	s_add_i32 s26, s50, s28
	v_lshl_add_u64 v[184:185], v[184:185], 0, s[16:17]
	s_mov_b32 m0, s26
	ds_read_b128 v[180:183], v167 offset:49152
	ds_read_b128 v[188:191], v167 offset:50176
	ds_read_b128 v[192:195], v167 offset:51200
	ds_read_b128 v[196:199], v167 offset:52224
	ds_read_b128 v[200:203], v167 offset:53248
	ds_read_b128 v[204:207], v167 offset:54272
	ds_read_b128 v[208:211], v167 offset:55296
	ds_read_b128 v[212:215], v167 offset:56320
	global_load_lds_dwordx4 v[184:185], off
	s_add_i32 m0, s26, 0x2000
	s_add_u32 s24, s24, 0x160080
	v_lshl_add_u64 v[184:185], v[216:217], 0, s[16:17]
	s_addc_u32 s25, s25, 0
	s_add_i32 s26, s51, s28
	global_load_lds_dwordx4 v[184:185], off
	v_lshl_add_u64 v[184:185], s[24:25], 0, v[146:147]
	s_mov_b32 m0, s26
	s_nop 0
	global_load_lds_dwordx4 v[184:185], off
	v_lshl_add_u64 v[184:185], s[24:25], 0, v[148:149]
	s_add_i32 m0, s26, 0x2000
	s_nop 0
	global_load_lds_dwordx4 v[184:185], off
	v_lshl_add_u64 v[184:185], v[218:219], 0, s[16:17]
	s_mov_b32 m0, s37
	s_nop 0
	v_lshl_add_u64 v[184:185], v[220:221], 0, s[16:17]
	s_mov_b32 m0, s38
	s_nop 0
	s_waitcnt vmcnt(6)
	s_waitcnt lgkmcnt(0)
	s_setprio 1
	s_barrier
	v_mfma_f32_16x16x32_bf16 v[62:65], v[130:133], v[180:183], v[62:65]
	v_mfma_f32_16x16x32_bf16 v[58:61], v[138:141], v[180:183], v[58:61]
	v_mfma_f32_16x16x32_bf16 v[54:57], v[130:133], v[192:195], v[54:57]
	v_mfma_f32_16x16x32_bf16 v[50:53], v[138:141], v[192:195], v[50:53]
	v_mfma_f32_16x16x32_bf16 v[30:33], v[130:133], v[200:203], v[30:33]
	v_mfma_f32_16x16x32_bf16 v[26:29], v[138:141], v[200:203], v[26:29]
	v_mfma_f32_16x16x32_bf16 v[22:25], v[130:133], v[208:211], v[22:25]
	v_mfma_f32_16x16x32_bf16 v[18:21], v[138:141], v[208:211], v[18:21]
	v_mfma_f32_16x16x32_bf16 v[62:65], v[134:137], v[188:191], v[62:65]
	v_mfma_f32_16x16x32_bf16 v[58:61], v[142:145], v[188:191], v[58:61]
	v_mfma_f32_16x16x32_bf16 v[54:57], v[134:137], v[196:199], v[54:57]
	v_mfma_f32_16x16x32_bf16 v[50:53], v[142:145], v[196:199], v[50:53]
	v_mfma_f32_16x16x32_bf16 v[30:33], v[134:137], v[204:207], v[30:33]
	v_mfma_f32_16x16x32_bf16 v[26:29], v[142:145], v[204:207], v[26:29]
	v_mfma_f32_16x16x32_bf16 v[22:25], v[134:137], v[212:215], v[22:25]
	v_mfma_f32_16x16x32_bf16 v[18:21], v[142:145], v[212:215], v[18:21]
	v_mfma_f32_16x16x32_bf16 v[46:49], v[158:161], v[180:183], v[46:49]
	v_mfma_f32_16x16x32_bf16 v[42:45], v[172:175], v[180:183], v[42:45]
	v_mfma_f32_16x16x32_bf16 v[38:41], v[158:161], v[192:195], v[38:41]
	v_mfma_f32_16x16x32_bf16 v[34:37], v[172:175], v[192:195], v[34:37]
	v_mfma_f32_16x16x32_bf16 v[14:17], v[158:161], v[200:203], v[14:17]
	v_mfma_f32_16x16x32_bf16 v[10:13], v[172:175], v[200:203], v[10:13]
	v_mfma_f32_16x16x32_bf16 v[6:9], v[158:161], v[208:211], v[6:9]
	v_mfma_f32_16x16x32_bf16 v[2:5], v[172:175], v[208:211], v[2:5]
	v_mfma_f32_16x16x32_bf16 v[46:49], v[168:171], v[188:191], v[46:49]
	v_mfma_f32_16x16x32_bf16 v[42:45], v[176:179], v[188:191], v[42:45]
	v_mfma_f32_16x16x32_bf16 v[38:41], v[168:171], v[196:199], v[38:41]
	v_mfma_f32_16x16x32_bf16 v[34:37], v[176:179], v[196:199], v[34:37]
	v_mfma_f32_16x16x32_bf16 v[14:17], v[168:171], v[204:207], v[14:17]
	v_mfma_f32_16x16x32_bf16 v[10:13], v[176:179], v[204:207], v[10:13]
	v_mfma_f32_16x16x32_bf16 v[6:9], v[168:171], v[212:215], v[6:9]
	v_mfma_f32_16x16x32_bf16 v[2:5], v[176:179], v[212:215], v[2:5]
	s_setprio 0
	s_barrier
	s_add_i32 s49, s49, 2
	s_add_u32 s22, s22, 0x100
	s_addc_u32 s23, s23, 0
	s_add_u32 s47, s47, 0x100
	s_addc_u32 s48, s48, 0
	s_cmpk_gt_u32 s49, 0x55
	s_cbranch_scc0 .LBB0_1195
	s_and_b64 vcc, exec, s[18:19]
	s_cbranch_vccz .LBB0_1198
	s_barrier
